# baseline (speedup 1.0000x reference)
; __device__ void convert_one(const float* W, bf16* WT, int K, int N, float* tile, int wv, const float* gain = nullptr) {
;   const int tn = N / 64, ntile = (K / 64) * tn;
;   const int tid = ltid(wv);
;   const int kq = tid >> 4, n4 = (tid & 15) * 4;
;   const int nr = tid >> 3, k8 = (tid & 7) * 8;
;   f32x4 v0, v1; float g0 = 1.f, g1 = 1.f;
;   int t = blockIdx.x;
;   if (t < ntile) {
;     const int k0 = (t / tn) * 64, n0 = (t % tn) * 64;
;     v0 = *(const f32x4*)(W + (size_t)(k0 + kq) * N + n0 + n4); v1 = *(const f32x4*)(W + (size_t)(k0 + kq + 32) * N + n0 + n4);
;     if (gain) { g0 = gain[k0 + kq]; g1 = gain[k0 + kq + 32]; }
;   }
; __device__ void convert_weights(const Params& p, int layer, float* tile, int wv) {
;     ...
;   convert_one(p.w_in + (size_t)layer * DM * NIN, WB + WO_IN, DM, NIN, tile, wv, p.norm1_g + (size_t)layer * DM);
.LBB0_61:
	v_readlane_b32 s64, v253, 11
	v_writelane_b32 v252, s18, 24
	s_mul_i32 s0, s20, 0x5c00000
	v_readlane_b32 s68, v253, 15
	v_writelane_b32 v252, s19, 25
	s_mov_b32 s4, s20
	s_mov_b32 s5, s63
	v_readlane_b32 s69, v253, 16
	s_add_u32 s6, s68, s0
	v_readlane_b32 s66, v253, 13
	s_addc_u32 s7, s69, 0
	v_writelane_b32 v252, s4, 26
	s_lshl_b64 s[0:1], s[4:5], 13
	v_readlane_b32 s67, v253, 14
	s_add_u32 s8, s66, s0
	s_addc_u32 s9, s67, s1
	v_readlane_b32 s0, v253, 31
	s_waitcnt vmcnt(3)
	v_mbcnt_lo_u32_b32 v15, -1, 0
	v_mbcnt_hi_u32_b32 v15, -1, v15
	v_readlane_b32 s1, v253, 32
	v_lshlrev_b32_e32 v2, 2, v15
	v_and_b32_e32 v16, 60, v2
	v_cndmask_b32_e64 v2, 0, 1, s[0:1]
	s_andn2_b64 vcc, exec, s[0:1]
	v_readlane_b32 s0, v253, 34
	v_readlane_b32 s1, v253, 35
	v_writelane_b32 v252, s5, 27
	v_or_b32_e32 v17, s91, v15
	v_cmp_ne_u32_e64 s[4:5], 1, v2
	v_cndmask_b32_e64 v2, 0, 1, s[0:1]
	v_ashrrev_i32_e32 v1, 4, v17
	v_mov_b32_e32 v12, 1.0
	v_lshlrev_b32_e32 v10, 2, v16
	v_cmp_ne_u32_e64 s[0:1], 1, v2
	v_mov_b32_e32 v14, 1.0
	v_readlane_b32 s65, v253, 12
	v_readlane_b32 s70, v253, 17
	v_readlane_b32 s71, v253, 18
	v_readlane_b32 s72, v253, 19
	v_readlane_b32 s73, v253, 20
	v_readlane_b32 s74, v253, 21
	v_readlane_b32 s75, v253, 22
	v_readlane_b32 s76, v253, 23
	v_readlane_b32 s77, v253, 24
	v_readlane_b32 s78, v253, 25
	v_readlane_b32 s79, v253, 26
	s_cbranch_vccnz .LBB0_65
	v_readlane_b32 s10, v253, 33
	v_mov_b64_e32 v[2:3], s[6:7]
	s_mov_b32 s14, 0xb800
	v_add_u32_e32 v12, s10, v1
	v_readlane_b32 s12, v252, 9
	s_waitcnt vmcnt(0)
	v_add_u32_e32 v6, 32, v12
	v_mad_i64_i32 v[4:5], s[10:11], v12, s14, v[2:3]
	v_readlane_b32 s13, v252, 10
	v_mad_i64_i32 v[2:3], s[10:11], v6, s14, v[2:3]
	s_nop 0
	v_lshl_add_u64 v[4:5], v[4:5], 0, s[12:13]
	v_mov_b32_e32 v11, v0
	v_lshl_add_u64 v[2:3], v[2:3], 0, s[12:13]
	v_lshl_add_u64 v[4:5], v[4:5], 0, v[10:11]
	v_lshl_add_u64 v[6:7], v[2:3], 0, v[10:11]
	global_load_dwordx4 v[2:5], v[4:5], off
	s_nop 0
	global_load_dwordx4 v[6:9], v[6:7], off
	s_and_b64 vcc, exec, s[0:1]
	s_cbranch_vccnz .LBB0_64
	v_ashrrev_i32_e32 v13, 31, v12
	v_lshl_add_u64 v[12:13], v[12:13], 2, s[8:9]
	global_load_dword v14, v[12:13], off
	s_nop 0
	global_load_dword v12, v[12:13], off offset:128
	s_branch .LBB0_65

;     #define ISSUE_NEXT() do { if (more) { gemm_issue_part1(A, lda, Bt, K, pm * BM, pn * BM, shm, tid); fresh = false; \
;                                           asm volatile("s_waitcnt vmcnt(8)" ::: "memory"); }     \
;                               else asm volatile("s_waitcnt vmcnt(0)" ::: "memory"); } while (0)
; __device__ __forceinline__ float rstd_of(unsigned long long v) { return rsqrtf((float)v * (SSQ_INV / DM) + EPS); }
; template <int EPI>
; __device__ void gemm_phase(const bf16* A, int lda, const bf16* Bt, int K, int N, const Params& p, bool last, bf16* dstb, bf16* shm, unsigned long long* SSQ, int wv, const float* gbias = nullptr) {
;     ...
;       unsigned long long sq[2][4]; float rsv[2][4]; f32x4 gbv[2][2];
;       _Pragma("unroll") for (int ai = 0; ai < 2; ++ai) _Pragma("unroll") for (int m = 0; m < 4; ++m) sq[ai][m] = SSQ[brow + ai * HALF + wr * 64 + m * 16 + fr];
;       _Pragma("unroll") for (int bj = 0; bj < 2; ++bj) _Pragma("unroll") for (int n = 0; n < 2; ++n)
;         gbv[bj][n] = *(const f32x4*)(gbias + (gate_tile ? c0 : 0) + wc * 32 + fq * 4 + bj * HALF + n * 16);
;       _Pragma("unroll") for (int ai = 0; ai < 2; ++ai) _Pragma("unroll") for (int m = 0; m < 4; ++m) rsv[ai][m] = rstd_of(sq[ai][m]);
;       asm volatile("s_waitcnt vmcnt(0)" ::: "memory");
;       asm volatile("" : "+v"(gbv[0][0]), "+v"(gbv[0][1]), "+v"(gbv[1][0]), "+v"(gbv[1][1]));
;       asm volatile("" : "+v"(rsv[0][0]), "+v"(rsv[0][1]), "+v"(rsv[0][2]), "+v"(rsv[0][3]), "+v"(rsv[1][0]), "+v"(rsv[1][1]), "+v"(rsv[1][2]), "+v"(rsv[1][3]));
;       ISSUE_NEXT();
.LBB0_181:
	v_and_b32_e32 v153, 15, v1
	v_ashrrev_i32_e32 v151, 8, v1
	v_or_b32_e32 v94, s10, v153
	v_lshl_add_u32 v94, v151, 6, v94
	v_ashrrev_i32_e32 v95, 31, v94
	v_lshl_add_u64 v[96:97], v[94:95], 3, s[58:59]
	global_load_dwordx2 v[120:121], v[96:97], off
	global_load_dwordx2 v[154:155], v[96:97], off offset:128
	global_load_dwordx2 v[112:113], v[96:97], off offset:256
	global_load_dwordx2 v[110:111], v[96:97], off offset:384
	v_add_u32_e32 v96, 0x80, v94
	v_ashrrev_i32_e32 v97, 31, v96
	v_lshl_add_u64 v[96:97], v[96:97], 3, s[58:59]
	global_load_dwordx2 v[104:105], v[96:97], off
	v_add_u32_e32 v96, 0x90, v94
	v_ashrrev_i32_e32 v97, 31, v96
	v_lshl_add_u64 v[96:97], v[96:97], 3, s[58:59]
	global_load_dwordx2 v[102:103], v[96:97], off
	v_add_u32_e32 v96, 0xa0, v94
	v_ashrrev_i32_e32 v97, 31, v96
	v_lshl_add_u64 v[96:97], v[96:97], 3, s[58:59]
	global_load_dwordx2 v[96:97], v[96:97], off
	v_add_u32_e32 v94, 0xb0, v94
	v_ashrrev_i32_e32 v95, 31, v94
	v_lshl_add_u64 v[94:95], v[94:95], 3, s[58:59]
	s_cmp_lt_i32 s7, 30
	global_load_dwordx2 v[94:95], v[94:95], off
	s_cselect_b64 s[16:17], -1, 0
	s_cmp_gt_i32 s7, 29
	s_cselect_b32 s18, s8, 0
	s_ashr_i32 s19, s18, 31
	s_lshl_b64 s[18:19], s[18:19], 2
	v_bfe_u32 v147, v1, 6, 2
	s_add_u32 s18, s23, s18
	v_bfe_u32 v149, v1, 4, 2
	s_addc_u32 s19, s24, s19
	v_lshlrev_b32_e32 v118, 7, v147
	v_mov_b32_e32 v119, v0
	v_lshl_add_u64 v[118:119], s[18:19], 0, v[118:119]
	v_lshlrev_b32_e32 v156, 4, v149
	v_mov_b32_e32 v157, v0
	v_lshl_add_u64 v[118:119], v[118:119], 0, v[156:157]
	s_mov_b64 s[18:19], -1
	s_waitcnt vmcnt(7)
	v_ffbh_u32_e32 v146, v121
	v_min_u32_e32 v146, 32, v146
	v_lshlrev_b64 v[120:121], v146, v[120:121]
	v_min_u32_e32 v120, 1, v120
	v_or_b32_e32 v120, v121, v120
	v_cvt_f32_u32_e32 v120, v120
	v_sub_u32_e32 v121, 32, v146
	v_ldexp_f32 v120, v120, v121
	v_fmamk_f32 v120, v120, 0x30000000, v194
	v_cmp_gt_f32_e32 vcc, s80, v120
	v_mul_f32_e32 v121, 0x4b800000, v120
	s_nop 0
	v_cndmask_b32_e32 v120, v120, v121, vcc
	v_rsq_f32_e32 v120, v120
	s_nop 0
	v_mul_f32_e32 v121, 0x45800000, v120
	v_cndmask_b32_e32 v160, v120, v121, vcc
	s_waitcnt vmcnt(6)
	v_ffbh_u32_e32 v120, v155
	v_min_u32_e32 v146, 32, v120
	v_lshlrev_b64 v[120:121], v146, v[154:155]
	v_min_u32_e32 v120, 1, v120
	v_or_b32_e32 v120, v121, v120
	v_cvt_f32_u32_e32 v120, v120
	v_sub_u32_e32 v121, 32, v146
	v_ldexp_f32 v120, v120, v121
	v_fmamk_f32 v120, v120, 0x30000000, v194
	v_cmp_gt_f32_e32 vcc, s80, v120
	v_mul_f32_e32 v121, 0x4b800000, v120
	s_nop 0
	v_cndmask_b32_e32 v120, v120, v121, vcc
	v_rsq_f32_e32 v120, v120
	s_nop 0
	v_mul_f32_e32 v121, 0x45800000, v120
	v_cndmask_b32_e32 v158, v120, v121, vcc
	s_waitcnt vmcnt(5)
	v_ffbh_u32_e32 v120, v113
	v_min_u32_e32 v120, 32, v120
	v_lshlrev_b64 v[112:113], v120, v[112:113]
	v_min_u32_e32 v112, 1, v112
	v_or_b32_e32 v112, v113, v112
	v_cvt_f32_u32_e32 v112, v112
	v_sub_u32_e32 v113, 32, v120
	v_ldexp_f32 v112, v112, v113
	v_fmamk_f32 v112, v112, 0x30000000, v194
	v_cmp_gt_f32_e32 vcc, s80, v112
	v_mul_f32_e32 v113, 0x4b800000, v112
	s_nop 0
	v_cndmask_b32_e32 v112, v112, v113, vcc
	v_rsq_f32_e32 v112, v112
	s_nop 0
	v_mul_f32_e32 v113, 0x45800000, v112
	v_cndmask_b32_e32 v156, v112, v113, vcc
	s_waitcnt vmcnt(4)
	v_ffbh_u32_e32 v112, v111
	v_min_u32_e32 v112, 32, v112
	v_lshlrev_b64 v[110:111], v112, v[110:111]
	v_min_u32_e32 v110, 1, v110
	v_or_b32_e32 v110, v111, v110
	v_cvt_f32_u32_e32 v110, v110
	v_sub_u32_e32 v111, 32, v112
	v_ldexp_f32 v110, v110, v111
	v_fmamk_f32 v110, v110, 0x30000000, v194
	v_cmp_gt_f32_e32 vcc, s80, v110
	v_mul_f32_e32 v111, 0x4b800000, v110
	s_nop 0
	v_cndmask_b32_e32 v110, v110, v111, vcc
	v_rsq_f32_e32 v110, v110
	s_nop 0
	v_mul_f32_e32 v111, 0x45800000, v110
	v_cndmask_b32_e32 v154, v110, v111, vcc
	s_waitcnt vmcnt(3)
	v_ffbh_u32_e32 v110, v105
	v_min_u32_e32 v110, 32, v110
	v_lshlrev_b64 v[104:105], v110, v[104:105]
	v_min_u32_e32 v104, 1, v104
	v_or_b32_e32 v104, v105, v104
	v_cvt_f32_u32_e32 v104, v104
	v_sub_u32_e32 v105, 32, v110
	v_ldexp_f32 v104, v104, v105
	v_fmamk_f32 v104, v104, 0x30000000, v194
	v_cmp_gt_f32_e32 vcc, s80, v104
	v_mul_f32_e32 v105, 0x4b800000, v104
	s_nop 0
	v_cndmask_b32_e32 v104, v104, v105, vcc
	v_rsq_f32_e32 v104, v104
	s_nop 0
	v_mul_f32_e32 v105, 0x45800000, v104
	v_cndmask_b32_e32 v152, v104, v105, vcc
	s_waitcnt vmcnt(2)
	v_ffbh_u32_e32 v104, v103
	v_min_u32_e32 v104, 32, v104
	v_lshlrev_b64 v[102:103], v104, v[102:103]
	v_min_u32_e32 v102, 1, v102
	v_or_b32_e32 v102, v103, v102
	v_cvt_f32_u32_e32 v102, v102
	v_sub_u32_e32 v103, 32, v104
	v_ldexp_f32 v102, v102, v103
	v_fmamk_f32 v102, v102, 0x30000000, v194
	v_cmp_gt_f32_e32 vcc, s80, v102
	v_mul_f32_e32 v103, 0x4b800000, v102
	s_nop 0
	v_cndmask_b32_e32 v102, v102, v103, vcc
	v_rsq_f32_e32 v102, v102
	s_nop 0
	v_mul_f32_e32 v103, 0x45800000, v102
	v_cndmask_b32_e32 v150, v102, v103, vcc
	s_waitcnt vmcnt(1)
	v_ffbh_u32_e32 v102, v97
	v_min_u32_e32 v102, 32, v102
	v_lshlrev_b64 v[96:97], v102, v[96:97]
	v_min_u32_e32 v96, 1, v96
	v_or_b32_e32 v96, v97, v96
	v_cvt_f32_u32_e32 v96, v96
	v_sub_u32_e32 v97, 32, v102
	v_ldexp_f32 v96, v96, v97
	v_fmamk_f32 v96, v96, 0x30000000, v194
	v_cmp_gt_f32_e32 vcc, s80, v96
	v_mul_f32_e32 v97, 0x4b800000, v96
	s_nop 0
	v_cndmask_b32_e32 v96, v96, v97, vcc
	v_rsq_f32_e32 v96, v96
	s_nop 0
	v_mul_f32_e32 v97, 0x45800000, v96
	v_cndmask_b32_e32 v148, v96, v97, vcc
	s_waitcnt vmcnt(0)
	v_ffbh_u32_e32 v96, v95
	v_min_u32_e32 v96, 32, v96
	v_lshlrev_b64 v[94:95], v96, v[94:95]
	v_min_u32_e32 v94, 1, v94
	v_or_b32_e32 v94, v95, v94
	v_cvt_f32_u32_e32 v94, v94
	v_sub_u32_e32 v95, 32, v96
	v_ldexp_f32 v94, v94, v95
	v_fmamk_f32 v94, v94, 0x30000000, v194
	v_cmp_gt_f32_e32 vcc, s80, v94
	v_mul_f32_e32 v95, 0x4b800000, v94
	s_nop 0
	v_cndmask_b32_e32 v94, v94, v95, vcc
	v_rsq_f32_e32 v94, v94
	s_nop 0
	v_mul_f32_e32 v95, 0x45800000, v94
	v_cndmask_b32_e32 v146, v94, v95, vcc
	global_load_dwordx4 v[94:97], v[118:119], off offset:576
	global_load_dwordx4 v[102:105], v[118:119], off offset:512
	global_load_dwordx4 v[110:113], v[118:119], off offset:64
	s_nop 0
	global_load_dwordx4 v[118:121], v[118:119], off
	s_waitcnt vmcnt(0)
	s_and_b64 vcc, exec, s[0:1]
	s_cbranch_vccnz .LBB0_185
	s_andn2_b64 vcc, exec, s[18:19]
	v_lshlrev_b32_e32 v155, 4, v1
	s_cbranch_vccz .LBB0_186

; __device__ __forceinline__ void st16_asm(void* ptr, u32x4 v) { asm volatile("global_store_dwordx4 %0, %1, off\n\ts_nop 7" :: "v"(ptr), "v"(v) : "memory"); }
; __device__ __forceinline__ void stg_flush(bf16* shm, int tid, bf16* dst, size_t pitch, bool first, bool tail_barrier = true) {
;     ...
;   _Pragma("unroll") for (int i = 0; i < 8; ++i) {
;     const int idx = tid + 512 * i, bjr = idx >> 11, row = (idx >> 4) & 127, c16 = idx & 15;
;     const u32x4 d = *(const u32x4*)stg_ptr(shm, bjr, row, 2 * c16);
;     st16_asm(dst + (size_t)row * pitch + bjr * HALF + c16 * 8, d); }
; template <int EPI>
; __device__ void gemm_phase(const bf16* A, int lda, const bf16* Bt, int K, int N, const Params& p, bool last, bf16* dstb, bf16* shm, unsigned long long* SSQ, int wv, const float* gbias = nullptr) {
;     ...
;         _Pragma("unroll") for (int ai = 0; ai < 2; ++ai) {
;           _Pragma("unroll") for (int m = 0; m < 4; ++m) {
;             const int rl = wr * 64 + m * 16 + fr; const float rs = rsv[ai][m];
;             _Pragma("unroll") for (int bj = 0; bj < 2; ++bj) _Pragma("unroll") for (int n = 0; n < 2; ++n) {
;               f32x4 v = acc[ai][bj][m][n] * rs; u32x2 o = {pk2(v[0], v[1]), pk2(v[2], v[3])};
;               *(u32x2*)stg_ptr(shm, bj, rl, wc * 8 + n * 4 + fq) = o; }
.LBB0_187:
	v_lshrrev_b32_e32 v157, 4, v1
	v_cmp_gt_u32_e32 vcc, s85, v1
	v_xor_b32_e32 v157, v157, v1
	v_bfe_u32 v159, v1, 4, 7
	v_cndmask_b32_e32 v161, v244, v245, vcc
	v_lshlrev_b32_e32 v157, 4, v157
	v_add_u32_e32 v161, 0, v161
	v_lshlrev_b32_e32 v162, 8, v159
	v_and_b32_e32 v157, 0xf0, v157
	v_add3_u32 v157, v161, v162, v157
	v_mul_u32_u24_e32 v186, s12, v159
	v_ashrrev_i32_e32 v159, 4, v1
	v_add_u32_e32 v161, 0x200, v1
	v_and_b32_e32 v162, 0xffffff80, v159
	v_lshrrev_b32_e32 v159, 4, v161
	v_cmp_gt_u32_e32 vcc, s85, v161
	v_xor_b32_e32 v159, v159, v1
	v_bfe_u32 v164, v161, 4, 7
	v_cndmask_b32_e32 v165, v244, v245, vcc
	v_lshlrev_b32_e32 v159, 4, v159
	v_add_u32_e32 v165, 0, v165
	v_lshlrev_b32_e32 v166, 8, v164
	v_and_b32_e32 v159, 0xf0, v159
	v_add3_u32 v159, v165, v166, v159
	v_ashrrev_i32_e32 v161, 4, v161
	v_add_u32_e32 v166, 0x400, v1
	v_mul_u32_u24_e32 v190, s12, v164
	v_and_b32_e32 v164, 0xffffff80, v161
	v_lshrrev_b32_e32 v161, 4, v166
	v_cmp_gt_u32_e32 vcc, s85, v166
	v_xor_b32_e32 v161, v161, v1
	v_bfe_u32 v167, v166, 4, 7
	v_cndmask_b32_e32 v168, v244, v245, vcc
	v_lshlrev_b32_e32 v161, 4, v161
	v_add_u32_e32 v168, 0, v168
	v_lshlrev_b32_e32 v169, 8, v167
	v_and_b32_e32 v161, 0xf0, v161
	v_add3_u32 v161, v168, v169, v161
	v_add_u32_e32 v168, 0x600, v1
	v_lshrrev_b32_e32 v169, 4, v168
	v_cmp_gt_u32_e32 vcc, s85, v168
	v_xor_b32_e32 v169, v169, v1
	v_bfe_u32 v170, v168, 4, 7
	v_cndmask_b32_e32 v171, v244, v245, vcc
	v_lshlrev_b32_e32 v169, 4, v169
	v_add_u32_e32 v171, 0, v171
	v_lshlrev_b32_e32 v172, 8, v170
	v_and_b32_e32 v169, 0xf0, v169
	v_mul_u32_u24_e32 v198, s12, v170
	v_add_u32_e32 v170, 0x800, v1
	v_add3_u32 v178, v171, v172, v169
	v_lshrrev_b32_e32 v171, 4, v170
	v_cmp_lt_u32_e32 vcc, s35, v1
	v_xor_b32_e32 v171, v171, v1
	v_bfe_u32 v172, v170, 4, 7
	v_cndmask_b32_e32 v173, v244, v245, vcc
	v_lshlrev_b32_e32 v171, 4, v171
	v_add_u32_e32 v173, 0, v173
	v_lshlrev_b32_e32 v174, 8, v172
	v_and_b32_e32 v171, 0xf0, v171
	v_mul_u32_u24_e32 v199, s12, v172
	v_add_u32_e32 v172, 0xa00, v1
	v_add3_u32 v206, v173, v174, v171
	v_lshrrev_b32_e32 v173, 4, v172
	v_cmp_gt_u32_e32 vcc, s85, v172
	v_xor_b32_e32 v173, v173, v1
	v_bfe_u32 v174, v172, 4, 7
	v_cndmask_b32_e32 v175, v244, v245, vcc
	v_lshlrev_b32_e32 v173, 4, v173
	v_add_u32_e32 v175, 0, v175
	v_lshlrev_b32_e32 v176, 8, v174
	v_and_b32_e32 v173, 0xf0, v173
	v_mul_u32_u24_e32 v200, s12, v174
	v_add_u32_e32 v174, 0xc00, v1
	v_add3_u32 v207, v175, v176, v173
	v_lshrrev_b32_e32 v175, 4, v174
	v_cmp_gt_u32_e32 vcc, s85, v174
	v_xor_b32_e32 v175, v175, v1
	v_bfe_u32 v176, v174, 4, 7
	v_cndmask_b32_e32 v177, v244, v245, vcc
	v_lshlrev_b32_e32 v175, 4, v175
	v_add_u32_e32 v177, 0, v177
	v_lshlrev_b32_e32 v180, 8, v176
	v_and_b32_e32 v175, 0xf0, v175
	v_mul_u32_u24_e32 v202, s12, v176
	v_add_u32_e32 v176, 0xe00, v1
	v_add3_u32 v208, v177, v180, v175
	v_lshrrev_b32_e32 v177, 4, v176
	v_cmp_gt_u32_e32 vcc, s85, v176
	v_xor_b32_e32 v177, v177, v1
	v_bfe_u32 v180, v176, 4, 7
	v_cndmask_b32_e32 v181, v244, v245, vcc
	v_lshlrev_b32_e32 v177, 4, v177
	v_lshlrev_b32_e32 v179, 4, v153
	v_add_u32_e32 v181, 0, v181
	v_lshlrev_b32_e32 v182, 8, v180
	v_and_b32_e32 v177, 0xf0, v177
	v_lshlrev_b32_e32 v151, 14, v151
	v_lshlrev_b32_e32 v153, 8, v153
	v_lshlrev_b32_e32 v147, 6, v147
	v_lshlrev_b32_e32 v149, 3, v149
	v_add3_u32 v209, v181, v182, v177
	v_mul_u32_u24_e32 v204, s12, v180
	v_add3_u32 v151, 0, v151, v153
	v_pk_mul_f32 v[180:181], v[144:145], v[160:161] op_sel_hi:[1,0]
	v_pk_mul_f32 v[182:183], v[142:143], v[160:161] op_sel_hi:[1,0]
	v_or_b32_e32 v153, v147, v149
	v_bitop3_b32 v147, v147, v179, v149 bitop3:0x36
	v_cvt_pk_bf16_f32 v182, v182, v183
	v_cvt_pk_bf16_f32 v183, v180, v181
	v_add_u32_e32 v149, v151, v147
	ds_write_b64 v149, v[182:183] offset:32768
	v_pk_mul_f32 v[180:181], v[140:141], v[160:161] op_sel_hi:[1,0]
	v_pk_mul_f32 v[182:183], v[138:139], v[160:161] op_sel_hi:[1,0]
	v_add_u32_e32 v187, 0x18000, v151
	v_cvt_pk_bf16_f32 v182, v182, v183
	v_cvt_pk_bf16_f32 v183, v180, v181
	v_pk_mul_f32 v[180:181], v[136:137], v[160:161] op_sel_hi:[1,0]
	v_pk_mul_f32 v[184:185], v[134:135], v[160:161] op_sel_hi:[1,0]
	v_add_u32_e32 v210, v187, v147
	v_cvt_pk_bf16_f32 v184, v184, v185
	v_cvt_pk_bf16_f32 v185, v180, v181
	v_bitop3_b32 v153, v153, v179, 32 bitop3:0x36
	ds_write_b64 v210, v[184:185]
	v_pk_mul_f32 v[180:181], v[132:133], v[160:161] op_sel_hi:[1,0]
	v_pk_mul_f32 v[184:185], v[130:131], v[160:161] op_sel_hi:[1,0]
	v_add_u32_e32 v211, v187, v153
	v_cvt_pk_bf16_f32 v184, v184, v185
	v_cvt_pk_bf16_f32 v185, v180, v181
	ds_write_b64 v211, v[184:185]
	v_pk_mul_f32 v[180:181], v[128:129], v[158:159] op_sel_hi:[1,0]
	v_pk_mul_f32 v[184:185], v[126:127], v[158:159] op_sel_hi:[1,0]
	v_add_u32_e32 v179, v151, v153
	v_cvt_pk_bf16_f32 v184, v184, v185
	v_cvt_pk_bf16_f32 v185, v180, v181
	ds_write_b64 v149, v[184:185] offset:36864
	v_pk_mul_f32 v[180:181], v[124:125], v[158:159] op_sel_hi:[1,0]
	v_pk_mul_f32 v[184:185], v[122:123], v[158:159] op_sel_hi:[1,0]
	v_add_u32_e32 v187, 0x1a000, v151
	v_cvt_pk_bf16_f32 v184, v184, v185
	v_cvt_pk_bf16_f32 v185, v180, v181
	ds_write2st64_b64 v179, v[182:183], v[184:185] offset0:64 offset1:72
	v_add_u32_e32 v184, 0x19000, v151
	v_pk_mul_f32 v[180:181], v[116:117], v[158:159] op_sel_hi:[1,0]
	v_pk_mul_f32 v[182:183], v[114:115], v[158:159] op_sel_hi:[1,0]
	v_add_u32_e32 v212, v184, v147
	v_cvt_pk_bf16_f32 v182, v182, v183
	v_cvt_pk_bf16_f32 v183, v180, v181
	ds_write_b64 v212, v[182:183]
	v_pk_mul_f32 v[180:181], v[108:109], v[158:159] op_sel_hi:[1,0]
	v_pk_mul_f32 v[182:183], v[106:107], v[158:159] op_sel_hi:[1,0]
	v_add_u32_e32 v213, v184, v153
; #define LDS_BARRIER() do { asm volatile("s_waitcnt lgkmcnt(0)" ::: "memory"); __builtin_amdgcn_s_barrier(); asm volatile("" ::: "memory"); } while (0)
; __device__ __forceinline__ void st16_asm(void* ptr, u32x4 v) { asm volatile("global_store_dwordx4 %0, %1, off\n\ts_nop 7" :: "v"(ptr), "v"(v) : "memory"); }
; __device__ __forceinline__ void stg_flush(bf16* shm, int tid, bf16* dst, size_t pitch, bool first, bool tail_barrier = true) {
;   LDS_BARRIER();
;   if (first) asm volatile("s_waitcnt vmcnt(0)" ::: "memory");
;   _Pragma("unroll") for (int i = 0; i < 8; ++i) {
;     const int idx = tid + 512 * i, bjr = idx >> 11, row = (idx >> 4) & 127, c16 = idx & 15;
;     const u32x4 d = *(const u32x4*)stg_ptr(shm, bjr, row, 2 * c16);
;     st16_asm(dst + (size_t)row * pitch + bjr * HALF + c16 * 8, d); }
;   if (tail_barrier) LDS_BARRIER();
; template <int EPI>
; __device__ void gemm_phase(const bf16* A, int lda, const bf16* Bt, int K, int N, const Params& p, bool last, bf16* dstb, bf16* shm, unsigned long long* SSQ, int wv, const float* gbias = nullptr) {
;     ...
;           _Pragma("unroll") for (int m = 0; m < 4; ++m) {
;             const int rl = wr * 64 + m * 16 + fr; const float rs = rsv[ai][m];
;             _Pragma("unroll") for (int bj = 0; bj < 2; ++bj) _Pragma("unroll") for (int n = 0; n < 2; ++n) {
;               f32x4 v = acc[ai][bj][m][n] * rs; u32x2 o = {pk2(v[0], v[1]), pk2(v[2], v[3])};
;               *(u32x2*)stg_ptr(shm, bj, rl, wc * 8 + n * 4 + fq) = o; }
;           }
;           stg_flush(shm, tid, dst + (size_t)(brow + ai * HALF) * pitch + c0, pitch, ai == 0, ai == 0);
	v_cvt_pk_bf16_f32 v182, v182, v183
	v_cvt_pk_bf16_f32 v183, v180, v181
	ds_write_b64 v213, v[182:183]
	v_pk_mul_f32 v[180:181], v[100:101], v[156:157] op_sel_hi:[1,0]
	v_pk_mul_f32 v[182:183], v[98:99], v[156:157] op_sel_hi:[1,0]
	v_pk_mul_f32 v[184:185], v[86:87], v[156:157] op_sel_hi:[1,0]
	v_cvt_pk_bf16_f32 v182, v182, v183
	v_cvt_pk_bf16_f32 v183, v180, v181
	ds_write_b64 v149, v[182:183] offset:40960
	v_pk_mul_f32 v[180:181], v[92:93], v[156:157] op_sel_hi:[1,0]
	v_pk_mul_f32 v[182:183], v[90:91], v[156:157] op_sel_hi:[1,0]
	v_cvt_pk_bf16_f32 v184, v184, v185
	v_cvt_pk_bf16_f32 v182, v182, v183
	v_cvt_pk_bf16_f32 v183, v180, v181
	v_pk_mul_f32 v[180:181], v[88:89], v[156:157] op_sel_hi:[1,0]
	v_add_u32_e32 v214, v187, v147
	v_cvt_pk_bf16_f32 v185, v180, v181
	ds_write_b64 v214, v[184:185]
	v_pk_mul_f32 v[180:181], v[84:85], v[156:157] op_sel_hi:[1,0]
	v_pk_mul_f32 v[184:185], v[82:83], v[156:157] op_sel_hi:[1,0]
	v_add_u32_e32 v215, v187, v153
	v_cvt_pk_bf16_f32 v184, v184, v185
	v_cvt_pk_bf16_f32 v185, v180, v181
	ds_write_b64 v215, v[184:185]
	v_pk_mul_f32 v[180:181], v[80:81], v[154:155] op_sel_hi:[1,0]
	v_pk_mul_f32 v[184:185], v[78:79], v[154:155] op_sel_hi:[1,0]
	s_ashr_i32 s9, s8, 31
	v_cvt_pk_bf16_f32 v184, v184, v185
	v_cvt_pk_bf16_f32 v185, v180, v181
	s_lshl_b64 s[16:17], s[8:9], 1
	ds_write_b64 v149, v[184:185] offset:45056
	v_pk_mul_f32 v[180:181], v[76:77], v[154:155] op_sel_hi:[1,0]
	v_pk_mul_f32 v[184:185], v[74:75], v[154:155] op_sel_hi:[1,0]
	s_add_u32 s9, s14, s16
	v_cvt_pk_bf16_f32 v184, v184, v185
	v_cvt_pk_bf16_f32 v185, v180, v181
	s_addc_u32 s7, s15, s17
	ds_write2st64_b64 v179, v[182:183], v[184:185] offset0:80 offset1:88
	v_add_u32_e32 v151, 0x1b000, v151
	v_pk_mul_f32 v[180:181], v[72:73], v[154:155] op_sel_hi:[1,0]
	v_pk_mul_f32 v[182:183], v[70:71], v[154:155] op_sel_hi:[1,0]
	s_mul_hi_i32 s15, s12, s10
	s_mul_i32 s14, s12, s10
	v_cvt_pk_bf16_f32 v182, v182, v183
	v_cvt_pk_bf16_f32 v183, v180, v181
	v_add_u32_e32 v147, v151, v147
	s_lshl_b64 s[14:15], s[14:15], 1
	ds_write_b64 v147, v[182:183]
	v_pk_mul_f32 v[180:181], v[68:69], v[154:155] op_sel_hi:[1,0]
	v_pk_mul_f32 v[182:183], v[66:67], v[154:155] op_sel_hi:[1,0]
	s_add_u32 s14, s9, s14
	v_ashrrev_i32_e32 v163, 31, v162
	v_cvt_pk_bf16_f32 v182, v182, v183
	v_cvt_pk_bf16_f32 v183, v180, v181
	v_add_u32_e32 v151, v151, v153
	s_addc_u32 s15, s7, s15
	v_lshlrev_b32_e32 v184, 1, v186
	v_mov_b32_e32 v185, v0
	ds_write_b64 v151, v[182:183]
	v_lshl_add_u64 v[186:187], s[14:15], 0, v[184:185]
	v_lshlrev_b64 v[188:189], 1, v[162:163]
	s_waitcnt lgkmcnt(0)
	s_barrier
	v_lshl_add_u64 v[186:187], v[186:187], 0, v[188:189]
	v_and_b32_e32 v162, 0xf0, v155
	v_mov_b32_e32 v163, v0
	s_waitcnt vmcnt(0)
	v_lshl_add_u64 v[186:187], v[186:187], 0, v[162:163]
	v_ashrrev_i32_e32 v165, 31, v164
	ds_read_b128 v[180:183], v157
	s_waitcnt lgkmcnt(0)
	global_store_dwordx4 v[186:187], v[180:183], off
	s_nop 7
	v_lshlrev_b32_e32 v186, 1, v190
	v_mov_b32_e32 v187, v0
	v_ashrrev_i32_e32 v166, 4, v166
	v_lshl_add_u64 v[190:191], s[14:15], 0, v[186:187]
	v_lshlrev_b64 v[192:193], 1, v[164:165]
	v_mul_u32_u24_e32 v196, s12, v167
	v_and_b32_e32 v166, 0xffffff80, v166
	v_lshl_add_u64 v[164:165], v[190:191], 0, v[192:193]
	v_ashrrev_i32_e32 v167, 31, v166
	v_lshl_add_u64 v[164:165], v[164:165], 0, v[162:163]
	v_lshlrev_b32_e32 v190, 1, v196
	v_mov_b32_e32 v191, v0
	v_ashrrev_i32_e32 v168, 4, v168
	ds_read_b128 v[180:183], v159
	s_waitcnt lgkmcnt(0)
	global_store_dwordx4 v[164:165], v[180:183], off
	s_nop 7
	v_lshl_add_u64 v[164:165], s[14:15], 0, v[190:191]
	v_lshlrev_b64 v[196:197], 1, v[166:167]
	v_and_b32_e32 v168, 0xffffff80, v168
	ds_read_b128 v[180:183], v161
	v_lshl_add_u64 v[164:165], v[164:165], 0, v[196:197]
	v_ashrrev_i32_e32 v169, 31, v168
	v_lshl_add_u64 v[164:165], v[164:165], 0, v[162:163]
	s_waitcnt lgkmcnt(0)
	global_store_dwordx4 v[164:165], v[180:183], off
	s_nop 7
	v_lshlrev_b32_e32 v180, 1, v198
	v_mov_b32_e32 v181, v0
	v_lshl_add_u64 v[182:183], s[14:15], 0, v[180:181]
	v_lshlrev_b64 v[168:169], 1, v[168:169]
	v_ashrrev_i32_e32 v170, 4, v170
	v_lshl_add_u64 v[182:183], v[182:183], 0, v[168:169]
	v_and_b32_e32 v170, 0xffffff80, v170
	v_lshl_add_u64 v[182:183], v[182:183], 0, v[162:163]
	v_ashrrev_i32_e32 v171, 31, v170
	ds_read_b128 v[164:167], v178
	s_waitcnt lgkmcnt(0)
	global_store_dwordx4 v[182:183], v[164:167], off
	s_nop 7
	v_lshlrev_b32_e32 v182, 1, v199
	v_mov_b32_e32 v183, v0
	v_lshl_add_u64 v[198:199], s[14:15], 0, v[182:183]
	v_lshlrev_b64 v[170:171], 1, v[170:171]
	v_ashrrev_i32_e32 v172, 4, v172
	v_lshl_add_u64 v[198:199], v[198:199], 0, v[170:171]
	v_and_b32_e32 v172, 0xffffff80, v172
	v_lshl_add_u64 v[198:199], v[198:199], 0, v[162:163]
	v_ashrrev_i32_e32 v173, 31, v172
	ds_read_b128 v[164:167], v206
	s_waitcnt lgkmcnt(0)
	global_store_dwordx4 v[198:199], v[164:167], off
	s_nop 7
	v_lshlrev_b32_e32 v198, 1, v200
	v_mov_b32_e32 v199, v0
	v_lshl_add_u64 v[200:201], s[14:15], 0, v[198:199]
	v_lshlrev_b64 v[172:173], 1, v[172:173]
	v_ashrrev_i32_e32 v174, 4, v174
	v_lshl_add_u64 v[200:201], v[200:201], 0, v[172:173]
	v_and_b32_e32 v174, 0xffffff80, v174
	v_lshl_add_u64 v[200:201], v[200:201], 0, v[162:163]
	v_ashrrev_i32_e32 v175, 31, v174
	ds_read_b128 v[164:167], v207
	s_waitcnt lgkmcnt(0)
	global_store_dwordx4 v[200:201], v[164:167], off
	s_nop 7
	v_lshlrev_b32_e32 v200, 1, v202
	v_mov_b32_e32 v201, v0
	v_lshl_add_u64 v[202:203], s[14:15], 0, v[200:201]
	v_lshlrev_b64 v[174:175], 1, v[174:175]
	v_ashrrev_i32_e32 v176, 4, v176
	v_lshl_add_u64 v[202:203], v[202:203], 0, v[174:175]
	v_and_b32_e32 v176, 0xffffff80, v176
	v_lshl_add_u64 v[202:203], v[202:203], 0, v[162:163]
	v_ashrrev_i32_e32 v177, 31, v176
	ds_read_b128 v[164:167], v208
	s_waitcnt lgkmcnt(0)
	global_store_dwordx4 v[202:203], v[164:167], off
	s_nop 7
	v_lshlrev_b32_e32 v202, 1, v204
	v_mov_b32_e32 v203, v0
	v_lshl_add_u64 v[204:205], s[14:15], 0, v[202:203]
	v_lshlrev_b64 v[176:177], 1, v[176:177]
	ds_read_b128 v[164:167], v209
	v_lshl_add_u64 v[204:205], v[204:205], 0, v[176:177]
	v_lshl_add_u64 v[204:205], v[204:205], 0, v[162:163]
	s_waitcnt lgkmcnt(0)
	global_store_dwordx4 v[204:205], v[164:167], off
	s_nop 7
	v_pk_mul_f32 v[164:165], v[64:65], v[152:153] op_sel_hi:[1,0]
	v_pk_mul_f32 v[166:167], v[62:63], v[152:153] op_sel_hi:[1,0]
	s_barrier
; #define LDS_BARRIER() do { asm volatile("s_waitcnt lgkmcnt(0)" ::: "memory"); __builtin_amdgcn_s_barrier(); asm volatile("" ::: "memory"); } while (0)
; __device__ __forceinline__ void st16_asm(void* ptr, u32x4 v) { asm volatile("global_store_dwordx4 %0, %1, off\n\ts_nop 7" :: "v"(ptr), "v"(v) : "memory"); }
; __device__ __forceinline__ void stg_flush(bf16* shm, int tid, bf16* dst, size_t pitch, bool first, bool tail_barrier = true) {
;   LDS_BARRIER();
;   if (first) asm volatile("s_waitcnt vmcnt(0)" ::: "memory");
;   _Pragma("unroll") for (int i = 0; i < 8; ++i) {
;     const int idx = tid + 512 * i, bjr = idx >> 11, row = (idx >> 4) & 127, c16 = idx & 15;
;     const u32x4 d = *(const u32x4*)stg_ptr(shm, bjr, row, 2 * c16);
;     st16_asm(dst + (size_t)row * pitch + bjr * HALF + c16 * 8, d); }
; template <int EPI>
; __device__ void gemm_phase(const bf16* A, int lda, const bf16* Bt, int K, int N, const Params& p, bool last, bf16* dstb, bf16* shm, unsigned long long* SSQ, int wv, const float* gbias = nullptr) {
;     ...
;         _Pragma("unroll") for (int ai = 0; ai < 2; ++ai) {
;           _Pragma("unroll") for (int m = 0; m < 4; ++m) {
;             const int rl = wr * 64 + m * 16 + fr; const float rs = rsv[ai][m];
;             _Pragma("unroll") for (int bj = 0; bj < 2; ++bj) _Pragma("unroll") for (int n = 0; n < 2; ++n) {
;               f32x4 v = acc[ai][bj][m][n] * rs; u32x2 o = {pk2(v[0], v[1]), pk2(v[2], v[3])};
;               *(u32x2*)stg_ptr(shm, bj, rl, wc * 8 + n * 4 + fq) = o; }
;           }
;           stg_flush(shm, tid, dst + (size_t)(brow + ai * HALF) * pitch + c0, pitch, ai == 0, ai == 0);
	v_cvt_pk_bf16_f32 v166, v166, v167
	v_cvt_pk_bf16_f32 v167, v164, v165
	ds_write_b64 v149, v[166:167] offset:32768
	v_pk_mul_f32 v[164:165], v[60:61], v[152:153] op_sel_hi:[1,0]
	v_pk_mul_f32 v[166:167], v[58:59], v[152:153] op_sel_hi:[1,0]
	v_pk_mul_f32 v[204:205], v[54:55], v[152:153] op_sel_hi:[1,0]
	v_cvt_pk_bf16_f32 v166, v166, v167
	v_cvt_pk_bf16_f32 v167, v164, v165
	v_pk_mul_f32 v[164:165], v[56:57], v[152:153] op_sel_hi:[1,0]
	v_cvt_pk_bf16_f32 v204, v204, v205
	v_cvt_pk_bf16_f32 v205, v164, v165
	ds_write_b64 v210, v[204:205]
	v_pk_mul_f32 v[164:165], v[52:53], v[152:153] op_sel_hi:[1,0]
	v_pk_mul_f32 v[204:205], v[50:51], v[152:153] op_sel_hi:[1,0]
	s_bitset1_b32 s10, 7
	v_cvt_pk_bf16_f32 v204, v204, v205
	v_cvt_pk_bf16_f32 v205, v164, v165
	ds_write_b64 v211, v[204:205]
	v_pk_mul_f32 v[164:165], v[48:49], v[150:151] op_sel_hi:[1,0]
	v_pk_mul_f32 v[204:205], v[46:47], v[150:151] op_sel_hi:[1,0]
	s_mul_hi_i32 s13, s12, s10
	v_cvt_pk_bf16_f32 v204, v204, v205
	v_cvt_pk_bf16_f32 v205, v164, v165
	ds_write_b64 v149, v[204:205] offset:36864
	v_pk_mul_f32 v[164:165], v[44:45], v[150:151] op_sel_hi:[1,0]
	v_pk_mul_f32 v[204:205], v[42:43], v[150:151] op_sel_hi:[1,0]
	s_mul_i32 s12, s12, s10
	v_cvt_pk_bf16_f32 v204, v204, v205
	v_cvt_pk_bf16_f32 v205, v164, v165
	ds_write2st64_b64 v179, v[166:167], v[204:205] offset0:64 offset1:72
	v_pk_mul_f32 v[164:165], v[40:41], v[150:151] op_sel_hi:[1,0]
	v_pk_mul_f32 v[166:167], v[38:39], v[150:151] op_sel_hi:[1,0]
	v_pk_mul_f32 v[204:205], v[22:23], v[148:149] op_sel_hi:[1,0]
	v_cvt_pk_bf16_f32 v166, v166, v167
	v_cvt_pk_bf16_f32 v167, v164, v165
	ds_write_b64 v212, v[166:167]
	v_pk_mul_f32 v[164:165], v[36:37], v[150:151] op_sel_hi:[1,0]
	v_pk_mul_f32 v[166:167], v[34:35], v[150:151] op_sel_hi:[1,0]
	v_cvt_pk_bf16_f32 v204, v204, v205
	v_cvt_pk_bf16_f32 v166, v166, v167
	v_cvt_pk_bf16_f32 v167, v164, v165
	ds_write_b64 v213, v[166:167]
	v_pk_mul_f32 v[164:165], v[32:33], v[148:149] op_sel_hi:[1,0]
	v_pk_mul_f32 v[166:167], v[30:31], v[148:149] op_sel_hi:[1,0]
	s_lshl_b64 s[12:13], s[12:13], 1
	v_cvt_pk_bf16_f32 v166, v166, v167
	v_cvt_pk_bf16_f32 v167, v164, v165
	ds_write_b64 v149, v[166:167] offset:40960
	v_pk_mul_f32 v[164:165], v[28:29], v[148:149] op_sel_hi:[1,0]
	v_pk_mul_f32 v[166:167], v[26:27], v[148:149] op_sel_hi:[1,0]
	s_add_u32 s12, s9, s12
	v_cvt_pk_bf16_f32 v166, v166, v167
	v_cvt_pk_bf16_f32 v167, v164, v165
	v_pk_mul_f32 v[164:165], v[24:25], v[148:149] op_sel_hi:[1,0]
	s_addc_u32 s13, s7, s13
	v_cvt_pk_bf16_f32 v205, v164, v165
	ds_write_b64 v214, v[204:205]
	v_pk_mul_f32 v[164:165], v[20:21], v[148:149] op_sel_hi:[1,0]
	v_pk_mul_f32 v[204:205], v[18:19], v[148:149] op_sel_hi:[1,0]
	v_lshl_add_u64 v[184:185], s[12:13], 0, v[184:185]
	v_cvt_pk_bf16_f32 v204, v204, v205
	v_cvt_pk_bf16_f32 v205, v164, v165
	ds_write_b64 v215, v[204:205]
	v_pk_mul_f32 v[164:165], v[16:17], v[146:147] op_sel_hi:[1,0]
	v_pk_mul_f32 v[204:205], v[14:15], v[146:147] op_sel_hi:[1,0]
	v_lshl_add_u64 v[184:185], v[184:185], 0, v[188:189]
	v_cvt_pk_bf16_f32 v204, v204, v205
	v_cvt_pk_bf16_f32 v205, v164, v165
	ds_write_b64 v149, v[204:205] offset:45056
	v_pk_mul_f32 v[164:165], v[12:13], v[146:147] op_sel_hi:[1,0]
	v_pk_mul_f32 v[204:205], v[10:11], v[146:147] op_sel_hi:[1,0]
	v_lshl_add_u64 v[184:185], v[184:185], 0, v[162:163]
	v_cvt_pk_bf16_f32 v204, v204, v205
	v_cvt_pk_bf16_f32 v205, v164, v165
	ds_write2st64_b64 v179, v[166:167], v[204:205] offset0:80 offset1:88
	v_pk_mul_f32 v[164:165], v[8:9], v[146:147] op_sel_hi:[1,0]
	v_pk_mul_f32 v[166:167], v[6:7], v[146:147] op_sel_hi:[1,0]
	s_nop 0
	v_cvt_pk_bf16_f32 v166, v166, v167
	v_cvt_pk_bf16_f32 v167, v164, v165
	ds_write_b64 v147, v[166:167]
	v_pk_mul_f32 v[164:165], v[4:5], v[146:147] op_sel_hi:[1,0]
	v_pk_mul_f32 v[166:167], v[2:3], v[146:147] op_sel_hi:[1,0]
	s_nop 0
	v_cvt_pk_bf16_f32 v166, v166, v167
	v_cvt_pk_bf16_f32 v167, v164, v165
	ds_write_b64 v151, v[166:167]
	s_waitcnt lgkmcnt(0)
	s_barrier
	ds_read_b128 v[164:167], v157
	s_waitcnt lgkmcnt(0)
	global_store_dwordx4 v[184:185], v[164:167], off
	s_nop 7
	v_lshl_add_u64 v[184:185], s[12:13], 0, v[186:187]
	v_lshl_add_u64 v[184:185], v[184:185], 0, v[192:193]
	v_lshl_add_u64 v[184:185], v[184:185], 0, v[162:163]
	ds_read_b128 v[164:167], v159
	s_waitcnt lgkmcnt(0)
	global_store_dwordx4 v[184:185], v[164:167], off
	s_nop 7
	v_lshl_add_u64 v[184:185], s[12:13], 0, v[190:191]
	v_lshl_add_u64 v[184:185], v[184:185], 0, v[196:197]
	ds_read_b128 v[164:167], v161
	v_lshl_add_u64 v[184:185], v[184:185], 0, v[162:163]
	s_waitcnt lgkmcnt(0)
	global_store_dwordx4 v[184:185], v[164:167], off
	s_nop 7
	ds_read_b128 v[164:167], v178
	v_lshl_add_u64 v[178:179], s[12:13], 0, v[180:181]
	v_lshl_add_u64 v[168:169], v[178:179], 0, v[168:169]
	v_lshl_add_u64 v[168:169], v[168:169], 0, v[162:163]
	s_waitcnt lgkmcnt(0)
	global_store_dwordx4 v[168:169], v[164:167], off
	s_nop 7
	v_lshl_add_u64 v[168:169], s[12:13], 0, v[182:183]
	v_lshl_add_u64 v[168:169], v[168:169], 0, v[170:171]
	v_lshl_add_u64 v[168:169], v[168:169], 0, v[162:163]
	ds_read_b128 v[164:167], v206
	s_waitcnt lgkmcnt(0)
	global_store_dwordx4 v[168:169], v[164:167], off
	s_nop 7
	v_lshl_add_u64 v[168:169], s[12:13], 0, v[198:199]
	v_lshl_add_u64 v[168:169], v[168:169], 0, v[172:173]
	v_lshl_add_u64 v[168:169], v[168:169], 0, v[162:163]
	ds_read_b128 v[164:167], v207
	s_waitcnt lgkmcnt(0)
	global_store_dwordx4 v[168:169], v[164:167], off
	s_nop 7
	v_lshl_add_u64 v[168:169], s[12:13], 0, v[200:201]
	v_lshl_add_u64 v[168:169], v[168:169], 0, v[174:175]
	v_lshl_add_u64 v[168:169], v[168:169], 0, v[162:163]
	ds_read_b128 v[164:167], v208
	s_waitcnt lgkmcnt(0)
	global_store_dwordx4 v[168:169], v[164:167], off
	s_nop 7
	v_lshl_add_u64 v[168:169], s[12:13], 0, v[202:203]
	v_lshl_add_u64 v[168:169], v[168:169], 0, v[176:177]
	ds_read_b128 v[164:167], v209
	v_lshl_add_u64 v[162:163], v[168:169], 0, v[162:163]
	s_waitcnt lgkmcnt(0)
	global_store_dwordx4 v[162:163], v[164:167], off
	s_nop 7
	s_cbranch_execnz .LBB0_161

; __device__ void mix_phase(const Params& p, int layer, bf16* shm, int wv) {
;     ...
;     const int wid = tid >> 6, lane = tid & 63, wr = wid >> 2, wc = wid & 3, fr = lane & 15, fq = lane >> 4;
;     const int cb = bcol + wc * 32 + fq * 4;
;     unsigned w1a[2][4][2][2];
;     _Pragma("unroll") for (int ai = 0; ai < 2; ++ai) _Pragma("unroll") for (int m = 0; m < 4; ++m) _Pragma("unroll") for (int bj = 0; bj < 2; ++bj) _Pragma("unroll") for (int n = 0; n < 2; ++n)
;       w1a[ai][m][bj][n] = *(const unsigned*)(Gp + ((size_t)pm_ * 16 + 8 + pn_) * 65536 + (ai * 16 + m * 4 + bj * 2 + n) * 2048 + tid * 4);
;     asm volatile("s_waitcnt vmcnt(0)" ::: "memory");
;     _Pragma("unroll") for (int ai = 0; ai < 2; ++ai) {
;       unsigned (&w1)[4][2][2] = w1a[ai];
;       _Pragma("unroll") for (int m = 0; m < 4; ++m) _Pragma("unroll") for (int bj = 0; bj < 2; ++bj) _Pragma("unroll") for (int n = 0; n < 2; ++n) {
;         f32x4 g1 = gate_u8(w1[m][bj][n]); f32x4 v = acc[ai][bj][m][n];
;         for (int j = 0; j < 4; ++j) v[j] *= fmaxf(g1[j], 1.f / 510.f);
;         u32x2 o = {pk2(v[0], v[1]), pk2(v[2], v[3])};
;         *(u32x2*)stg_ptr(shm, bj, wr * 64 + m * 16 + fr, wc * 8 + n * 4 + fq) = o; }
.LBB0_396:
	s_or_b64 exec, exec, s[12:13]
	s_mov_b32 s1, 0xffffc0
	v_lshlrev_b32_e32 v130, 2, v249
	v_ashrrev_i32_e32 v131, 31, v130
	v_lshl_add_u64 v[130:131], s[10:11], 0, v[130:131]
	v_add_co_u32_e32 v134, vcc, 0x80000, v130
	s_mov_b64 s[10:11], 0x80000
	s_nop 0
	v_addc_co_u32_e32 v135, vcc, 0, v131, vcc
	v_add_co_u32_e32 v136, vcc, 0x81000, v130
	v_lshl_add_u64 v[132:133], v[130:131], 0, s[10:11]
	s_nop 0
	v_addc_co_u32_e32 v137, vcc, 0, v131, vcc
	v_add_co_u32_e32 v138, vcc, 0x82000, v130
	v_and_b32_e32 v1, 15, v249
	s_nop 0
	v_addc_co_u32_e32 v139, vcc, 0, v131, vcc
	v_add_co_u32_e32 v140, vcc, 0x83000, v130
	v_lshlrev_b32_e32 v196, 4, v1
	s_nop 0
	v_addc_co_u32_e32 v141, vcc, 0, v131, vcc
	global_load_dword v182, v[134:135], off
	global_load_dword v184, v[136:137], off
	global_load_dword v185, v[136:137], off offset:2048
	global_load_dword v186, v[138:139], off
	global_load_dword v187, v[138:139], off offset:2048
	global_load_dword v188, v[140:141], off
	global_load_dword v189, v[140:141], off offset:2048
	global_load_dword v190, v[132:133], off offset:2048
	v_add_co_u32_e32 v132, vcc, 0x84000, v130
	s_lshl_b64 s[8:9], s[8:9], 1
	s_nop 0
	v_addc_co_u32_e32 v133, vcc, 0, v131, vcc
	v_add_co_u32_e32 v134, vcc, 0x85000, v130
	v_bfe_u32 v172, v249, 4, 7
	s_nop 0
	v_addc_co_u32_e32 v135, vcc, 0, v131, vcc
	v_add_co_u32_e32 v136, vcc, 0x86000, v130
	s_add_u32 s5, s31, s8
	s_nop 0
	v_addc_co_u32_e32 v137, vcc, 0, v131, vcc
	v_add_co_u32_e32 v138, vcc, 0x87000, v130
	s_waitcnt vmcnt(7)
	v_cvt_f32_ubyte1_e32 v198, v182
	v_addc_co_u32_e32 v139, vcc, 0, v131, vcc
	global_load_dword v191, v[132:133], off
	global_load_dword v192, v[132:133], off offset:2048
	global_load_dword v193, v[134:135], off
	global_load_dword v180, v[134:135], off offset:2048
	global_load_dword v176, v[136:137], off
	global_load_dword v171, v[136:137], off offset:2048
	global_load_dword v170, v[138:139], off
	global_load_dword v169, v[138:139], off offset:2048
	v_add_co_u32_e32 v132, vcc, 0x88000, v130
	v_cvt_f32_ubyte2_e32 v199, v182
	s_nop 0
	v_addc_co_u32_e32 v133, vcc, 0, v131, vcc
	v_add_co_u32_e32 v134, vcc, 0x89000, v130
	v_cvt_f32_ubyte3_e32 v200, v182
	s_nop 0
	v_addc_co_u32_e32 v135, vcc, 0, v131, vcc
	v_add_co_u32_e32 v136, vcc, 0x8a000, v130
	s_nop 1
	v_addc_co_u32_e32 v137, vcc, 0, v131, vcc
	v_add_co_u32_e32 v138, vcc, 0x8b000, v130
	s_nop 1
	v_addc_co_u32_e32 v139, vcc, 0, v131, vcc
	global_load_dword v168, v[132:133], off
	global_load_dword v167, v[132:133], off offset:2048
	global_load_dword v166, v[134:135], off
	global_load_dword v165, v[134:135], off offset:2048
	global_load_dword v164, v[136:137], off
	global_load_dword v163, v[136:137], off offset:2048
	global_load_dword v162, v[138:139], off
	global_load_dword v160, v[138:139], off offset:2048
	v_add_co_u32_e32 v132, vcc, 0x8c000, v130
	s_nop 1
	v_addc_co_u32_e32 v133, vcc, 0, v131, vcc
	v_add_co_u32_e32 v134, vcc, 0x8d000, v130
	s_nop 1
	v_addc_co_u32_e32 v135, vcc, 0, v131, vcc
	v_add_co_u32_e32 v136, vcc, 0x8e000, v130
	s_nop 1
	v_addc_co_u32_e32 v137, vcc, 0, v131, vcc
	v_add_co_u32_e32 v130, vcc, 0x8f000, v130
	s_nop 1
	v_addc_co_u32_e32 v131, vcc, 0, v131, vcc
	global_load_dword v161, v[132:133], off
	global_load_dword v159, v[132:133], off offset:2048
	global_load_dword v158, v[134:135], off
	global_load_dword v157, v[134:135], off offset:2048
	global_load_dword v156, v[136:137], off
	global_load_dword v153, v[136:137], off offset:2048
	global_load_dword v150, v[130:131], off
	global_load_dword v147, v[130:131], off offset:2048
	v_add_u32_e32 v132, 0x200, v249
	v_lshrrev_b32_e32 v131, 2, v249
	v_cmp_gt_u32_e32 vcc, s85, v249
	v_lshrrev_b32_e32 v133, 4, v132
	v_and_or_b32 v183, v131, s1, v1
	v_cndmask_b32_e32 v1, v244, v245, vcc
	v_cmp_gt_u32_e32 vcc, s85, v132
	v_xor_b32_e32 v133, v133, v249
	v_bfe_u32 v173, v132, 4, 7
	v_cndmask_b32_e32 v134, v244, v245, vcc
	v_lshlrev_b32_e32 v133, 4, v133
	v_add_u32_e32 v134, 0, v134
	v_lshlrev_b32_e32 v135, 8, v173
	v_and_b32_e32 v133, 0xf0, v133
	v_add3_u32 v146, v134, v135, v133
	v_add_u32_e32 v134, 0x400, v249
	v_lshrrev_b32_e32 v135, 4, v134
	v_cmp_gt_u32_e32 vcc, s85, v134
	v_xor_b32_e32 v135, v135, v249
	v_bfe_u32 v174, v134, 4, 7
	v_cndmask_b32_e32 v136, v244, v245, vcc
	v_lshlrev_b32_e32 v135, 4, v135
	v_add_u32_e32 v136, 0, v136
	v_lshlrev_b32_e32 v137, 8, v174
	v_and_b32_e32 v135, 0xf0, v135
	v_add3_u32 v148, v136, v137, v135
	v_add_u32_e32 v136, 0x600, v249
	v_lshrrev_b32_e32 v137, 4, v136
	v_cmp_gt_u32_e32 vcc, s85, v136
	v_xor_b32_e32 v137, v137, v249
	v_bfe_u32 v175, v136, 4, 7
	v_cndmask_b32_e32 v138, v244, v245, vcc
	v_lshlrev_b32_e32 v137, 4, v137
	v_add_u32_e32 v138, 0, v138
	v_lshlrev_b32_e32 v139, 8, v175
	v_and_b32_e32 v137, 0xf0, v137
	v_add3_u32 v149, v138, v139, v137
	v_add_u32_e32 v138, 0x800, v249
	v_lshrrev_b32_e32 v139, 4, v138
	v_cmp_lt_u32_e32 vcc, s65, v249
	v_xor_b32_e32 v139, v139, v249
	v_bfe_u32 v177, v138, 4, 7
	v_cndmask_b32_e32 v140, v244, v245, vcc
	v_lshlrev_b32_e32 v139, 4, v139
	v_add_u32_e32 v140, 0, v140
	v_lshlrev_b32_e32 v141, 8, v177
	v_and_b32_e32 v139, 0xf0, v139
	v_add3_u32 v151, v140, v141, v139
	v_add_u32_e32 v140, 0xa00, v249
	v_lshrrev_b32_e32 v141, 4, v140
	v_cmp_gt_u32_e32 vcc, s85, v140
	v_xor_b32_e32 v141, v141, v249
	v_bfe_u32 v178, v140, 4, 7
	v_cndmask_b32_e32 v142, v244, v245, vcc
	v_lshlrev_b32_e32 v141, 4, v141
	v_add_u32_e32 v142, 0, v142
	v_lshlrev_b32_e32 v143, 8, v178
	v_and_b32_e32 v141, 0xf0, v141
	v_add3_u32 v152, v142, v143, v141
	v_add_u32_e32 v142, 0xc00, v249
	v_lshrrev_b32_e32 v143, 4, v142
	v_cmp_gt_u32_e32 vcc, s85, v142
	v_xor_b32_e32 v143, v143, v249
	v_bfe_u32 v179, v142, 4, 7
	v_cndmask_b32_e32 v144, v244, v245, vcc
	v_lshlrev_b32_e32 v143, 4, v143
	v_add_u32_e32 v144, 0, v144
	v_lshlrev_b32_e32 v145, 8, v179
	v_and_b32_e32 v143, 0xf0, v143
	v_add3_u32 v154, v144, v145, v143
	v_add_u32_e32 v144, 0xe00, v249
	v_lshrrev_b32_e32 v145, 4, v144
	v_cmp_gt_u32_e32 vcc, s85, v144
	v_xor_b32_e32 v145, v145, v249
	v_bfe_u32 v181, v144, 4, 7
	v_cndmask_b32_e32 v155, v244, v245, vcc
	v_lshlrev_b32_e32 v145, 4, v145
	v_add_u32_e32 v155, 0, v155
	v_lshlrev_b32_e32 v197, 8, v181
	v_and_b32_e32 v145, 0xf0, v145
	v_add3_u32 v155, v155, v197, v145
	v_lshl_add_u32 v197, v183, 8, 0
	v_cvt_f32_ubyte0_e32 v183, v182
	v_mul_f32_e32 v182, 0x3b808081, v183
	v_mul_f32_e32 v183, 0x3b808081, v198
	v_max_f32_e32 v182, 0x3b008081, v182
	v_max_f32_e32 v183, 0x3b008081, v183
	v_pk_mul_f32 v[126:127], v[126:127], v[182:183]
	v_mul_f32_e32 v182, 0x3b808081, v199
	v_mul_f32_e32 v183, 0x3b808081, v200
	v_max_f32_e32 v182, 0x3b008081, v182
	v_max_f32_e32 v183, 0x3b008081, v183
	v_pk_mul_f32 v[128:129], v[128:129], v[182:183]
	v_cvt_pk_bf16_f32 v182, v126, v127
	v_lshrrev_b32_e32 v126, 1, v249
	v_and_b32_e32 v126, 24, v126
	v_and_b32_e32 v127, 0xc0, v249
	v_cvt_pk_bf16_f32 v183, v128, v129
	v_or_b32_e32 v198, v126, v127
	v_bitop3_b32 v127, v126, v196, v127 bitop3:0x36
	s_waitcnt vmcnt(24)
; __device__ void mix_phase(const Params& p, int layer, bf16* shm, int wv) {
;     ...
;     unsigned w1a[2][4][2][2];
;     _Pragma("unroll") for (int ai = 0; ai < 2; ++ai) _Pragma("unroll") for (int m = 0; m < 4; ++m) _Pragma("unroll") for (int bj = 0; bj < 2; ++bj) _Pragma("unroll") for (int n = 0; n < 2; ++n)
;       w1a[ai][m][bj][n] = *(const unsigned*)(Gp + ((size_t)pm_ * 16 + 8 + pn_) * 65536 + (ai * 16 + m * 4 + bj * 2 + n) * 2048 + tid * 4);
;     asm volatile("s_waitcnt vmcnt(0)" ::: "memory");
;     _Pragma("unroll") for (int ai = 0; ai < 2; ++ai) {
;       unsigned (&w1)[4][2][2] = w1a[ai];
;       _Pragma("unroll") for (int m = 0; m < 4; ++m) _Pragma("unroll") for (int bj = 0; bj < 2; ++bj) _Pragma("unroll") for (int n = 0; n < 2; ++n) {
;         f32x4 g1 = gate_u8(w1[m][bj][n]); f32x4 v = acc[ai][bj][m][n];
;         for (int j = 0; j < 4; ++j) v[j] *= fmaxf(g1[j], 1.f / 510.f);
;         u32x2 o = {pk2(v[0], v[1]), pk2(v[2], v[3])};
;         *(u32x2*)stg_ptr(shm, bj, wr * 64 + m * 16 + fr, wc * 8 + n * 4 + fq) = o; }
;       stg_flush(shm, tid, MX + (size_t)(brow + ai * HALF) * DM + bcol, (size_t)DM, false, ai == 0);
	v_cvt_f32_ubyte0_e32 v128, v190
	v_cvt_f32_ubyte1_e32 v129, v190
	v_add_u32_e32 v126, v197, v127
	v_mul_f32_e32 v128, 0x3b808081, v128
	v_mul_f32_e32 v129, 0x3b808081, v129
	s_waitcnt vmcnt(0)
	ds_write_b64 v126, v[182:183] offset:32768
	v_cvt_f32_ubyte2_e32 v182, v190
	v_cvt_f32_ubyte3_e32 v183, v190
	v_max_f32_e32 v128, 0x3b008081, v128
	v_max_f32_e32 v129, 0x3b008081, v129
	v_pk_mul_f32 v[122:123], v[122:123], v[128:129]
	v_mul_f32_e32 v128, 0x3b808081, v182
	v_mul_f32_e32 v129, 0x3b808081, v183
	v_max_f32_e32 v128, 0x3b008081, v128
	v_max_f32_e32 v129, 0x3b008081, v129
	v_pk_mul_f32 v[124:125], v[124:125], v[128:129]
	v_cvt_f32_ubyte2_e32 v183, v184
	v_cvt_pk_bf16_f32 v129, v124, v125
	v_cvt_f32_ubyte0_e32 v124, v184
	v_cvt_f32_ubyte1_e32 v125, v184
	v_mul_f32_e32 v124, 0x3b808081, v124
	v_mul_f32_e32 v125, 0x3b808081, v125
	v_cvt_f32_ubyte3_e32 v184, v184
	v_max_f32_e32 v124, 0x3b008081, v124
	v_max_f32_e32 v125, 0x3b008081, v125
	v_pk_mul_f32 v[118:119], v[118:119], v[124:125]
	v_mul_f32_e32 v124, 0x3b808081, v183
	v_mul_f32_e32 v125, 0x3b808081, v184
	v_max_f32_e32 v124, 0x3b008081, v124
	v_max_f32_e32 v125, 0x3b008081, v125
	v_add_u32_e32 v182, 0x18000, v197
	v_pk_mul_f32 v[120:121], v[120:121], v[124:125]
	v_cvt_pk_bf16_f32 v118, v118, v119
	v_cvt_pk_bf16_f32 v119, v120, v121
	v_add_u32_e32 v120, v182, v127
	ds_write_b64 v120, v[118:119]
	v_cvt_f32_ubyte0_e32 v118, v185
	v_cvt_f32_ubyte1_e32 v119, v185
	v_mul_f32_e32 v118, 0x3b808081, v118
	v_mul_f32_e32 v119, 0x3b808081, v119
	v_cvt_f32_ubyte2_e32 v121, v185
	v_cvt_f32_ubyte3_e32 v124, v185
	v_max_f32_e32 v118, 0x3b008081, v118
	v_max_f32_e32 v119, 0x3b008081, v119
	v_pk_mul_f32 v[114:115], v[114:115], v[118:119]
	v_mul_f32_e32 v118, 0x3b808081, v121
	v_mul_f32_e32 v119, 0x3b808081, v124
	v_max_f32_e32 v118, 0x3b008081, v118
	v_max_f32_e32 v119, 0x3b008081, v119
	v_cvt_pk_bf16_f32 v128, v122, v123
	v_bitop3_b32 v123, v198, v196, 32 bitop3:0x36
	v_pk_mul_f32 v[116:117], v[116:117], v[118:119]
	v_cvt_pk_bf16_f32 v114, v114, v115
	v_cvt_pk_bf16_f32 v115, v116, v117
	v_add_u32_e32 v116, v182, v123
	ds_write_b64 v116, v[114:115]
	v_cvt_f32_ubyte0_e32 v114, v186
	v_cvt_f32_ubyte1_e32 v115, v186
	v_mul_f32_e32 v114, 0x3b808081, v114
	v_mul_f32_e32 v115, 0x3b808081, v115
	v_cvt_f32_ubyte2_e32 v117, v186
	v_cvt_f32_ubyte3_e32 v118, v186
	v_max_f32_e32 v114, 0x3b008081, v114
	v_max_f32_e32 v115, 0x3b008081, v115
	v_pk_mul_f32 v[110:111], v[110:111], v[114:115]
	v_mul_f32_e32 v114, 0x3b808081, v117
	v_mul_f32_e32 v115, 0x3b808081, v118
	v_max_f32_e32 v114, 0x3b008081, v114
	v_max_f32_e32 v115, 0x3b008081, v115
	v_pk_mul_f32 v[112:113], v[112:113], v[114:115]
	v_cvt_pk_bf16_f32 v110, v110, v111
	v_cvt_pk_bf16_f32 v111, v112, v113
	ds_write_b64 v126, v[110:111] offset:36864
	v_cvt_f32_ubyte0_e32 v110, v187
	v_cvt_f32_ubyte1_e32 v111, v187
	v_mul_f32_e32 v110, 0x3b808081, v110
	v_mul_f32_e32 v111, 0x3b808081, v111
	v_cvt_f32_ubyte2_e32 v112, v187
	v_cvt_f32_ubyte3_e32 v113, v187
	v_max_f32_e32 v110, 0x3b008081, v110
	v_max_f32_e32 v111, 0x3b008081, v111
	v_pk_mul_f32 v[106:107], v[106:107], v[110:111]
	v_mul_f32_e32 v110, 0x3b808081, v112
	v_mul_f32_e32 v111, 0x3b808081, v113
	v_max_f32_e32 v110, 0x3b008081, v110
	v_max_f32_e32 v111, 0x3b008081, v111
	v_pk_mul_f32 v[108:109], v[108:109], v[110:111]
	v_add_u32_e32 v122, v197, v123
	v_cvt_pk_bf16_f32 v106, v106, v107
	v_cvt_pk_bf16_f32 v107, v108, v109
	ds_write2st64_b64 v122, v[128:129], v[106:107] offset0:64 offset1:72
	v_cvt_f32_ubyte0_e32 v106, v188
	v_cvt_f32_ubyte1_e32 v107, v188
	v_mul_f32_e32 v106, 0x3b808081, v106
	v_mul_f32_e32 v107, 0x3b808081, v107
	v_cvt_f32_ubyte2_e32 v109, v188
	v_cvt_f32_ubyte3_e32 v110, v188
	v_max_f32_e32 v106, 0x3b008081, v106
	v_max_f32_e32 v107, 0x3b008081, v107
	v_pk_mul_f32 v[102:103], v[102:103], v[106:107]
	v_mul_f32_e32 v106, 0x3b808081, v109
	v_mul_f32_e32 v107, 0x3b808081, v110
	v_max_f32_e32 v106, 0x3b008081, v106
	v_max_f32_e32 v107, 0x3b008081, v107
	v_add_u32_e32 v108, 0x19000, v197
	v_pk_mul_f32 v[104:105], v[104:105], v[106:107]
	v_cvt_pk_bf16_f32 v102, v102, v103
	v_cvt_pk_bf16_f32 v103, v104, v105
	v_add_u32_e32 v106, v108, v127
	ds_write_b64 v106, v[102:103]
	v_cvt_f32_ubyte0_e32 v102, v189
	v_cvt_f32_ubyte1_e32 v103, v189
	v_mul_f32_e32 v102, 0x3b808081, v102
	v_mul_f32_e32 v103, 0x3b808081, v103
	v_cvt_f32_ubyte2_e32 v104, v189
	v_cvt_f32_ubyte3_e32 v105, v189
	v_max_f32_e32 v102, 0x3b008081, v102
	v_max_f32_e32 v103, 0x3b008081, v103
	v_pk_mul_f32 v[98:99], v[98:99], v[102:103]
	v_mul_f32_e32 v102, 0x3b808081, v104
	v_mul_f32_e32 v103, 0x3b808081, v105
	v_max_f32_e32 v102, 0x3b008081, v102
	v_max_f32_e32 v103, 0x3b008081, v103
	v_pk_mul_f32 v[100:101], v[100:101], v[102:103]
	v_cvt_pk_bf16_f32 v98, v98, v99
	v_cvt_pk_bf16_f32 v99, v100, v101
	v_add_u32_e32 v107, v108, v123
	ds_write_b64 v107, v[98:99]
	v_cvt_f32_ubyte0_e32 v98, v191
	v_cvt_f32_ubyte1_e32 v99, v191
	v_mul_f32_e32 v98, 0x3b808081, v98
	v_mul_f32_e32 v99, 0x3b808081, v99
	v_cvt_f32_ubyte2_e32 v100, v191
	v_cvt_f32_ubyte3_e32 v101, v191
	v_max_f32_e32 v98, 0x3b008081, v98
	v_max_f32_e32 v99, 0x3b008081, v99
	v_pk_mul_f32 v[94:95], v[94:95], v[98:99]
	v_mul_f32_e32 v98, 0x3b808081, v100
	v_mul_f32_e32 v99, 0x3b808081, v101
	v_max_f32_e32 v98, 0x3b008081, v98
	v_max_f32_e32 v99, 0x3b008081, v99
	v_pk_mul_f32 v[96:97], v[96:97], v[98:99]
	v_cvt_pk_bf16_f32 v94, v94, v95
	v_cvt_pk_bf16_f32 v95, v96, v97
	ds_write_b64 v126, v[94:95] offset:40960
	v_cvt_f32_ubyte0_e32 v94, v192
	v_cvt_f32_ubyte1_e32 v95, v192
	v_mul_f32_e32 v94, 0x3b808081, v94
	v_mul_f32_e32 v95, 0x3b808081, v95
	v_cvt_f32_ubyte2_e32 v96, v192
; #define LDS_BARRIER() do { asm volatile("s_waitcnt lgkmcnt(0)" ::: "memory"); __builtin_amdgcn_s_barrier(); asm volatile("" ::: "memory"); } while (0)
; __device__ __forceinline__ void stg_flush(bf16* shm, int tid, bf16* dst, size_t pitch, bool first, bool tail_barrier = true) {
;   LDS_BARRIER();
; __device__ void mix_phase(const Params& p, int layer, bf16* shm, int wv) {
;     ...
;     _Pragma("unroll") for (int ai = 0; ai < 2; ++ai) {
;       unsigned (&w1)[4][2][2] = w1a[ai];
;       _Pragma("unroll") for (int m = 0; m < 4; ++m) _Pragma("unroll") for (int bj = 0; bj < 2; ++bj) _Pragma("unroll") for (int n = 0; n < 2; ++n) {
;         f32x4 g1 = gate_u8(w1[m][bj][n]); f32x4 v = acc[ai][bj][m][n];
;         for (int j = 0; j < 4; ++j) v[j] *= fmaxf(g1[j], 1.f / 510.f);
;         u32x2 o = {pk2(v[0], v[1]), pk2(v[2], v[3])};
;         *(u32x2*)stg_ptr(shm, bj, wr * 64 + m * 16 + fr, wc * 8 + n * 4 + fq) = o; }
;       stg_flush(shm, tid, MX + (size_t)(brow + ai * HALF) * DM + bcol, (size_t)DM, false, ai == 0);
	v_cvt_f32_ubyte3_e32 v97, v192
	v_max_f32_e32 v94, 0x3b008081, v94
	v_max_f32_e32 v95, 0x3b008081, v95
	v_pk_mul_f32 v[90:91], v[90:91], v[94:95]
	v_mul_f32_e32 v94, 0x3b808081, v96
	v_mul_f32_e32 v95, 0x3b808081, v97
	v_max_f32_e32 v94, 0x3b008081, v94
	v_max_f32_e32 v95, 0x3b008081, v95
	v_pk_mul_f32 v[92:93], v[92:93], v[94:95]
	v_cvt_pk_bf16_f32 v90, v90, v91
	v_cvt_pk_bf16_f32 v91, v92, v93
	v_cvt_f32_ubyte0_e32 v92, v193
	v_cvt_f32_ubyte1_e32 v93, v193
	v_mul_f32_e32 v92, 0x3b808081, v92
	v_mul_f32_e32 v93, 0x3b808081, v93
	v_cvt_f32_ubyte2_e32 v95, v193
	v_cvt_f32_ubyte3_e32 v96, v193
	v_max_f32_e32 v92, 0x3b008081, v92
	v_max_f32_e32 v93, 0x3b008081, v93
	v_pk_mul_f32 v[86:87], v[86:87], v[92:93]
	v_mul_f32_e32 v92, 0x3b808081, v95
	v_mul_f32_e32 v93, 0x3b808081, v96
	v_max_f32_e32 v92, 0x3b008081, v92
	v_max_f32_e32 v93, 0x3b008081, v93
	v_add_u32_e32 v94, 0x1a000, v197
	v_pk_mul_f32 v[88:89], v[88:89], v[92:93]
	v_cvt_pk_bf16_f32 v86, v86, v87
	v_cvt_pk_bf16_f32 v87, v88, v89
	v_add_u32_e32 v108, v94, v127
	ds_write_b64 v108, v[86:87]
	v_cvt_f32_ubyte0_e32 v86, v180
	v_cvt_f32_ubyte1_e32 v87, v180
	v_mul_f32_e32 v86, 0x3b808081, v86
	v_mul_f32_e32 v87, 0x3b808081, v87
	v_cvt_f32_ubyte2_e32 v88, v180
	v_cvt_f32_ubyte3_e32 v89, v180
	v_max_f32_e32 v86, 0x3b008081, v86
	v_max_f32_e32 v87, 0x3b008081, v87
	v_pk_mul_f32 v[82:83], v[82:83], v[86:87]
	v_mul_f32_e32 v86, 0x3b808081, v88
	v_mul_f32_e32 v87, 0x3b808081, v89
	v_max_f32_e32 v86, 0x3b008081, v86
	v_max_f32_e32 v87, 0x3b008081, v87
	v_pk_mul_f32 v[84:85], v[84:85], v[86:87]
	v_cvt_pk_bf16_f32 v82, v82, v83
	v_cvt_pk_bf16_f32 v83, v84, v85
	v_add_u32_e32 v109, v94, v123
	ds_write_b64 v109, v[82:83]
	v_cvt_f32_ubyte0_e32 v82, v176
	v_cvt_f32_ubyte1_e32 v83, v176
	v_mul_f32_e32 v82, 0x3b808081, v82
	v_mul_f32_e32 v83, 0x3b808081, v83
	v_cvt_f32_ubyte2_e32 v84, v176
	v_cvt_f32_ubyte3_e32 v85, v176
	v_max_f32_e32 v82, 0x3b008081, v82
	v_max_f32_e32 v83, 0x3b008081, v83
	v_pk_mul_f32 v[78:79], v[78:79], v[82:83]
	v_mul_f32_e32 v82, 0x3b808081, v84
	v_mul_f32_e32 v83, 0x3b808081, v85
	v_max_f32_e32 v82, 0x3b008081, v82
	v_max_f32_e32 v83, 0x3b008081, v83
	v_pk_mul_f32 v[80:81], v[80:81], v[82:83]
	v_cvt_pk_bf16_f32 v78, v78, v79
	v_cvt_pk_bf16_f32 v79, v80, v81
	ds_write_b64 v126, v[78:79] offset:45056
	v_cvt_f32_ubyte0_e32 v78, v171
	v_cvt_f32_ubyte1_e32 v79, v171
	v_mul_f32_e32 v78, 0x3b808081, v78
	v_mul_f32_e32 v79, 0x3b808081, v79
	v_cvt_f32_ubyte2_e32 v80, v171
	v_cvt_f32_ubyte3_e32 v81, v171
	v_max_f32_e32 v78, 0x3b008081, v78
	v_max_f32_e32 v79, 0x3b008081, v79
	v_pk_mul_f32 v[74:75], v[74:75], v[78:79]
	v_mul_f32_e32 v78, 0x3b808081, v80
	v_mul_f32_e32 v79, 0x3b808081, v81
	v_max_f32_e32 v78, 0x3b008081, v78
	v_max_f32_e32 v79, 0x3b008081, v79
	v_pk_mul_f32 v[76:77], v[76:77], v[78:79]
	v_cvt_pk_bf16_f32 v74, v74, v75
	v_cvt_pk_bf16_f32 v75, v76, v77
	ds_write2st64_b64 v122, v[90:91], v[74:75] offset0:80 offset1:88
	v_cvt_f32_ubyte0_e32 v74, v170
	v_cvt_f32_ubyte1_e32 v75, v170
	v_mul_f32_e32 v74, 0x3b808081, v74
	v_mul_f32_e32 v75, 0x3b808081, v75
	v_cvt_f32_ubyte2_e32 v77, v170
	v_cvt_f32_ubyte3_e32 v78, v170
	v_max_f32_e32 v74, 0x3b008081, v74
	v_max_f32_e32 v75, 0x3b008081, v75
	v_pk_mul_f32 v[70:71], v[70:71], v[74:75]
	v_mul_f32_e32 v74, 0x3b808081, v77
	v_mul_f32_e32 v75, 0x3b808081, v78
	v_max_f32_e32 v74, 0x3b008081, v74
	v_max_f32_e32 v75, 0x3b008081, v75
	v_add_u32_e32 v76, 0x1b000, v197
	v_pk_mul_f32 v[72:73], v[72:73], v[74:75]
	v_cvt_pk_bf16_f32 v70, v70, v71
	v_cvt_pk_bf16_f32 v71, v72, v73
	v_add_u32_e32 v110, v76, v127
	v_lshrrev_b32_e32 v130, 4, v249
	ds_write_b64 v110, v[70:71]
	v_cvt_f32_ubyte0_e32 v70, v169
	v_cvt_f32_ubyte1_e32 v71, v169
	v_xor_b32_e32 v130, v130, v249
	v_mul_f32_e32 v70, 0x3b808081, v70
	v_mul_f32_e32 v71, 0x3b808081, v71
	v_lshlrev_b32_e32 v130, 4, v130
	v_cvt_f32_ubyte2_e32 v72, v169
	v_cvt_f32_ubyte3_e32 v73, v169
	v_max_f32_e32 v70, 0x3b008081, v70
	v_max_f32_e32 v71, 0x3b008081, v71
	v_add_u32_e32 v1, 0, v1
	v_lshlrev_b32_e32 v131, 8, v172
	v_and_b32_e32 v130, 0xf0, v130
	v_pk_mul_f32 v[66:67], v[66:67], v[70:71]
	v_mul_f32_e32 v70, 0x3b808081, v72
	v_mul_f32_e32 v71, 0x3b808081, v73
	s_addc_u32 s1, s35, s9
	v_add3_u32 v1, v1, v131, v130
	v_ashrrev_i32_e32 v130, 4, v249
	v_max_f32_e32 v70, 0x3b008081, v70
	v_max_f32_e32 v71, 0x3b008081, v71
	s_lshl_b64 s[8:9], s[6:7], 12
	v_and_b32_e32 v130, 0xffffff80, v130
	v_pk_mul_f32 v[68:69], v[68:69], v[70:71]
	s_add_u32 s8, s5, s8
	v_ashrrev_i32_e32 v131, 31, v130
	v_cvt_pk_bf16_f32 v66, v66, v67
	v_cvt_pk_bf16_f32 v67, v68, v69
	v_add_u32_e32 v111, v76, v123
	s_addc_u32 s9, s1, s9
	v_lshlrev_b32_e32 v68, 12, v172
	v_mov_b32_e32 v69, v0
	ds_write_b64 v111, v[66:67]
	v_lshl_add_u64 v[66:67], s[8:9], 0, v[68:69]
	v_lshlrev_b64 v[70:71], 1, v[130:131]
	v_ashrrev_i32_e32 v132, 4, v132
	s_waitcnt lgkmcnt(0)
	s_barrier
; #define LDS_BARRIER() do { asm volatile("s_waitcnt lgkmcnt(0)" ::: "memory"); __builtin_amdgcn_s_barrier(); asm volatile("" ::: "memory"); } while (0)
; __device__ __forceinline__ void st16_asm(void* ptr, u32x4 v) { asm volatile("global_store_dwordx4 %0, %1, off\n\ts_nop 7" :: "v"(ptr), "v"(v) : "memory"); }
; __device__ __forceinline__ void stg_flush(bf16* shm, int tid, bf16* dst, size_t pitch, bool first, bool tail_barrier = true) {
;   LDS_BARRIER();
;   if (first) asm volatile("s_waitcnt vmcnt(0)" ::: "memory");
;   _Pragma("unroll") for (int i = 0; i < 8; ++i) {
;     const int idx = tid + 512 * i, bjr = idx >> 11, row = (idx >> 4) & 127, c16 = idx & 15;
;     const u32x4 d = *(const u32x4*)stg_ptr(shm, bjr, row, 2 * c16);
;     st16_asm(dst + (size_t)row * pitch + bjr * HALF + c16 * 8, d); }
;   if (tail_barrier) LDS_BARRIER();
; }
; __device__ void mix_phase(const Params& p, int layer, bf16* shm, int wv) {
;     ...
;     _Pragma("unroll") for (int ai = 0; ai < 2; ++ai) {
;       unsigned (&w1)[4][2][2] = w1a[ai];
;       _Pragma("unroll") for (int m = 0; m < 4; ++m) _Pragma("unroll") for (int bj = 0; bj < 2; ++bj) _Pragma("unroll") for (int n = 0; n < 2; ++n) {
;         f32x4 g1 = gate_u8(w1[m][bj][n]); f32x4 v = acc[ai][bj][m][n];
;         for (int j = 0; j < 4; ++j) v[j] *= fmaxf(g1[j], 1.f / 510.f);
;         u32x2 o = {pk2(v[0], v[1]), pk2(v[2], v[3])};
;         *(u32x2*)stg_ptr(shm, bj, wr * 64 + m * 16 + fr, wc * 8 + n * 4 + fq) = o; }
;       stg_flush(shm, tid, MX + (size_t)(brow + ai * HALF) * DM + bcol, (size_t)DM, false, ai == 0);
	v_lshl_add_u64 v[76:77], v[66:67], 0, v[70:71]
	v_lshlrev_b32_e32 v66, 4, v249
	v_and_b32_e32 v132, 0xffffff80, v132
	ds_read_b128 v[72:75], v1
	v_and_b32_e32 v66, 0xf0, v66
	v_mov_b32_e32 v67, v0
	v_ashrrev_i32_e32 v133, 31, v132
	v_lshl_add_u64 v[76:77], v[76:77], 0, v[66:67]
	s_waitcnt lgkmcnt(0)
	global_store_dwordx4 v[76:77], v[72:75], off
	s_nop 7
	v_lshlrev_b32_e32 v72, 12, v173
	v_mov_b32_e32 v73, v0
	v_ashrrev_i32_e32 v134, 4, v134
	v_lshl_add_u64 v[80:81], s[8:9], 0, v[72:73]
	v_lshlrev_b64 v[74:75], 1, v[132:133]
	v_and_b32_e32 v134, 0xffffff80, v134
	ds_read_b128 v[76:79], v146
	v_lshl_add_u64 v[80:81], v[80:81], 0, v[74:75]
	v_ashrrev_i32_e32 v135, 31, v134
	v_lshl_add_u64 v[80:81], v[80:81], 0, v[66:67]
	s_waitcnt lgkmcnt(0)
	global_store_dwordx4 v[80:81], v[76:79], off
	s_nop 7
	v_lshlrev_b32_e32 v76, 12, v174
	v_mov_b32_e32 v77, v0
	v_ashrrev_i32_e32 v136, 4, v136
	v_lshl_add_u64 v[84:85], s[8:9], 0, v[76:77]
	v_lshlrev_b64 v[78:79], 1, v[134:135]
	v_and_b32_e32 v136, 0xffffff80, v136
	ds_read_b128 v[80:83], v148
	v_lshl_add_u64 v[84:85], v[84:85], 0, v[78:79]
	v_ashrrev_i32_e32 v137, 31, v136
	v_lshl_add_u64 v[84:85], v[84:85], 0, v[66:67]
	s_waitcnt lgkmcnt(0)
	global_store_dwordx4 v[84:85], v[80:83], off
	s_nop 7
	v_lshlrev_b32_e32 v80, 12, v175
	v_mov_b32_e32 v81, v0
	v_ashrrev_i32_e32 v138, 4, v138
	v_lshl_add_u64 v[88:89], s[8:9], 0, v[80:81]
	v_lshlrev_b64 v[82:83], 1, v[136:137]
	v_and_b32_e32 v138, 0xffffff80, v138
	ds_read_b128 v[84:87], v149
	v_lshl_add_u64 v[88:89], v[88:89], 0, v[82:83]
	v_ashrrev_i32_e32 v139, 31, v138
	v_lshl_add_u64 v[88:89], v[88:89], 0, v[66:67]
	s_waitcnt lgkmcnt(0)
	global_store_dwordx4 v[88:89], v[84:87], off
	s_nop 7
	v_lshlrev_b32_e32 v84, 12, v177
	v_mov_b32_e32 v85, v0
	v_ashrrev_i32_e32 v140, 4, v140
	v_lshl_add_u64 v[92:93], s[8:9], 0, v[84:85]
	v_lshlrev_b64 v[86:87], 1, v[138:139]
	v_and_b32_e32 v140, 0xffffff80, v140
	ds_read_b128 v[88:91], v151
	v_lshl_add_u64 v[92:93], v[92:93], 0, v[86:87]
	v_ashrrev_i32_e32 v141, 31, v140
	v_lshl_add_u64 v[92:93], v[92:93], 0, v[66:67]
	s_waitcnt lgkmcnt(0)
	global_store_dwordx4 v[92:93], v[88:91], off
	s_nop 7
	v_lshlrev_b32_e32 v88, 12, v178
	v_mov_b32_e32 v89, v0
	v_ashrrev_i32_e32 v142, 4, v142
	v_lshl_add_u64 v[96:97], s[8:9], 0, v[88:89]
	v_lshlrev_b64 v[90:91], 1, v[140:141]
	v_and_b32_e32 v142, 0xffffff80, v142
	ds_read_b128 v[92:95], v152
	v_lshl_add_u64 v[96:97], v[96:97], 0, v[90:91]
	v_ashrrev_i32_e32 v143, 31, v142
	v_lshl_add_u64 v[96:97], v[96:97], 0, v[66:67]
	s_waitcnt lgkmcnt(0)
	global_store_dwordx4 v[96:97], v[92:95], off
	s_nop 7
	v_lshlrev_b32_e32 v92, 12, v179
	v_mov_b32_e32 v93, v0
	v_ashrrev_i32_e32 v144, 4, v144
	v_lshl_add_u64 v[100:101], s[8:9], 0, v[92:93]
	v_lshlrev_b64 v[94:95], 1, v[142:143]
	v_and_b32_e32 v144, 0xffffff80, v144
	ds_read_b128 v[96:99], v154
	v_lshl_add_u64 v[100:101], v[100:101], 0, v[94:95]
	v_ashrrev_i32_e32 v145, 31, v144
	v_lshl_add_u64 v[100:101], v[100:101], 0, v[66:67]
	s_waitcnt lgkmcnt(0)
	global_store_dwordx4 v[100:101], v[96:99], off
	s_nop 7
	v_lshlrev_b32_e32 v96, 12, v181
	v_mov_b32_e32 v97, v0
	v_lshl_add_u64 v[104:105], s[8:9], 0, v[96:97]
	v_lshlrev_b64 v[98:99], 1, v[144:145]
	ds_read_b128 v[100:103], v155
	v_lshl_add_u64 v[104:105], v[104:105], 0, v[98:99]
	v_lshl_add_u64 v[104:105], v[104:105], 0, v[66:67]
	s_waitcnt lgkmcnt(0)
	global_store_dwordx4 v[104:105], v[100:103], off
	s_nop 7
	v_cvt_f32_ubyte0_e32 v100, v168
	v_cvt_f32_ubyte1_e32 v101, v168
	v_mul_f32_e32 v100, 0x3b808081, v100
	v_mul_f32_e32 v101, 0x3b808081, v101
	v_cvt_f32_ubyte2_e32 v102, v168
	v_cvt_f32_ubyte3_e32 v103, v168
	v_max_f32_e32 v100, 0x3b008081, v100
	v_max_f32_e32 v101, 0x3b008081, v101
	v_pk_mul_f32 v[62:63], v[62:63], v[100:101]
	v_mul_f32_e32 v100, 0x3b808081, v102
	v_mul_f32_e32 v101, 0x3b808081, v103
	v_max_f32_e32 v100, 0x3b008081, v100
	v_max_f32_e32 v101, 0x3b008081, v101
	v_pk_mul_f32 v[64:65], v[64:65], v[100:101]
	v_cvt_pk_bf16_f32 v62, v62, v63
	v_cvt_pk_bf16_f32 v63, v64, v65
	s_barrier
	ds_write_b64 v126, v[62:63] offset:32768
	v_cvt_f32_ubyte0_e32 v62, v167
	v_cvt_f32_ubyte1_e32 v63, v167
	v_mul_f32_e32 v62, 0x3b808081, v62
	v_mul_f32_e32 v63, 0x3b808081, v63
	v_cvt_f32_ubyte2_e32 v64, v167
	v_cvt_f32_ubyte3_e32 v65, v167
	v_max_f32_e32 v62, 0x3b008081, v62
	v_max_f32_e32 v63, 0x3b008081, v63
	v_pk_mul_f32 v[58:59], v[58:59], v[62:63]
	v_mul_f32_e32 v62, 0x3b808081, v64
	v_mul_f32_e32 v63, 0x3b808081, v65
	v_max_f32_e32 v62, 0x3b008081, v62
	v_max_f32_e32 v63, 0x3b008081, v63
	v_pk_mul_f32 v[60:61], v[60:61], v[62:63]
	v_cvt_pk_bf16_f32 v58, v58, v59
	v_cvt_pk_bf16_f32 v59, v60, v61
	v_cvt_f32_ubyte0_e32 v60, v166
	v_cvt_f32_ubyte1_e32 v61, v166
	v_mul_f32_e32 v60, 0x3b808081, v60
	v_mul_f32_e32 v61, 0x3b808081, v61
	v_cvt_f32_ubyte2_e32 v62, v166
	v_cvt_f32_ubyte3_e32 v63, v166
	v_max_f32_e32 v60, 0x3b008081, v60
	v_max_f32_e32 v61, 0x3b008081, v61
	v_pk_mul_f32 v[54:55], v[54:55], v[60:61]
	v_mul_f32_e32 v60, 0x3b808081, v62
	v_mul_f32_e32 v61, 0x3b808081, v63
	v_max_f32_e32 v60, 0x3b008081, v60
	v_max_f32_e32 v61, 0x3b008081, v61
	v_pk_mul_f32 v[56:57], v[56:57], v[60:61]
	v_cvt_pk_bf16_f32 v54, v54, v55
	v_cvt_pk_bf16_f32 v55, v56, v57
	ds_write_b64 v120, v[54:55]
	v_cvt_f32_ubyte0_e32 v54, v165
	v_cvt_f32_ubyte1_e32 v55, v165
	v_mul_f32_e32 v54, 0x3b808081, v54
	v_mul_f32_e32 v55, 0x3b808081, v55
	v_cvt_f32_ubyte2_e32 v56, v165
	v_cvt_f32_ubyte3_e32 v57, v165
	v_max_f32_e32 v54, 0x3b008081, v54
	v_max_f32_e32 v55, 0x3b008081, v55
	v_pk_mul_f32 v[50:51], v[50:51], v[54:55]
	v_mul_f32_e32 v54, 0x3b808081, v56
	v_mul_f32_e32 v55, 0x3b808081, v57
	v_max_f32_e32 v54, 0x3b008081, v54
; __device__ void mix_phase(const Params& p, int layer, bf16* shm, int wv) {
;     ...
;     _Pragma("unroll") for (int ai = 0; ai < 2; ++ai) {
;       unsigned (&w1)[4][2][2] = w1a[ai];
;       _Pragma("unroll") for (int m = 0; m < 4; ++m) _Pragma("unroll") for (int bj = 0; bj < 2; ++bj) _Pragma("unroll") for (int n = 0; n < 2; ++n) {
;         f32x4 g1 = gate_u8(w1[m][bj][n]); f32x4 v = acc[ai][bj][m][n];
;         for (int j = 0; j < 4; ++j) v[j] *= fmaxf(g1[j], 1.f / 510.f);
;         u32x2 o = {pk2(v[0], v[1]), pk2(v[2], v[3])};
;         *(u32x2*)stg_ptr(shm, bj, wr * 64 + m * 16 + fr, wc * 8 + n * 4 + fq) = o; }
;       stg_flush(shm, tid, MX + (size_t)(brow + ai * HALF) * DM + bcol, (size_t)DM, false, ai == 0);
	v_max_f32_e32 v55, 0x3b008081, v55
	v_pk_mul_f32 v[52:53], v[52:53], v[54:55]
	v_cvt_pk_bf16_f32 v50, v50, v51
	v_cvt_pk_bf16_f32 v51, v52, v53
	ds_write_b64 v116, v[50:51]
	v_cvt_f32_ubyte0_e32 v50, v164
	v_cvt_f32_ubyte1_e32 v51, v164
	v_mul_f32_e32 v50, 0x3b808081, v50
	v_mul_f32_e32 v51, 0x3b808081, v51
	v_cvt_f32_ubyte2_e32 v52, v164
	v_cvt_f32_ubyte3_e32 v53, v164
	v_max_f32_e32 v50, 0x3b008081, v50
	v_max_f32_e32 v51, 0x3b008081, v51
	v_pk_mul_f32 v[46:47], v[46:47], v[50:51]
	v_mul_f32_e32 v50, 0x3b808081, v52
	v_mul_f32_e32 v51, 0x3b808081, v53
	v_max_f32_e32 v50, 0x3b008081, v50
	v_max_f32_e32 v51, 0x3b008081, v51
	v_pk_mul_f32 v[48:49], v[48:49], v[50:51]
	v_cvt_pk_bf16_f32 v46, v46, v47
	v_cvt_pk_bf16_f32 v47, v48, v49
	ds_write_b64 v126, v[46:47] offset:36864
	v_cvt_f32_ubyte0_e32 v46, v163
	v_cvt_f32_ubyte1_e32 v47, v163
	v_mul_f32_e32 v46, 0x3b808081, v46
	v_mul_f32_e32 v47, 0x3b808081, v47
	v_cvt_f32_ubyte2_e32 v48, v163
	v_cvt_f32_ubyte3_e32 v49, v163
	v_max_f32_e32 v46, 0x3b008081, v46
	v_max_f32_e32 v47, 0x3b008081, v47
	v_pk_mul_f32 v[42:43], v[42:43], v[46:47]
	v_mul_f32_e32 v46, 0x3b808081, v48
	v_mul_f32_e32 v47, 0x3b808081, v49
	v_max_f32_e32 v46, 0x3b008081, v46
	v_max_f32_e32 v47, 0x3b008081, v47
	v_pk_mul_f32 v[44:45], v[44:45], v[46:47]
	v_cvt_pk_bf16_f32 v42, v42, v43
	v_cvt_pk_bf16_f32 v43, v44, v45
	ds_write2st64_b64 v122, v[58:59], v[42:43] offset0:64 offset1:72
	v_cvt_f32_ubyte0_e32 v42, v162
	v_cvt_f32_ubyte1_e32 v43, v162
	v_mul_f32_e32 v42, 0x3b808081, v42
	v_mul_f32_e32 v43, 0x3b808081, v43
	v_cvt_f32_ubyte2_e32 v44, v162
	v_cvt_f32_ubyte3_e32 v45, v162
	v_max_f32_e32 v42, 0x3b008081, v42
	v_max_f32_e32 v43, 0x3b008081, v43
	v_pk_mul_f32 v[38:39], v[38:39], v[42:43]
	v_mul_f32_e32 v42, 0x3b808081, v44
	v_mul_f32_e32 v43, 0x3b808081, v45
	v_max_f32_e32 v42, 0x3b008081, v42
	v_max_f32_e32 v43, 0x3b008081, v43
	v_pk_mul_f32 v[40:41], v[40:41], v[42:43]
	v_cvt_pk_bf16_f32 v38, v38, v39
	v_cvt_pk_bf16_f32 v39, v40, v41
	ds_write_b64 v106, v[38:39]
	v_cvt_f32_ubyte0_e32 v38, v160
	v_cvt_f32_ubyte1_e32 v39, v160
	v_mul_f32_e32 v38, 0x3b808081, v38
	v_mul_f32_e32 v39, 0x3b808081, v39
	v_cvt_f32_ubyte2_e32 v40, v160
	v_cvt_f32_ubyte3_e32 v41, v160
	v_max_f32_e32 v38, 0x3b008081, v38
	v_max_f32_e32 v39, 0x3b008081, v39
	v_pk_mul_f32 v[34:35], v[34:35], v[38:39]
	v_mul_f32_e32 v38, 0x3b808081, v40
	v_mul_f32_e32 v39, 0x3b808081, v41
	v_max_f32_e32 v38, 0x3b008081, v38
	v_max_f32_e32 v39, 0x3b008081, v39
	v_pk_mul_f32 v[36:37], v[36:37], v[38:39]
	v_cvt_pk_bf16_f32 v34, v34, v35
	v_cvt_pk_bf16_f32 v35, v36, v37
	ds_write_b64 v107, v[34:35]
	s_waitcnt vmcnt(7)
	v_cvt_f32_ubyte0_e32 v34, v161
	v_cvt_f32_ubyte1_e32 v35, v161
	v_mul_f32_e32 v34, 0x3b808081, v34
	v_mul_f32_e32 v35, 0x3b808081, v35
	v_cvt_f32_ubyte2_e32 v36, v161
	v_cvt_f32_ubyte3_e32 v37, v161
	v_max_f32_e32 v34, 0x3b008081, v34
	v_max_f32_e32 v35, 0x3b008081, v35
	v_pk_mul_f32 v[30:31], v[30:31], v[34:35]
	v_mul_f32_e32 v34, 0x3b808081, v36
	v_mul_f32_e32 v35, 0x3b808081, v37
	v_max_f32_e32 v34, 0x3b008081, v34
	v_max_f32_e32 v35, 0x3b008081, v35
	v_pk_mul_f32 v[32:33], v[32:33], v[34:35]
	v_cvt_pk_bf16_f32 v30, v30, v31
	v_cvt_pk_bf16_f32 v31, v32, v33
	ds_write_b64 v126, v[30:31] offset:40960
	s_waitcnt vmcnt(6)
	v_cvt_f32_ubyte0_e32 v30, v159
	v_cvt_f32_ubyte1_e32 v31, v159
	v_mul_f32_e32 v30, 0x3b808081, v30
	v_mul_f32_e32 v31, 0x3b808081, v31
	v_cvt_f32_ubyte2_e32 v32, v159
	v_cvt_f32_ubyte3_e32 v33, v159
	v_max_f32_e32 v30, 0x3b008081, v30
	v_max_f32_e32 v31, 0x3b008081, v31
	v_pk_mul_f32 v[26:27], v[26:27], v[30:31]
	v_mul_f32_e32 v30, 0x3b808081, v32
	v_mul_f32_e32 v31, 0x3b808081, v33
	v_max_f32_e32 v30, 0x3b008081, v30
	v_max_f32_e32 v31, 0x3b008081, v31
	v_pk_mul_f32 v[28:29], v[28:29], v[30:31]
	v_cvt_pk_bf16_f32 v26, v26, v27
	v_cvt_pk_bf16_f32 v27, v28, v29
	s_waitcnt vmcnt(5)
	v_cvt_f32_ubyte0_e32 v28, v158
	v_cvt_f32_ubyte1_e32 v29, v158
	v_mul_f32_e32 v28, 0x3b808081, v28
	v_mul_f32_e32 v29, 0x3b808081, v29
	v_cvt_f32_ubyte2_e32 v30, v158
	v_cvt_f32_ubyte3_e32 v31, v158
	v_max_f32_e32 v28, 0x3b008081, v28
	v_max_f32_e32 v29, 0x3b008081, v29
	v_pk_mul_f32 v[22:23], v[22:23], v[28:29]
	v_mul_f32_e32 v28, 0x3b808081, v30
	v_mul_f32_e32 v29, 0x3b808081, v31
	v_max_f32_e32 v28, 0x3b008081, v28
	v_max_f32_e32 v29, 0x3b008081, v29
	v_pk_mul_f32 v[24:25], v[24:25], v[28:29]
	v_cvt_pk_bf16_f32 v22, v22, v23
	v_cvt_pk_bf16_f32 v23, v24, v25
	ds_write_b64 v108, v[22:23]
	s_waitcnt vmcnt(4)
	v_cvt_f32_ubyte0_e32 v22, v157
	v_cvt_f32_ubyte1_e32 v23, v157
	v_mul_f32_e32 v22, 0x3b808081, v22
	v_mul_f32_e32 v23, 0x3b808081, v23
	v_cvt_f32_ubyte2_e32 v24, v157
	v_cvt_f32_ubyte3_e32 v25, v157
	v_max_f32_e32 v22, 0x3b008081, v22
	v_max_f32_e32 v23, 0x3b008081, v23
	v_pk_mul_f32 v[18:19], v[18:19], v[22:23]
	v_mul_f32_e32 v22, 0x3b808081, v24
	v_mul_f32_e32 v23, 0x3b808081, v25
	v_max_f32_e32 v22, 0x3b008081, v22
	v_max_f32_e32 v23, 0x3b008081, v23
	v_pk_mul_f32 v[20:21], v[20:21], v[22:23]
	v_cvt_pk_bf16_f32 v18, v18, v19
	v_cvt_pk_bf16_f32 v19, v20, v21
	ds_write_b64 v109, v[18:19]
	s_waitcnt vmcnt(3)
; __device__ void mix_phase(const Params& p, int layer, bf16* shm, int wv) {
;     ...
;     _Pragma("unroll") for (int ai = 0; ai < 2; ++ai) {
;       unsigned (&w1)[4][2][2] = w1a[ai];
;       _Pragma("unroll") for (int m = 0; m < 4; ++m) _Pragma("unroll") for (int bj = 0; bj < 2; ++bj) _Pragma("unroll") for (int n = 0; n < 2; ++n) {
;         f32x4 g1 = gate_u8(w1[m][bj][n]); f32x4 v = acc[ai][bj][m][n];
;         for (int j = 0; j < 4; ++j) v[j] *= fmaxf(g1[j], 1.f / 510.f);
;         u32x2 o = {pk2(v[0], v[1]), pk2(v[2], v[3])};
;         *(u32x2*)stg_ptr(shm, bj, wr * 64 + m * 16 + fr, wc * 8 + n * 4 + fq) = o; }
;       stg_flush(shm, tid, MX + (size_t)(brow + ai * HALF) * DM + bcol, (size_t)DM, false, ai == 0);
;     }
;     asm volatile("s_waitcnt vmcnt(0)" ::: "memory");
	v_cvt_f32_ubyte0_e32 v18, v156
	v_cvt_f32_ubyte1_e32 v19, v156
	v_mul_f32_e32 v18, 0x3b808081, v18
	v_mul_f32_e32 v19, 0x3b808081, v19
	v_cvt_f32_ubyte2_e32 v20, v156
	v_cvt_f32_ubyte3_e32 v21, v156
	v_max_f32_e32 v18, 0x3b008081, v18
	v_max_f32_e32 v19, 0x3b008081, v19
	v_pk_mul_f32 v[14:15], v[14:15], v[18:19]
	v_mul_f32_e32 v18, 0x3b808081, v20
	v_mul_f32_e32 v19, 0x3b808081, v21
	v_max_f32_e32 v18, 0x3b008081, v18
	v_max_f32_e32 v19, 0x3b008081, v19
	v_pk_mul_f32 v[16:17], v[16:17], v[18:19]
	v_cvt_pk_bf16_f32 v14, v14, v15
	v_cvt_pk_bf16_f32 v15, v16, v17
	ds_write_b64 v126, v[14:15] offset:45056
	s_waitcnt vmcnt(2)
	v_cvt_f32_ubyte0_e32 v14, v153
	v_cvt_f32_ubyte1_e32 v15, v153
	v_mul_f32_e32 v14, 0x3b808081, v14
	v_mul_f32_e32 v15, 0x3b808081, v15
	v_cvt_f32_ubyte2_e32 v16, v153
	v_cvt_f32_ubyte3_e32 v17, v153
	v_max_f32_e32 v14, 0x3b008081, v14
	v_max_f32_e32 v15, 0x3b008081, v15
	v_pk_mul_f32 v[10:11], v[10:11], v[14:15]
	v_mul_f32_e32 v14, 0x3b808081, v16
	v_mul_f32_e32 v15, 0x3b808081, v17
	v_max_f32_e32 v14, 0x3b008081, v14
	v_max_f32_e32 v15, 0x3b008081, v15
	v_pk_mul_f32 v[12:13], v[12:13], v[14:15]
	v_cvt_pk_bf16_f32 v10, v10, v11
	v_cvt_pk_bf16_f32 v11, v12, v13
	ds_write2st64_b64 v122, v[26:27], v[10:11] offset0:80 offset1:88
	s_waitcnt vmcnt(1)
	v_cvt_f32_ubyte0_e32 v10, v150
	v_cvt_f32_ubyte1_e32 v11, v150
	v_mul_f32_e32 v10, 0x3b808081, v10
	v_mul_f32_e32 v11, 0x3b808081, v11
	v_cvt_f32_ubyte2_e32 v12, v150
	v_cvt_f32_ubyte3_e32 v13, v150
	v_max_f32_e32 v10, 0x3b008081, v10
	v_max_f32_e32 v11, 0x3b008081, v11
	v_pk_mul_f32 v[6:7], v[6:7], v[10:11]
	v_mul_f32_e32 v10, 0x3b808081, v12
	v_mul_f32_e32 v11, 0x3b808081, v13
	v_max_f32_e32 v10, 0x3b008081, v10
	v_max_f32_e32 v11, 0x3b008081, v11
	v_pk_mul_f32 v[8:9], v[8:9], v[10:11]
	v_cvt_pk_bf16_f32 v6, v6, v7
	v_cvt_pk_bf16_f32 v7, v8, v9
	ds_write_b64 v110, v[6:7]
	s_waitcnt vmcnt(0)
	v_cvt_f32_ubyte0_e32 v6, v147
	v_cvt_f32_ubyte1_e32 v7, v147
	v_mul_f32_e32 v6, 0x3b808081, v6
	v_mul_f32_e32 v7, 0x3b808081, v7
	s_bitset1_b32 s6, 7
	v_cvt_f32_ubyte2_e32 v8, v147
	v_cvt_f32_ubyte3_e32 v9, v147
	v_max_f32_e32 v6, 0x3b008081, v6
	v_max_f32_e32 v7, 0x3b008081, v7
	s_ashr_i32 s7, s6, 31
	v_pk_mul_f32 v[2:3], v[2:3], v[6:7]
	v_mul_f32_e32 v6, 0x3b808081, v8
	v_mul_f32_e32 v7, 0x3b808081, v9
	s_lshl_b64 s[6:7], s[6:7], 12
	v_max_f32_e32 v6, 0x3b008081, v6
	v_max_f32_e32 v7, 0x3b008081, v7
	s_add_u32 s6, s5, s6
	v_pk_mul_f32 v[4:5], v[4:5], v[6:7]
	s_addc_u32 s7, s1, s7
	v_cvt_pk_bf16_f32 v2, v2, v3
	v_cvt_pk_bf16_f32 v3, v4, v5
	v_lshl_add_u64 v[6:7], s[6:7], 0, v[68:69]
	ds_write_b64 v111, v[2:3]
	v_lshl_add_u64 v[6:7], v[6:7], 0, v[70:71]
	s_waitcnt lgkmcnt(0)
	s_barrier
	v_lshl_add_u64 v[6:7], v[6:7], 0, v[66:67]
	ds_read_b128 v[2:5], v1
	s_waitcnt lgkmcnt(0)
	global_store_dwordx4 v[6:7], v[2:5], off
	s_nop 7
	v_lshl_add_u64 v[6:7], s[6:7], 0, v[72:73]
	v_lshl_add_u64 v[6:7], v[6:7], 0, v[74:75]
	v_lshl_add_u64 v[6:7], v[6:7], 0, v[66:67]
	ds_read_b128 v[2:5], v146
	s_waitcnt lgkmcnt(0)
	global_store_dwordx4 v[6:7], v[2:5], off
	s_nop 7
	v_lshl_add_u64 v[6:7], s[6:7], 0, v[76:77]
	v_lshl_add_u64 v[6:7], v[6:7], 0, v[78:79]
	v_lshl_add_u64 v[6:7], v[6:7], 0, v[66:67]
	ds_read_b128 v[2:5], v148
	s_waitcnt lgkmcnt(0)
	global_store_dwordx4 v[6:7], v[2:5], off
	s_nop 7
	v_lshl_add_u64 v[6:7], s[6:7], 0, v[80:81]
	v_lshl_add_u64 v[6:7], v[6:7], 0, v[82:83]
	v_lshl_add_u64 v[6:7], v[6:7], 0, v[66:67]
	ds_read_b128 v[2:5], v149
	s_waitcnt lgkmcnt(0)
	global_store_dwordx4 v[6:7], v[2:5], off
	s_nop 7
	v_lshl_add_u64 v[6:7], s[6:7], 0, v[84:85]
	v_lshl_add_u64 v[6:7], v[6:7], 0, v[86:87]
	v_lshl_add_u64 v[6:7], v[6:7], 0, v[66:67]
	ds_read_b128 v[2:5], v151
	s_waitcnt lgkmcnt(0)
	global_store_dwordx4 v[6:7], v[2:5], off
	s_nop 7
	v_lshl_add_u64 v[6:7], s[6:7], 0, v[88:89]
	v_lshl_add_u64 v[6:7], v[6:7], 0, v[90:91]
	v_lshl_add_u64 v[6:7], v[6:7], 0, v[66:67]
	ds_read_b128 v[2:5], v152
	s_waitcnt lgkmcnt(0)
	global_store_dwordx4 v[6:7], v[2:5], off
	s_nop 7
	v_lshl_add_u64 v[6:7], s[6:7], 0, v[92:93]
	v_lshl_add_u64 v[6:7], v[6:7], 0, v[94:95]
	v_lshl_add_u64 v[6:7], v[6:7], 0, v[66:67]
	ds_read_b128 v[2:5], v154
	s_waitcnt lgkmcnt(0)
	global_store_dwordx4 v[6:7], v[2:5], off
	s_nop 7
	v_lshl_add_u64 v[6:7], s[6:7], 0, v[96:97]
	v_lshl_add_u64 v[6:7], v[6:7], 0, v[98:99]
	ds_read_b128 v[2:5], v155
	v_lshl_add_u64 v[6:7], v[6:7], 0, v[66:67]
	s_waitcnt lgkmcnt(0)
	global_store_dwordx4 v[6:7], v[2:5], off
	s_nop 7
	s_waitcnt vmcnt(0)
	s_add_i32 s19, s19, 1
	s_mov_b64 s[6:7], 0

; __device__ __forceinline__ float bflo(unsigned u) { return __uint_as_float(u << 16); }
; __device__ __forceinline__ float bfhi(unsigned u) { return __uint_as_float(u & 0xffff0000u); }
; #define shx(v, m) shxt<m>(v)
;     #define ISSUE_NEXT() do { if (more) { gemm_issue_part1(A, lda, Bt, K, pm * BM, pn * BM, shm, tid); fresh = false; \
;                                           asm volatile("s_waitcnt vmcnt(8)" ::: "memory"); }     \
;                               else asm volatile("s_waitcnt vmcnt(0)" ::: "memory"); } while (0)
; template <int EPI>
; __device__ void gemm_phase(const bf16* A, int lda, const bf16* Bt, int K, int N, const Params& p, bool last, bf16* dstb, bf16* shm, unsigned long long* SSQ, int wv, const float* gbias = nullptr) {
;     ...
;       _Pragma("unroll") for (int ai = 0; ai < 2; ++ai) {
;         u32x2 xo[4][2][2];
;         _Pragma("unroll") for (int m = 0; m < 4; ++m) _Pragma("unroll") for (int bj = 0; bj < 2; ++bj) _Pragma("unroll") for (int n = 0; n < 2; ++n)
;           xo[m][bj][n] = *(const u32x2*)(Xb + (size_t)(brow + ai * HALF + wr * 64 + m * 16 + fr) * DM + bcol + wc * 32 + fq * 4 + bj * HALF + n * 16);
;         if (ai == 0) { ISSUE_NEXT(); asm volatile("s_waitcnt vmcnt(0)" ::: "memory"); } else asm volatile("s_waitcnt vmcnt(0)" ::: "memory");
;         _Pragma("unroll") for (int m = 0; m < 4; ++m) {
;           const int rl = ai * HALF + wr * 64 + m * 16 + fr;
;           const size_t ro = (size_t)(brow + rl) * DM + bcol + wc * 32 + fq * 4;
;           float ssq = 0.f;
;           _Pragma("unroll") for (int bj = 0; bj < 2; ++bj) _Pragma("unroll") for (int n = 0; n < 2; ++n) {
;             const u32x2 xv = xo[m][bj][n];
;             f32x4 v = acc[ai][bj][m][n];
;             v[0] += bflo(xv[0]); v[1] += bfhi(xv[0]); v[2] += bflo(xv[1]); v[3] += bfhi(xv[1]);
;             if (last) *(f32x4*)(p.out + ro + bj * HALF + n * 16) = v;
;             else {
;               u32x2 o = {pk2(v[0], v[1]), pk2(v[2], v[3])};
;               *(u32x2*)stg_ptr(shm, bj, wr * 64 + m * 16 + fr, wc * 8 + n * 4 + fq) = o;
;               float r0 = bflo(o[0]), r1 = bfhi(o[0]), r2 = bflo(o[1]), r3 = bfhi(o[1]);
;               ssq += (r0 * r0 + r1 * r1) + (r2 * r2 + r3 * r3); }
;           }
;           if (!last) { ssq += shx(ssq, 16); ssq += shx(ssq, 32); if (fq == 0) atomicAdd(SSQ + brow + rl, (unsigned long long)(ssq * SSQ_SCALE + 0.5f)); }
.LBB0_498:
	v_cmp_eq_u32_e32 vcc, 0, v172
	s_waitcnt vmcnt(15)
	v_lshlrev_b32_e32 v172, 16, v170
	v_and_b32_e32 v173, 0xffff0000, v170
	v_pk_add_f32 v[126:127], v[126:127], v[172:173]
	v_lshlrev_b32_e32 v170, 16, v171
	v_and_b32_e32 v171, 0xffff0000, v171
	v_pk_add_f32 v[128:129], v[128:129], v[170:171]
	v_cvt_pk_bf16_f32 v170, v126, v127
	v_or_b32_e32 v130, v130, v131
	v_lshlrev_b32_e32 v131, 4, v131
	v_cvt_pk_bf16_f32 v171, v128, v129
	v_and_b32_e32 v129, 0xffff0000, v170
	v_or_b32_e32 v167, v166, v168
	v_bitop3_b32 v127, v166, v131, v168 bitop3:0x36
	v_lshlrev_b32_e32 v128, 16, v170
	v_and_b32_e32 v168, 0xffff0000, v171
	v_mul_f32_e32 v129, v129, v129
	v_lshlrev_b32_e32 v166, 16, v171
	v_fmac_f32_e32 v129, v128, v128
	v_mul_f32_e32 v128, v168, v168
	v_fmac_f32_e32 v128, v166, v166
	v_add_f32_e32 v166, v129, v128
	s_waitcnt vmcnt(14)
	v_lshlrev_b32_e32 v128, 16, v164
	v_and_b32_e32 v129, 0xffff0000, v164
	v_pk_add_f32 v[122:123], v[122:123], v[128:129]
	v_lshlrev_b32_e32 v128, 16, v165
	v_and_b32_e32 v129, 0xffff0000, v165
	v_lshl_add_u32 v133, v130, 8, 0
	v_pk_add_f32 v[124:125], v[124:125], v[128:129]
	v_cvt_pk_bf16_f32 v128, v122, v123
	v_bitop3_b32 v123, v167, v131, 32 bitop3:0x36
	v_add_u32_e32 v126, v133, v127
	v_cvt_pk_bf16_f32 v129, v124, v125
	v_add_u32_e32 v122, v133, v123
	v_and_b32_e32 v125, 0xffff0000, v128
	s_waitcnt vmcnt(0)
	ds_write_b64 v126, v[170:171] offset:32768
	ds_write_b64 v122, v[128:129] offset:32768
	v_lshlrev_b32_e32 v124, 16, v128
	v_lshlrev_b32_e32 v128, 16, v129
	v_and_b32_e32 v129, 0xffff0000, v129
	v_mul_f32_e32 v125, v125, v125
	v_fmac_f32_e32 v125, v124, v124
	v_mul_f32_e32 v124, v129, v129
	v_fmac_f32_e32 v124, v128, v128
	v_add_f32_e32 v124, v125, v124
	v_add_f32_e32 v128, v166, v124
	v_lshlrev_b32_e32 v124, 16, v162
	v_and_b32_e32 v125, 0xffff0000, v162
	v_pk_add_f32 v[118:119], v[118:119], v[124:125]
	v_lshlrev_b32_e32 v124, 16, v163
	v_and_b32_e32 v125, 0xffff0000, v163
	v_add_u32_e32 v129, 0x18000, v133
	v_pk_add_f32 v[120:121], v[120:121], v[124:125]
	v_cvt_pk_bf16_f32 v124, v118, v119
	v_cvt_pk_bf16_f32 v125, v120, v121
	v_add_u32_e32 v118, v129, v127
	v_and_b32_e32 v120, 0xffff0000, v124
	ds_write_b64 v118, v[124:125]
	v_lshlrev_b32_e32 v119, 16, v124
	v_and_b32_e32 v124, 0xffff0000, v125
	v_mul_f32_e32 v120, v120, v120
	v_lshlrev_b32_e32 v121, 16, v125
	v_fmac_f32_e32 v120, v119, v119
	v_mul_f32_e32 v119, v124, v124
	v_fmac_f32_e32 v119, v121, v121
	v_add_f32_e32 v119, v120, v119
	v_lshlrev_b32_e32 v120, 16, v160
	v_and_b32_e32 v121, 0xffff0000, v160
	v_pk_add_f32 v[114:115], v[114:115], v[120:121]
	v_lshlrev_b32_e32 v120, 16, v161
	v_and_b32_e32 v121, 0xffff0000, v161
	v_pk_add_f32 v[116:117], v[116:117], v[120:121]
	v_cvt_pk_bf16_f32 v120, v114, v115
	v_cvt_pk_bf16_f32 v121, v116, v117
	v_add_u32_e32 v114, v129, v123
	v_and_b32_e32 v116, 0xffff0000, v120
	ds_write_b64 v114, v[120:121]
	v_lshlrev_b32_e32 v115, 16, v120
	v_and_b32_e32 v120, 0xffff0000, v121
	v_mul_f32_e32 v116, v116, v116
	v_lshlrev_b32_e32 v117, 16, v121
	v_fmac_f32_e32 v116, v115, v115
	v_mul_f32_e32 v115, v120, v120
	v_fmac_f32_e32 v115, v117, v117
	v_add_f32_e32 v119, v128, v119
	v_add_f32_e32 v115, v116, v115
	v_add_f32_e32 v115, v119, v115
	v_mov_b32_e32 v116, v115
	v_mov_b32_e32 v117, v115
	s_nop 1
	v_permlane16_swap_b32_e32 v116, v117
	v_xor_b32_e32 v116, v117, v116
	v_xor_b32_e32 v116, v116, v115
	s_lshl_b64 s[4:5], s[8:9], 3
	v_add_f32_e32 v115, v115, v116
	s_add_u32 s16, s48, s4
	v_mov_b32_e32 v116, v115
	v_mov_b32_e32 v117, v115
	s_addc_u32 s17, s49, s5
	s_nop 0
	v_permlane32_swap_b32_e32 v116, v117
	v_ashrrev_i32_e32 v131, 31, v130
	s_and_saveexec_b64 s[4:5], vcc
	s_cbranch_execz .LBB0_500
	v_xor_b32_e32 v116, v117, v116
	v_xor_b32_e32 v116, v116, v115
	v_add_f32_e32 v115, v115, v116
	v_fma_f32 v115, v115, s62, 0.5
	v_trunc_f32_e32 v115, v115
	v_mul_f32_e32 v116, 0x2f800000, v115
	v_floor_f32_e32 v117, v116
	v_fmac_f32_e32 v115, 0xcf800000, v117
	v_cvt_u32_f32_e32 v116, v115
	v_cvt_u32_f32_e32 v117, v117
	v_lshl_add_u64 v[120:121], v[130:131], 3, s[16:17]
	global_atomic_add_x2 v[120:121], v[116:117], off

; #define LDS_BARRIER() do { asm volatile("s_waitcnt lgkmcnt(0)" ::: "memory"); __builtin_amdgcn_s_barrier(); asm volatile("" ::: "memory"); } while (0)
; __device__ __forceinline__ void st16_asm(void* ptr, u32x4 v) { asm volatile("global_store_dwordx4 %0, %1, off\n\ts_nop 7" :: "v"(ptr), "v"(v) : "memory"); }
; __device__ __forceinline__ void stg_flush(bf16* shm, int tid, bf16* dst, size_t pitch, bool first, bool tail_barrier = true) {
;   LDS_BARRIER();
;   if (first) asm volatile("s_waitcnt vmcnt(0)" ::: "memory");
;   _Pragma("unroll") for (int i = 0; i < 8; ++i) {
;     const int idx = tid + 512 * i, bjr = idx >> 11, row = (idx >> 4) & 127, c16 = idx & 15;
;     const u32x4 d = *(const u32x4*)stg_ptr(shm, bjr, row, 2 * c16);
;     st16_asm(dst + (size_t)row * pitch + bjr * HALF + c16 * 8, d); }
;   if (tail_barrier) LDS_BARRIER();
; }
; template <int EPI>
; __device__ void gemm_phase(const bf16* A, int lda, const bf16* Bt, int K, int N, const Params& p, bool last, bf16* dstb, bf16* shm, unsigned long long* SSQ, int wv, const float* gbias = nullptr) {
;     ...
;         if (!last) stg_flush(shm, tid, Xb + (size_t)(brow + ai * HALF) * DM + bcol, (size_t)DM, false, ai == 0);
.LBB0_506:
	s_or_b64 exec, exec, s[4:5]
	v_lshrrev_b32_e32 v66, 4, v1
	v_lshlrev_b32_e32 v67, 3, v1
	v_and_b32_e32 v115, 0x7f, v66
	v_cmp_gt_u32_e64 s[4:5], s85, v1
	v_and_b32_e32 v90, 0x78, v67
	v_lshlrev_b32_e32 v68, 8, v115
	v_cndmask_b32_e64 v67, v244, v245, s[4:5]
	v_add3_u32 v82, 0, v67, v68
	v_add_u32_e32 v68, 0x200, v1
	v_bfe_u32 v116, v68, 4, 7
	v_cmp_gt_u32_e64 s[4:5], s85, v68
	v_lshlrev_b32_e32 v71, 8, v116
	v_xor_b32_e32 v66, v66, v1
	v_cndmask_b32_e64 v70, v244, v245, s[4:5]
	v_add3_u32 v91, 0, v70, v71
	v_add_u32_e32 v70, 0x400, v1
	v_bfe_u32 v117, v70, 4, 7
	v_cmp_gt_u32_e64 s[4:5], s85, v70
	v_lshlrev_b32_e32 v73, 8, v117
	v_lshlrev_b32_e32 v66, 4, v66
	v_cndmask_b32_e64 v72, v244, v245, s[4:5]
	v_add3_u32 v93, 0, v72, v73
	v_add_u32_e32 v72, 0x600, v1
	v_bfe_u32 v119, v72, 4, 7
	v_cmp_gt_u32_e64 s[4:5], s85, v72
	v_lshlrev_b32_e32 v75, 8, v119
	v_lshrrev_b32_e32 v69, 4, v68
	v_cndmask_b32_e64 v74, v244, v245, s[4:5]
	v_add3_u32 v95, 0, v74, v75
	v_add_u32_e32 v74, 0x800, v1
	v_bfe_u32 v120, v74, 4, 7
	v_cmp_lt_u32_e64 s[4:5], s65, v1
	v_lshlrev_b32_e32 v77, 8, v120
	v_lshrrev_b32_e32 v71, 4, v70
	v_cndmask_b32_e64 v76, v244, v245, s[4:5]
	v_add3_u32 v97, 0, v76, v77
	v_add_u32_e32 v76, 0xa00, v1
	v_bfe_u32 v121, v76, 4, 7
	v_cmp_gt_u32_e64 s[4:5], s85, v76
	v_lshlrev_b32_e32 v79, 8, v121
	v_lshrrev_b32_e32 v73, 4, v72
	v_cndmask_b32_e64 v78, v244, v245, s[4:5]
	v_add3_u32 v99, 0, v78, v79
	v_add_u32_e32 v78, 0xc00, v1
	v_bfe_u32 v123, v78, 4, 7
	v_cmp_gt_u32_e64 s[4:5], s85, v78
	v_lshlrev_b32_e32 v81, 8, v123
	v_lshrrev_b32_e32 v75, 4, v74
	v_cndmask_b32_e64 v80, v244, v245, s[4:5]
	v_add3_u32 v101, 0, v80, v81
	v_add_u32_e32 v80, 0xe00, v1
	v_lshrrev_b32_e32 v77, 4, v76
	v_lshrrev_b32_e32 v79, 4, v78
	v_lshrrev_b32_e32 v81, 4, v80
	v_and_b32_e32 v83, 0xf0, v66
	v_ashrrev_i32_e32 v66, 4, v1
	v_xor_b32_e32 v69, v69, v1
	v_xor_b32_e32 v71, v71, v1
	v_xor_b32_e32 v73, v73, v1
	v_xor_b32_e32 v75, v75, v1
	v_xor_b32_e32 v77, v77, v1
	v_xor_b32_e32 v79, v79, v1
	v_xor_b32_e32 v1, v81, v1
	v_cmp_gt_u32_e64 s[4:5], s85, v80
	v_lshlrev_b32_e32 v1, 4, v1
	v_and_b32_e32 v104, 0xf0, v1
	v_cndmask_b32_e64 v84, v244, v245, s[4:5]
	v_ashrrev_i32_e32 v1, 4, v80
	s_add_u32 s4, s14, s10
	v_and_b32_e32 v66, 0xffffff80, v66
	v_bfe_u32 v124, v80, 4, 7
	v_and_b32_e32 v80, 0xffffff80, v1
	s_addc_u32 s5, s15, s11
	v_add_u32_e32 v1, v82, v83
	v_lshlrev_b32_e32 v82, 12, v115
	v_mov_b32_e32 v83, v0
	v_ashrrev_i32_e32 v67, 31, v66
	v_lshl_add_u64 v[82:83], s[4:5], 0, v[82:83]
	v_lshl_add_u64 v[88:89], v[66:67], 1, v[82:83]
	v_lshlrev_b32_e32 v82, 1, v90
	v_mov_b32_e32 v83, v0
	v_ashrrev_i32_e32 v68, 4, v68
	v_lshlrev_b32_e32 v85, 8, v124
	s_waitcnt lgkmcnt(0)
	s_barrier
	v_lshl_add_u64 v[88:89], v[88:89], 0, v[82:83]
	v_lshlrev_b32_e32 v69, 4, v69
	v_and_b32_e32 v68, 0xffffff80, v68
	v_add3_u32 v103, 0, v84, v85
	ds_read_b128 v[84:87], v1
	s_waitcnt lgkmcnt(0)
	global_store_dwordx4 v[88:89], v[84:87], off
	s_nop 7
	v_lshlrev_b32_e32 v88, 12, v116
	v_mov_b32_e32 v89, v0
	v_and_b32_e32 v92, 0xf0, v69
	v_ashrrev_i32_e32 v69, 31, v68
	v_lshl_add_u64 v[88:89], s[4:5], 0, v[88:89]
	v_lshl_add_u64 v[88:89], v[68:69], 1, v[88:89]
	v_ashrrev_i32_e32 v70, 4, v70
	v_add_u32_e32 v125, v91, v92
	v_lshl_add_u64 v[88:89], v[88:89], 0, v[82:83]
	v_lshlrev_b32_e32 v71, 4, v71
	v_and_b32_e32 v70, 0xffffff80, v70
	ds_read_b128 v[84:87], v125
	s_waitcnt lgkmcnt(0)
	global_store_dwordx4 v[88:89], v[84:87], off
	s_nop 7
	v_lshlrev_b32_e32 v88, 12, v117
	v_mov_b32_e32 v89, v0
	v_and_b32_e32 v94, 0xf0, v71
	v_ashrrev_i32_e32 v71, 31, v70
	v_lshl_add_u64 v[88:89], s[4:5], 0, v[88:89]
	v_lshl_add_u64 v[88:89], v[70:71], 1, v[88:89]
	v_ashrrev_i32_e32 v72, 4, v72
	v_add_u32_e32 v127, v93, v94
	v_lshl_add_u64 v[88:89], v[88:89], 0, v[82:83]
	v_lshlrev_b32_e32 v73, 4, v73
	v_and_b32_e32 v72, 0xffffff80, v72
	ds_read_b128 v[84:87], v127
	s_waitcnt lgkmcnt(0)
	global_store_dwordx4 v[88:89], v[84:87], off
	s_nop 7
	v_lshlrev_b32_e32 v88, 12, v119
	v_mov_b32_e32 v89, v0
	v_and_b32_e32 v96, 0xf0, v73
	v_ashrrev_i32_e32 v73, 31, v72
	v_lshl_add_u64 v[88:89], s[4:5], 0, v[88:89]
	v_lshl_add_u64 v[88:89], v[72:73], 1, v[88:89]
	v_ashrrev_i32_e32 v74, 4, v74
	v_add_u32_e32 v128, v95, v96
	v_lshl_add_u64 v[88:89], v[88:89], 0, v[82:83]
	v_lshlrev_b32_e32 v75, 4, v75
	v_and_b32_e32 v74, 0xffffff80, v74
	ds_read_b128 v[84:87], v128
	s_waitcnt lgkmcnt(0)
	global_store_dwordx4 v[88:89], v[84:87], off
	s_nop 7
	v_lshlrev_b32_e32 v88, 12, v120
	v_mov_b32_e32 v89, v0
	v_and_b32_e32 v98, 0xf0, v75
	v_ashrrev_i32_e32 v75, 31, v74
	v_lshl_add_u64 v[88:89], s[4:5], 0, v[88:89]
	v_lshl_add_u64 v[88:89], v[74:75], 1, v[88:89]
	v_ashrrev_i32_e32 v76, 4, v76
	v_add_u32_e32 v129, v97, v98
	v_lshl_add_u64 v[88:89], v[88:89], 0, v[82:83]
	v_lshlrev_b32_e32 v77, 4, v77
	v_and_b32_e32 v76, 0xffffff80, v76
	ds_read_b128 v[84:87], v129
	s_waitcnt lgkmcnt(0)
	global_store_dwordx4 v[88:89], v[84:87], off
	s_nop 7
	v_lshlrev_b32_e32 v88, 12, v121
	v_mov_b32_e32 v89, v0
	v_and_b32_e32 v100, 0xf0, v77
	v_ashrrev_i32_e32 v77, 31, v76
	v_lshl_add_u64 v[88:89], s[4:5], 0, v[88:89]
	v_lshl_add_u64 v[88:89], v[76:77], 1, v[88:89]
	v_ashrrev_i32_e32 v78, 4, v78
	v_add_u32_e32 v133, v99, v100
	v_lshl_add_u64 v[88:89], v[88:89], 0, v[82:83]
	v_lshlrev_b32_e32 v79, 4, v79
	v_and_b32_e32 v78, 0xffffff80, v78
	ds_read_b128 v[84:87], v133
	s_waitcnt lgkmcnt(0)
	global_store_dwordx4 v[88:89], v[84:87], off
	s_nop 7
	v_lshlrev_b32_e32 v88, 12, v123
	v_mov_b32_e32 v89, v0
	v_and_b32_e32 v102, 0xf0, v79
	v_ashrrev_i32_e32 v79, 31, v78
	v_lshl_add_u64 v[88:89], s[4:5], 0, v[88:89]
	v_lshl_add_u64 v[88:89], v[78:79], 1, v[88:89]
	v_add_u32_e32 v136, v101, v102
	v_lshl_add_u64 v[88:89], v[88:89], 0, v[82:83]
	ds_read_b128 v[84:87], v136
	s_waitcnt lgkmcnt(0)
	global_store_dwordx4 v[88:89], v[84:87], off
	s_nop 7
	v_lshlrev_b32_e32 v88, 12, v124
	v_mov_b32_e32 v89, v0
	v_ashrrev_i32_e32 v81, 31, v80
	v_add_u32_e32 v137, v103, v104
	v_lshl_add_u64 v[88:89], s[4:5], 0, v[88:89]
	ds_read_b128 v[84:87], v137
	v_lshl_add_u64 v[88:89], v[80:81], 1, v[88:89]
	v_lshl_add_u64 v[88:89], v[88:89], 0, v[82:83]
	s_waitcnt lgkmcnt(0)
	global_store_dwordx4 v[88:89], v[84:87], off
	s_nop 7
	v_add_u32_e32 v84, 0x80, v132
	v_ashrrev_i32_e32 v85, 31, v84
	v_lshlrev_b64 v[84:85], 12, v[84:85]
	s_barrier
; __device__ __forceinline__ float bflo(unsigned u) { return __uint_as_float(u << 16); }
; __device__ __forceinline__ float bfhi(unsigned u) { return __uint_as_float(u & 0xffff0000u); }
; #define shx(v, m) shxt<m>(v)
;     #define ISSUE_NEXT() do { if (more) { gemm_issue_part1(A, lda, Bt, K, pm * BM, pn * BM, shm, tid); fresh = false; \
;                                           asm volatile("s_waitcnt vmcnt(8)" ::: "memory"); }     \
;                               else asm volatile("s_waitcnt vmcnt(0)" ::: "memory"); } while (0)
; template <int EPI>
; __device__ void gemm_phase(const bf16* A, int lda, const bf16* Bt, int K, int N, const Params& p, bool last, bf16* dstb, bf16* shm, unsigned long long* SSQ, int wv, const float* gbias = nullptr) {
;     ...
;       _Pragma("unroll") for (int ai = 0; ai < 2; ++ai) {
;         u32x2 xo[4][2][2];
;         _Pragma("unroll") for (int m = 0; m < 4; ++m) _Pragma("unroll") for (int bj = 0; bj < 2; ++bj) _Pragma("unroll") for (int n = 0; n < 2; ++n)
;           xo[m][bj][n] = *(const u32x2*)(Xb + (size_t)(brow + ai * HALF + wr * 64 + m * 16 + fr) * DM + bcol + wc * 32 + fq * 4 + bj * HALF + n * 16);
;         if (ai == 0) { ISSUE_NEXT(); asm volatile("s_waitcnt vmcnt(0)" ::: "memory"); } else asm volatile("s_waitcnt vmcnt(0)" ::: "memory");
;         _Pragma("unroll") for (int m = 0; m < 4; ++m) {
;           const int rl = ai * HALF + wr * 64 + m * 16 + fr;
;           const size_t ro = (size_t)(brow + rl) * DM + bcol + wc * 32 + fq * 4;
;           float ssq = 0.f;
;           _Pragma("unroll") for (int bj = 0; bj < 2; ++bj) _Pragma("unroll") for (int n = 0; n < 2; ++n) {
;             const u32x2 xv = xo[m][bj][n];
;             f32x4 v = acc[ai][bj][m][n];
;             v[0] += bflo(xv[0]); v[1] += bfhi(xv[0]); v[2] += bflo(xv[1]); v[3] += bfhi(xv[1]);
;             if (last) *(f32x4*)(p.out + ro + bj * HALF + n * 16) = v;
;             else {
;               u32x2 o = {pk2(v[0], v[1]), pk2(v[2], v[3])};
;               *(u32x2*)stg_ptr(shm, bj, wr * 64 + m * 16 + fr, wc * 8 + n * 4 + fq) = o;
;               float r0 = bflo(o[0]), r1 = bfhi(o[0]), r2 = bflo(o[1]), r3 = bfhi(o[1]);
;               ssq += (r0 * r0 + r1 * r1) + (r2 * r2 + r3 * r3); }
;           }
;           if (!last) { ssq += shx(ssq, 16); ssq += shx(ssq, 32); if (fq == 0) atomicAdd(SSQ + brow + rl, (unsigned long long)(ssq * SSQ_SCALE + 0.5f)); }
	v_lshl_add_u64 v[84:85], v[134:135], 0, v[84:85]
	global_load_dwordx2 v[138:139], v[84:85], off
	global_load_dwordx2 v[140:141], v[84:85], off offset:32
	global_load_dwordx2 v[142:143], v[84:85], off offset:256
	global_load_dwordx2 v[144:145], v[84:85], off offset:288
	v_add_u32_e32 v84, 0x90, v132
	v_ashrrev_i32_e32 v85, 31, v84
	v_lshlrev_b64 v[84:85], 12, v[84:85]
	v_lshl_add_u64 v[84:85], v[134:135], 0, v[84:85]
	global_load_dwordx2 v[106:107], v[84:85], off
	global_load_dwordx2 v[104:105], v[84:85], off offset:32
	global_load_dwordx2 v[102:103], v[84:85], off offset:256
	global_load_dwordx2 v[100:101], v[84:85], off offset:288
	v_add_u32_e32 v84, 0xa0, v132
	v_ashrrev_i32_e32 v85, 31, v84
	v_lshlrev_b64 v[84:85], 12, v[84:85]
	v_lshl_add_u64 v[84:85], v[134:135], 0, v[84:85]
	global_load_dwordx2 v[98:99], v[84:85], off
	global_load_dwordx2 v[96:97], v[84:85], off offset:32
	global_load_dwordx2 v[94:95], v[84:85], off offset:256
	global_load_dwordx2 v[92:93], v[84:85], off offset:288
	v_add_u32_e32 v84, 0xb0, v132
	v_ashrrev_i32_e32 v85, 31, v84
	v_lshlrev_b64 v[84:85], 12, v[84:85]
	v_lshl_add_u64 v[84:85], v[134:135], 0, v[84:85]
	global_load_dwordx2 v[90:91], v[84:85], off
	global_load_dwordx2 v[88:89], v[84:85], off offset:32
	global_load_dwordx2 v[86:87], v[84:85], off offset:256
	s_nop 0
	global_load_dwordx2 v[84:85], v[84:85], off offset:288
	s_waitcnt vmcnt(0)
	v_lshlrev_b32_e32 v134, 16, v138
	v_and_b32_e32 v135, 0xffff0000, v138
	v_pk_add_f32 v[62:63], v[62:63], v[134:135]
	v_lshlrev_b32_e32 v134, 16, v139
	v_and_b32_e32 v135, 0xffff0000, v139
	v_pk_add_f32 v[64:65], v[64:65], v[134:135]
	v_cvt_pk_bf16_f32 v62, v62, v63
	v_cvt_pk_bf16_f32 v63, v64, v65
	ds_write_b64 v126, v[62:63] offset:32768
	v_lshlrev_b32_e32 v64, 16, v62
	v_and_b32_e32 v62, 0xffff0000, v62
	v_lshlrev_b32_e32 v65, 16, v63
	v_and_b32_e32 v63, 0xffff0000, v63
	v_mul_f32_e32 v62, v62, v62
	v_mul_f32_e32 v63, v63, v63
	v_fmac_f32_e32 v62, v64, v64
	v_fmac_f32_e32 v63, v65, v65
	v_add_f32_e32 v64, v62, v63
	v_lshlrev_b32_e32 v62, 16, v140
	v_and_b32_e32 v63, 0xffff0000, v140
	v_pk_add_f32 v[58:59], v[58:59], v[62:63]
	v_lshlrev_b32_e32 v62, 16, v141
	v_and_b32_e32 v63, 0xffff0000, v141
	v_pk_add_f32 v[60:61], v[60:61], v[62:63]
	v_cvt_pk_bf16_f32 v58, v58, v59
	v_cvt_pk_bf16_f32 v59, v60, v61
	ds_write_b64 v122, v[58:59] offset:32768
	v_lshlrev_b32_e32 v60, 16, v58
	v_and_b32_e32 v58, 0xffff0000, v58
	v_lshlrev_b32_e32 v61, 16, v59
	v_and_b32_e32 v59, 0xffff0000, v59
	v_mul_f32_e32 v58, v58, v58
	v_mul_f32_e32 v59, v59, v59
	v_fmac_f32_e32 v58, v60, v60
	v_fmac_f32_e32 v59, v61, v61
	v_add_f32_e32 v58, v58, v59
	v_add_f32_e32 v60, v64, v58
	v_lshlrev_b32_e32 v58, 16, v142
	v_and_b32_e32 v59, 0xffff0000, v142
	v_pk_add_f32 v[54:55], v[54:55], v[58:59]
	v_lshlrev_b32_e32 v58, 16, v143
	v_and_b32_e32 v59, 0xffff0000, v143
	v_pk_add_f32 v[56:57], v[56:57], v[58:59]
	v_cvt_pk_bf16_f32 v54, v54, v55
	v_cvt_pk_bf16_f32 v55, v56, v57
	ds_write_b64 v118, v[54:55]
	v_lshlrev_b32_e32 v56, 16, v54
	v_and_b32_e32 v54, 0xffff0000, v54
	v_lshlrev_b32_e32 v57, 16, v55
	v_and_b32_e32 v55, 0xffff0000, v55
	v_mul_f32_e32 v54, v54, v54
	v_mul_f32_e32 v55, v55, v55
	v_fmac_f32_e32 v54, v56, v56
	v_fmac_f32_e32 v55, v57, v57
	v_add_f32_e32 v54, v54, v55
	v_add_f32_e32 v56, v60, v54
	v_lshlrev_b32_e32 v54, 16, v144
	v_and_b32_e32 v55, 0xffff0000, v144
	v_pk_add_f32 v[50:51], v[50:51], v[54:55]
	v_lshlrev_b32_e32 v54, 16, v145
	v_and_b32_e32 v55, 0xffff0000, v145
	v_pk_add_f32 v[52:53], v[52:53], v[54:55]
	v_cvt_pk_bf16_f32 v50, v50, v51
	v_cvt_pk_bf16_f32 v51, v52, v53
	ds_write_b64 v114, v[50:51]
	v_lshlrev_b32_e32 v52, 16, v50
	v_and_b32_e32 v50, 0xffff0000, v50
	v_lshlrev_b32_e32 v53, 16, v51
	v_and_b32_e32 v51, 0xffff0000, v51
	v_mul_f32_e32 v50, v50, v50
	v_mul_f32_e32 v51, v51, v51
	v_fmac_f32_e32 v50, v52, v52
	v_fmac_f32_e32 v51, v53, v53
	v_add_f32_e32 v50, v50, v51
	v_add_f32_e32 v50, v56, v50
	v_mov_b32_e32 v51, v50
	v_mov_b32_e32 v52, v50
	s_nop 1
	v_permlane16_swap_b32_e32 v51, v52
	v_xor_b32_e32 v51, v52, v51
	v_xor_b32_e32 v51, v51, v50
	v_add_f32_e32 v50, v50, v51
	v_mov_b32_e32 v51, v50
	v_mov_b32_e32 v52, v50
	s_nop 1
	v_permlane32_swap_b32_e32 v51, v52
	s_and_saveexec_b64 s[4:5], vcc
	s_cbranch_execz .LBB0_508
	v_xor_b32_e32 v51, v52, v51
	v_xor_b32_e32 v51, v51, v50
	v_add_f32_e32 v50, v50, v51
	v_fma_f32 v50, v50, s62, 0.5
	v_trunc_f32_e32 v50, v50
	v_mul_f32_e32 v51, 0x2f800000, v50
	v_floor_f32_e32 v51, v51
	v_fmac_f32_e32 v50, 0xcf800000, v51
	v_cvt_u32_f32_e32 v50, v50
	v_cvt_u32_f32_e32 v51, v51
	v_lshl_add_u64 v[52:53], v[130:131], 3, s[16:17]
	global_atomic_add_x2 v[52:53], v[50:51], off offset:1024

; __device__ __forceinline__ char* stg_ptr(bf16* shm, int bj, int row, int chunk8) {
;   return (char*)shm + (bj ? 98304 : 32768) + row * 256 + ((chunk8 ^ ((row & 15) << 1)) << 3);
; template <int EPI>
; __device__ void gemm_phase(const bf16* A, int lda, const bf16* Bt, int K, int N, const Params& p, bool last, bf16* dstb, bf16* shm, unsigned long long* SSQ, int wv, const float* gbias = nullptr) {
;     ...
;       _Pragma("unroll") for (int ai = 0; ai < 2; ++ai) {
;         _Pragma("unroll") for (int m = 0; m < 4; ++m) {
;           const int rl = wr * 64 + m * 16 + fr; const float rs = rsv[ai][m];
;           _Pragma("unroll") for (int bj = 0; bj < 2; ++bj) _Pragma("unroll") for (int n = 0; n < 2; ++n) {
;             f32x4 v = acc[ai][bj][m][n] * rs;
;             for (int j = 0; j < 4; ++j) { float r = fmaxf(v[j], 0.f); v[j] = r * r; }
;             u32x2 o = {pk2(v[0], v[1]), pk2(v[2], v[3])};
;             *(u32x2*)stg_ptr(shm, bj, rl, wc * 8 + n * 4 + fq) = o; }
;         }
;         stg_flush(shm, tid, dstb + (size_t)(brow + ai * HALF) * N + bcol, (size_t)N, ai == 0, ai == 0);
.LBB0_554:
	v_lshrrev_b32_e32 v131, 4, v1
	v_cmp_gt_u32_e32 vcc, s85, v1
	v_xor_b32_e32 v131, v131, v1
	v_bfe_u32 v166, v1, 4, 7
	v_cndmask_b32_e32 v139, v244, v245, vcc
	v_lshlrev_b32_e32 v131, 4, v131
	v_add_u32_e32 v139, 0, v139
	v_lshlrev_b32_e32 v141, 8, v166
	v_and_b32_e32 v131, 0xf0, v131
	v_add3_u32 v131, v139, v141, v131
	v_ashrrev_i32_e32 v139, 4, v1
	v_add_u32_e32 v141, 0x200, v1
	v_and_b32_e32 v146, 0xffffff80, v139
	v_lshrrev_b32_e32 v139, 4, v141
	v_cmp_gt_u32_e32 vcc, s85, v141
	v_xor_b32_e32 v139, v139, v1
	v_bfe_u32 v167, v141, 4, 7
	v_cndmask_b32_e32 v143, v244, v245, vcc
	v_lshlrev_b32_e32 v139, 4, v139
	v_add_u32_e32 v143, 0, v143
	v_lshlrev_b32_e32 v145, 8, v167
	v_and_b32_e32 v139, 0xf0, v139
	v_add3_u32 v139, v143, v145, v139
	v_ashrrev_i32_e32 v141, 4, v141
	v_add_u32_e32 v143, 0x400, v1
	v_and_b32_e32 v148, 0xffffff80, v141
	v_lshrrev_b32_e32 v141, 4, v143
	v_cmp_gt_u32_e32 vcc, s85, v143
	v_xor_b32_e32 v141, v141, v1
	v_bfe_u32 v168, v143, 4, 7
	v_cndmask_b32_e32 v145, v244, v245, vcc
	v_lshlrev_b32_e32 v141, 4, v141
	v_add_u32_e32 v145, 0, v145
	v_lshlrev_b32_e32 v150, 8, v168
	v_and_b32_e32 v141, 0xf0, v141
	v_add3_u32 v141, v145, v150, v141
	v_ashrrev_i32_e32 v143, 4, v143
	v_add_u32_e32 v145, 0x600, v1
	v_and_b32_e32 v150, 0xffffff80, v143
	v_lshrrev_b32_e32 v143, 4, v145
	v_cmp_gt_u32_e32 vcc, s85, v145
	v_xor_b32_e32 v143, v143, v1
	v_bfe_u32 v169, v145, 4, 7
	v_cndmask_b32_e32 v152, v244, v245, vcc
	v_lshlrev_b32_e32 v143, 4, v143
	v_add_u32_e32 v152, 0, v152
	v_lshlrev_b32_e32 v153, 8, v169
	v_and_b32_e32 v143, 0xf0, v143
	v_ashrrev_i32_e32 v145, 4, v145
	v_add_u32_e32 v154, 0x800, v1
	v_add3_u32 v143, v152, v153, v143
	v_and_b32_e32 v152, 0xffffff80, v145
	v_lshrrev_b32_e32 v145, 4, v154
	v_cmp_lt_u32_e32 vcc, s65, v1
	v_xor_b32_e32 v145, v145, v1
	v_bfe_u32 v170, v154, 4, 7
	v_cndmask_b32_e32 v155, v244, v245, vcc
	v_lshlrev_b32_e32 v145, 4, v145
	v_add_u32_e32 v155, 0, v155
	v_lshlrev_b32_e32 v156, 8, v170
	v_and_b32_e32 v145, 0xf0, v145
	v_add3_u32 v145, v155, v156, v145
	v_add_u32_e32 v156, 0xa00, v1
	v_lshrrev_b32_e32 v157, 4, v156
	v_cmp_gt_u32_e32 vcc, s85, v156
	v_xor_b32_e32 v157, v157, v1
	v_bfe_u32 v171, v156, 4, 7
	v_cndmask_b32_e32 v158, v244, v245, vcc
	v_lshlrev_b32_e32 v157, 4, v157
	v_add_u32_e32 v158, 0, v158
	v_lshlrev_b32_e32 v159, 8, v171
	v_and_b32_e32 v157, 0xf0, v157
	v_add3_u32 v162, v158, v159, v157
	v_add_u32_e32 v158, 0xc00, v1
	v_lshrrev_b32_e32 v159, 4, v158
	v_cmp_gt_u32_e32 vcc, s85, v158
	v_xor_b32_e32 v159, v159, v1
	v_bfe_u32 v172, v158, 4, 7
	v_cndmask_b32_e32 v160, v244, v245, vcc
	v_lshlrev_b32_e32 v159, 4, v159
	v_pk_mul_f32 v[128:129], v[128:129], v[138:139] op_sel_hi:[1,0]
	v_pk_mul_f32 v[126:127], v[126:127], v[138:139] op_sel_hi:[1,0]
	v_add_u32_e32 v160, 0, v160
	v_lshlrev_b32_e32 v161, 8, v172
	v_and_b32_e32 v159, 0xf0, v159
	v_max_f32_e32 v126, 0, v126
	v_max_f32_e32 v127, 0, v127
	v_max_f32_e32 v128, 0, v128
	v_max_f32_e32 v129, 0, v129
	v_add3_u32 v163, v160, v161, v159
	v_add_u32_e32 v160, 0xe00, v1
	v_pk_mul_f32 v[126:127], v[126:127], v[126:127]
	v_pk_mul_f32 v[128:129], v[128:129], v[128:129]
	v_lshlrev_b32_e32 v165, 4, v137
	v_lshrrev_b32_e32 v161, 4, v160
	v_lshlrev_b32_e32 v133, 14, v133
	v_lshlrev_b32_e32 v137, 8, v137
	v_cvt_pk_bf16_f32 v126, v126, v127
	v_cvt_pk_bf16_f32 v127, v128, v129
	v_lshrrev_b32_e32 v128, 1, v1
	v_xor_b32_e32 v161, v161, v1
	v_add3_u32 v133, 0, v133, v137
	v_and_b32_e32 v128, 24, v128
	v_and_b32_e32 v1, 0xc0, v1
	v_pk_mul_f32 v[118:119], v[118:119], v[138:139] op_sel_hi:[1,0]
	v_or_b32_e32 v129, v128, v1
	v_bitop3_b32 v128, v128, v165, v1 bitop3:0x36
	v_pk_mul_f32 v[120:121], v[120:121], v[138:139] op_sel_hi:[1,0]
	v_max_f32_e32 v118, 0, v118
	v_max_f32_e32 v119, 0, v119
	v_pk_mul_f32 v[112:113], v[112:113], v[136:137] op_sel_hi:[1,0]
	v_pk_mul_f32 v[110:111], v[110:111], v[136:137] op_sel_hi:[1,0]
	v_pk_mul_f32 v[104:105], v[104:105], v[136:137] op_sel_hi:[1,0]
	v_pk_mul_f32 v[102:103], v[102:103], v[136:137] op_sel_hi:[1,0]
	v_pk_mul_f32 v[96:97], v[96:97], v[132:133] op_sel_hi:[1,0]
	v_pk_mul_f32 v[94:95], v[94:95], v[132:133] op_sel_hi:[1,0]
	v_pk_mul_f32 v[88:89], v[88:89], v[132:133] op_sel_hi:[1,0]
	v_pk_mul_f32 v[86:87], v[86:87], v[132:133] op_sel_hi:[1,0]
	v_pk_mul_f32 v[80:81], v[80:81], v[134:135] op_sel_hi:[1,0]
	v_pk_mul_f32 v[78:79], v[78:79], v[134:135] op_sel_hi:[1,0]
	v_pk_mul_f32 v[72:73], v[72:73], v[134:135] op_sel_hi:[1,0]
	v_pk_mul_f32 v[70:71], v[70:71], v[134:135] op_sel_hi:[1,0]
	v_add_u32_e32 v1, v133, v128
	v_pk_mul_f32 v[118:119], v[118:119], v[118:119]
	v_max_f32_e32 v120, 0, v120
	v_max_f32_e32 v121, 0, v121
	v_max_f32_e32 v110, 0, v110
	v_max_f32_e32 v111, 0, v111
	v_max_f32_e32 v112, 0, v112
	v_max_f32_e32 v113, 0, v113
	v_max_f32_e32 v102, 0, v102
	v_max_f32_e32 v103, 0, v103
	v_max_f32_e32 v104, 0, v104
	v_max_f32_e32 v105, 0, v105
	v_max_f32_e32 v94, 0, v94
	v_max_f32_e32 v95, 0, v95
	v_max_f32_e32 v96, 0, v96
	v_max_f32_e32 v97, 0, v97
	v_max_f32_e32 v86, 0, v86
	v_max_f32_e32 v87, 0, v87
	v_max_f32_e32 v88, 0, v88
	v_max_f32_e32 v89, 0, v89
	v_max_f32_e32 v78, 0, v78
	v_max_f32_e32 v79, 0, v79
	v_max_f32_e32 v80, 0, v80
	v_max_f32_e32 v81, 0, v81
	v_max_f32_e32 v70, 0, v70
	v_max_f32_e32 v71, 0, v71
	v_max_f32_e32 v72, 0, v72
	v_max_f32_e32 v73, 0, v73
	ds_write_b64 v1, v[126:127] offset:32768
	v_pk_mul_f32 v[120:121], v[120:121], v[120:121]
	v_cvt_pk_bf16_f32 v126, v118, v119
	v_bitop3_b32 v119, v129, v165, 32 bitop3:0x36
	v_pk_mul_f32 v[110:111], v[110:111], v[110:111]
	v_pk_mul_f32 v[112:113], v[112:113], v[112:113]
	v_pk_mul_f32 v[102:103], v[102:103], v[102:103]
; template <int EPI>
; __device__ void gemm_phase(const bf16* A, int lda, const bf16* Bt, int K, int N, const Params& p, bool last, bf16* dstb, bf16* shm, unsigned long long* SSQ, int wv, const float* gbias = nullptr) {
;     ...
;       _Pragma("unroll") for (int ai = 0; ai < 2; ++ai) {
;         _Pragma("unroll") for (int m = 0; m < 4; ++m) {
;           const int rl = wr * 64 + m * 16 + fr; const float rs = rsv[ai][m];
;           _Pragma("unroll") for (int bj = 0; bj < 2; ++bj) _Pragma("unroll") for (int n = 0; n < 2; ++n) {
;             f32x4 v = acc[ai][bj][m][n] * rs;
;             for (int j = 0; j < 4; ++j) { float r = fmaxf(v[j], 0.f); v[j] = r * r; }
;             u32x2 o = {pk2(v[0], v[1]), pk2(v[2], v[3])};
;             *(u32x2*)stg_ptr(shm, bj, rl, wc * 8 + n * 4 + fq) = o; }
;         }
;         stg_flush(shm, tid, dstb + (size_t)(brow + ai * HALF) * N + bcol, (size_t)N, ai == 0, ai == 0);
	v_pk_mul_f32 v[104:105], v[104:105], v[104:105]
	v_pk_mul_f32 v[94:95], v[94:95], v[94:95]
	v_pk_mul_f32 v[96:97], v[96:97], v[96:97]
	v_pk_mul_f32 v[86:87], v[86:87], v[86:87]
	v_pk_mul_f32 v[88:89], v[88:89], v[88:89]
	v_pk_mul_f32 v[78:79], v[78:79], v[78:79]
	v_pk_mul_f32 v[80:81], v[80:81], v[80:81]
	v_pk_mul_f32 v[70:71], v[70:71], v[70:71]
	v_pk_mul_f32 v[72:73], v[72:73], v[72:73]
	v_cvt_pk_bf16_f32 v127, v120, v121
	v_add_u32_e32 v118, v133, v119
	v_cvt_pk_bf16_f32 v110, v110, v111
	v_cvt_pk_bf16_f32 v111, v112, v113
	v_cvt_pk_bf16_f32 v102, v102, v103
	v_cvt_pk_bf16_f32 v103, v104, v105
	v_cvt_pk_bf16_f32 v94, v94, v95
	v_cvt_pk_bf16_f32 v95, v96, v97
	v_cvt_pk_bf16_f32 v86, v86, v87
	v_cvt_pk_bf16_f32 v87, v88, v89
	v_cvt_pk_bf16_f32 v78, v78, v79
	v_cvt_pk_bf16_f32 v79, v80, v81
	v_cvt_pk_bf16_f32 v70, v70, v71
	v_cvt_pk_bf16_f32 v71, v72, v73
	v_pk_mul_f32 v[120:121], v[124:125], v[138:139] op_sel_hi:[1,0]
	v_pk_mul_f32 v[122:123], v[122:123], v[138:139] op_sel_hi:[1,0]
	v_pk_mul_f32 v[116:117], v[116:117], v[138:139] op_sel_hi:[1,0]
	v_pk_mul_f32 v[114:115], v[114:115], v[138:139] op_sel_hi:[1,0]
	ds_write_b64 v1, v[110:111] offset:36864
	ds_write2st64_b64 v118, v[126:127], v[102:103] offset0:64 offset1:72
	v_pk_mul_f32 v[102:103], v[108:109], v[136:137] op_sel_hi:[1,0]
	v_pk_mul_f32 v[104:105], v[106:107], v[136:137] op_sel_hi:[1,0]
	v_pk_mul_f32 v[100:101], v[100:101], v[136:137] op_sel_hi:[1,0]
	v_pk_mul_f32 v[98:99], v[98:99], v[136:137] op_sel_hi:[1,0]
	ds_write_b64 v1, v[94:95] offset:40960
	v_pk_mul_f32 v[88:89], v[92:93], v[132:133] op_sel_hi:[1,0]
	v_pk_mul_f32 v[90:91], v[90:91], v[132:133] op_sel_hi:[1,0]
	v_pk_mul_f32 v[84:85], v[84:85], v[132:133] op_sel_hi:[1,0]
	v_pk_mul_f32 v[82:83], v[82:83], v[132:133] op_sel_hi:[1,0]
	ds_write_b64 v1, v[78:79] offset:45056
	ds_write2st64_b64 v118, v[86:87], v[70:71] offset0:80 offset1:88
	v_pk_mul_f32 v[70:71], v[76:77], v[134:135] op_sel_hi:[1,0]
	v_pk_mul_f32 v[72:73], v[74:75], v[134:135] op_sel_hi:[1,0]
	v_pk_mul_f32 v[68:69], v[68:69], v[134:135] op_sel_hi:[1,0]
	v_pk_mul_f32 v[66:67], v[66:67], v[134:135] op_sel_hi:[1,0]
	s_lshl_b64 s[12:13], s[10:11], 1
	v_max_f32_e32 v122, 0, v122
	v_max_f32_e32 v123, 0, v123
	v_max_f32_e32 v120, 0, v120
	v_max_f32_e32 v121, 0, v121
	v_max_f32_e32 v114, 0, v114
	v_max_f32_e32 v115, 0, v115
	v_max_f32_e32 v116, 0, v116
	v_max_f32_e32 v117, 0, v117
	v_max_f32_e32 v104, 0, v104
	v_max_f32_e32 v105, 0, v105
	v_max_f32_e32 v102, 0, v102
	v_max_f32_e32 v103, 0, v103
	v_max_f32_e32 v98, 0, v98
	v_max_f32_e32 v99, 0, v99
	v_max_f32_e32 v100, 0, v100
	v_max_f32_e32 v101, 0, v101
	v_max_f32_e32 v90, 0, v90
	v_max_f32_e32 v91, 0, v91
	v_max_f32_e32 v88, 0, v88
	v_max_f32_e32 v89, 0, v89
	v_max_f32_e32 v82, 0, v82
	v_max_f32_e32 v83, 0, v83
	v_max_f32_e32 v84, 0, v84
	v_max_f32_e32 v85, 0, v85
	v_max_f32_e32 v72, 0, v72
	v_max_f32_e32 v73, 0, v73
	v_max_f32_e32 v70, 0, v70
	v_max_f32_e32 v71, 0, v71
	v_max_f32_e32 v66, 0, v66
	v_max_f32_e32 v67, 0, v67
	v_max_f32_e32 v68, 0, v68
	v_max_f32_e32 v69, 0, v69
	s_add_u32 s11, s86, s12
	v_add_u32_e32 v129, 0x18000, v133
	v_pk_mul_f32 v[122:123], v[122:123], v[122:123]
	v_pk_mul_f32 v[120:121], v[120:121], v[120:121]
	v_pk_mul_f32 v[114:115], v[114:115], v[114:115]
	v_pk_mul_f32 v[116:117], v[116:117], v[116:117]
	v_add_u32_e32 v110, 0x19000, v133
	v_pk_mul_f32 v[104:105], v[104:105], v[104:105]
	v_pk_mul_f32 v[102:103], v[102:103], v[102:103]
	v_pk_mul_f32 v[98:99], v[98:99], v[98:99]
	v_pk_mul_f32 v[100:101], v[100:101], v[100:101]
	v_add_u32_e32 v94, 0x1a000, v133
	v_pk_mul_f32 v[90:91], v[90:91], v[90:91]
	v_pk_mul_f32 v[88:89], v[88:89], v[88:89]
	v_pk_mul_f32 v[82:83], v[82:83], v[82:83]
	v_pk_mul_f32 v[84:85], v[84:85], v[84:85]
	v_add_u32_e32 v78, 0x1b000, v133
	v_pk_mul_f32 v[72:73], v[72:73], v[72:73]
	v_pk_mul_f32 v[70:71], v[70:71], v[70:71]
	v_pk_mul_f32 v[66:67], v[66:67], v[66:67]
	v_pk_mul_f32 v[68:69], v[68:69], v[68:69]
	s_addc_u32 s10, s87, s13
	v_cvt_pk_bf16_f32 v122, v122, v123
	v_cvt_pk_bf16_f32 v123, v120, v121
	v_add_u32_e32 v120, v129, v128
	v_cvt_pk_bf16_f32 v114, v114, v115
	v_cvt_pk_bf16_f32 v115, v116, v117
	v_add_u32_e32 v116, v129, v119
	v_cvt_pk_bf16_f32 v104, v104, v105
	v_cvt_pk_bf16_f32 v105, v102, v103
	v_add_u32_e32 v106, v110, v128
	v_cvt_pk_bf16_f32 v98, v98, v99
	v_cvt_pk_bf16_f32 v99, v100, v101
	v_add_u32_e32 v107, v110, v119
	v_cvt_pk_bf16_f32 v90, v90, v91
	v_cvt_pk_bf16_f32 v91, v88, v89
	v_add_u32_e32 v108, v94, v128
	v_cvt_pk_bf16_f32 v82, v82, v83
	v_cvt_pk_bf16_f32 v83, v84, v85
	v_add_u32_e32 v109, v94, v119
	v_cvt_pk_bf16_f32 v72, v72, v73
	v_cvt_pk_bf16_f32 v73, v70, v71
	v_add_u32_e32 v110, v78, v128
	v_cvt_pk_bf16_f32 v66, v66, v67
	v_cvt_pk_bf16_f32 v67, v68, v69
	v_add_u32_e32 v111, v78, v119
	s_lshl_b64 s[12:13], s[6:7], 14
	ds_write_b64 v120, v[122:123]
	ds_write_b64 v116, v[114:115]
	ds_write_b64 v106, v[104:105]
	ds_write_b64 v107, v[98:99]
	ds_write_b64 v108, v[90:91]
	ds_write_b64 v109, v[82:83]
	ds_write_b64 v110, v[72:73]
	ds_write_b64 v111, v[66:67]
	s_add_u32 s12, s11, s12
	v_ashrrev_i32_e32 v147, 31, v146
	s_addc_u32 s13, s10, s13
	s_waitcnt lgkmcnt(0)
	s_barrier
; #define LDS_BARRIER() do { asm volatile("s_waitcnt lgkmcnt(0)" ::: "memory"); __builtin_amdgcn_s_barrier(); asm volatile("" ::: "memory"); } while (0)
; __device__ __forceinline__ void st16_asm(void* ptr, u32x4 v) { asm volatile("global_store_dwordx4 %0, %1, off\n\ts_nop 7" :: "v"(ptr), "v"(v) : "memory"); }
; __device__ __forceinline__ void stg_flush(bf16* shm, int tid, bf16* dst, size_t pitch, bool first, bool tail_barrier = true) {
;   LDS_BARRIER();
;   if (first) asm volatile("s_waitcnt vmcnt(0)" ::: "memory");
;   _Pragma("unroll") for (int i = 0; i < 8; ++i) {
;     const int idx = tid + 512 * i, bjr = idx >> 11, row = (idx >> 4) & 127, c16 = idx & 15;
;     const u32x4 d = *(const u32x4*)stg_ptr(shm, bjr, row, 2 * c16);
;     st16_asm(dst + (size_t)row * pitch + bjr * HALF + c16 * 8, d); }
;   if (tail_barrier) LDS_BARRIER();
; }
; template <int EPI>
; __device__ void gemm_phase(const bf16* A, int lda, const bf16* Bt, int K, int N, const Params& p, bool last, bf16* dstb, bf16* shm, unsigned long long* SSQ, int wv, const float* gbias = nullptr) {
;     ...
;       _Pragma("unroll") for (int ai = 0; ai < 2; ++ai) {
;         _Pragma("unroll") for (int m = 0; m < 4; ++m) {
;           const int rl = wr * 64 + m * 16 + fr; const float rs = rsv[ai][m];
;           _Pragma("unroll") for (int bj = 0; bj < 2; ++bj) _Pragma("unroll") for (int n = 0; n < 2; ++n) {
;             f32x4 v = acc[ai][bj][m][n] * rs;
;             for (int j = 0; j < 4; ++j) { float r = fmaxf(v[j], 0.f); v[j] = r * r; }
	v_lshlrev_b32_e32 v68, 14, v166
	v_mov_b32_e32 v69, v0
	s_waitcnt vmcnt(0)
	v_lshl_add_u64 v[66:67], s[12:13], 0, v[68:69]
	v_lshlrev_b64 v[70:71], 1, v[146:147]
	ds_read_b128 v[72:75], v131
	v_lshl_add_u64 v[76:77], v[66:67], 0, v[70:71]
	v_and_b32_e32 v66, 0xf0, v135
	v_mov_b32_e32 v67, v0
	v_ashrrev_i32_e32 v149, 31, v148
	v_lshl_add_u64 v[76:77], v[76:77], 0, v[66:67]
	s_waitcnt lgkmcnt(0)
	global_store_dwordx4 v[76:77], v[72:75], off
	s_nop 7
	v_lshlrev_b32_e32 v72, 14, v167
	v_mov_b32_e32 v73, v0
	v_lshl_add_u64 v[80:81], s[12:13], 0, v[72:73]
	v_lshlrev_b64 v[74:75], 1, v[148:149]
	ds_read_b128 v[76:79], v139
	v_lshl_add_u64 v[80:81], v[80:81], 0, v[74:75]
	v_ashrrev_i32_e32 v151, 31, v150
	v_lshl_add_u64 v[80:81], v[80:81], 0, v[66:67]
	s_waitcnt lgkmcnt(0)
	global_store_dwordx4 v[80:81], v[76:79], off
	s_nop 7
	v_lshlrev_b32_e32 v76, 14, v168
	v_mov_b32_e32 v77, v0
	v_lshl_add_u64 v[84:85], s[12:13], 0, v[76:77]
	v_lshlrev_b64 v[78:79], 1, v[150:151]
	ds_read_b128 v[80:83], v141
	v_lshl_add_u64 v[84:85], v[84:85], 0, v[78:79]
	v_ashrrev_i32_e32 v153, 31, v152
	v_lshl_add_u64 v[84:85], v[84:85], 0, v[66:67]
	s_waitcnt lgkmcnt(0)
	global_store_dwordx4 v[84:85], v[80:83], off
	s_nop 7
	v_lshlrev_b32_e32 v80, 14, v169
	v_mov_b32_e32 v81, v0
	v_ashrrev_i32_e32 v154, 4, v154
	v_lshl_add_u64 v[88:89], s[12:13], 0, v[80:81]
	v_lshlrev_b64 v[82:83], 1, v[152:153]
	v_and_b32_e32 v154, 0xffffff80, v154
	ds_read_b128 v[84:87], v143
	v_lshl_add_u64 v[88:89], v[88:89], 0, v[82:83]
	v_ashrrev_i32_e32 v155, 31, v154
	v_lshl_add_u64 v[88:89], v[88:89], 0, v[66:67]
	s_waitcnt lgkmcnt(0)
	global_store_dwordx4 v[88:89], v[84:87], off
	s_nop 7
	v_lshlrev_b32_e32 v84, 14, v170
	v_mov_b32_e32 v85, v0
	v_ashrrev_i32_e32 v156, 4, v156
	v_lshl_add_u64 v[92:93], s[12:13], 0, v[84:85]
	v_lshlrev_b64 v[86:87], 1, v[154:155]
	v_and_b32_e32 v156, 0xffffff80, v156
	ds_read_b128 v[88:91], v145
	v_lshl_add_u64 v[92:93], v[92:93], 0, v[86:87]
	v_ashrrev_i32_e32 v157, 31, v156
	v_lshl_add_u64 v[92:93], v[92:93], 0, v[66:67]
	s_waitcnt lgkmcnt(0)
	global_store_dwordx4 v[92:93], v[88:91], off
	s_nop 7
	v_lshlrev_b32_e32 v88, 14, v171
	v_mov_b32_e32 v89, v0
	v_ashrrev_i32_e32 v158, 4, v158
	v_lshl_add_u64 v[96:97], s[12:13], 0, v[88:89]
	v_lshlrev_b64 v[90:91], 1, v[156:157]
	v_and_b32_e32 v158, 0xffffff80, v158
	ds_read_b128 v[92:95], v162
	v_lshl_add_u64 v[96:97], v[96:97], 0, v[90:91]
	v_ashrrev_i32_e32 v159, 31, v158
	v_cmp_gt_u32_e32 vcc, s85, v160
	v_lshl_add_u64 v[96:97], v[96:97], 0, v[66:67]
	s_waitcnt lgkmcnt(0)
	global_store_dwordx4 v[96:97], v[92:95], off
	s_nop 7
	v_lshlrev_b32_e32 v92, 14, v172
	v_mov_b32_e32 v93, v0
	v_bfe_u32 v173, v160, 4, 7
	v_cndmask_b32_e32 v164, v244, v245, vcc
	v_lshlrev_b32_e32 v161, 4, v161
	v_ashrrev_i32_e32 v160, 4, v160
	v_lshl_add_u64 v[100:101], s[12:13], 0, v[92:93]
	v_lshlrev_b64 v[94:95], 1, v[158:159]
	v_add_u32_e32 v164, 0, v164
	v_lshlrev_b32_e32 v174, 8, v173
	v_and_b32_e32 v161, 0xf0, v161
	v_and_b32_e32 v160, 0xffffff80, v160
	ds_read_b128 v[96:99], v163
	v_lshl_add_u64 v[100:101], v[100:101], 0, v[94:95]
	s_bitset1_b32 s6, 7
	v_add3_u32 v164, v164, v174, v161
	v_ashrrev_i32_e32 v161, 31, v160
	v_lshl_add_u64 v[100:101], v[100:101], 0, v[66:67]
	s_waitcnt lgkmcnt(0)
	global_store_dwordx4 v[100:101], v[96:99], off
	s_nop 7
	v_lshlrev_b32_e32 v96, 14, v173
	v_mov_b32_e32 v97, v0
	v_pk_mul_f32 v[8:9], v[8:9], v[140:141] op_sel_hi:[1,0]
	v_pk_mul_f32 v[6:7], v[6:7], v[140:141] op_sel_hi:[1,0]
	s_ashr_i32 s7, s6, 31
	v_lshl_add_u64 v[104:105], s[12:13], 0, v[96:97]
	v_lshlrev_b64 v[98:99], 1, v[160:161]
	v_pk_mul_f32 v[64:65], v[64:65], v[130:131] op_sel_hi:[1,0]
	v_pk_mul_f32 v[62:63], v[62:63], v[130:131] op_sel_hi:[1,0]
	v_pk_mul_f32 v[60:61], v[60:61], v[130:131] op_sel_hi:[1,0]
	v_pk_mul_f32 v[58:59], v[58:59], v[130:131] op_sel_hi:[1,0]
	v_pk_mul_f32 v[56:57], v[56:57], v[130:131] op_sel_hi:[1,0]
	v_pk_mul_f32 v[54:55], v[54:55], v[130:131] op_sel_hi:[1,0]
	v_pk_mul_f32 v[52:53], v[52:53], v[130:131] op_sel_hi:[1,0]
	v_pk_mul_f32 v[50:51], v[50:51], v[130:131] op_sel_hi:[1,0]
	v_pk_mul_f32 v[48:49], v[48:49], v[144:145] op_sel_hi:[1,0]
	v_pk_mul_f32 v[46:47], v[46:47], v[144:145] op_sel_hi:[1,0]
	v_pk_mul_f32 v[44:45], v[44:45], v[144:145] op_sel_hi:[1,0]
	v_pk_mul_f32 v[42:43], v[42:43], v[144:145] op_sel_hi:[1,0]
	v_pk_mul_f32 v[40:41], v[40:41], v[144:145] op_sel_hi:[1,0]
	v_pk_mul_f32 v[38:39], v[38:39], v[144:145] op_sel_hi:[1,0]
	v_pk_mul_f32 v[36:37], v[36:37], v[144:145] op_sel_hi:[1,0]
	v_pk_mul_f32 v[34:35], v[34:35], v[144:145] op_sel_hi:[1,0]
	v_pk_mul_f32 v[32:33], v[32:33], v[142:143] op_sel_hi:[1,0]
	v_pk_mul_f32 v[30:31], v[30:31], v[142:143] op_sel_hi:[1,0]
	v_pk_mul_f32 v[28:29], v[28:29], v[142:143] op_sel_hi:[1,0]
	v_pk_mul_f32 v[26:27], v[26:27], v[142:143] op_sel_hi:[1,0]
	v_pk_mul_f32 v[24:25], v[24:25], v[142:143] op_sel_hi:[1,0]
	v_pk_mul_f32 v[22:23], v[22:23], v[142:143] op_sel_hi:[1,0]
	v_pk_mul_f32 v[20:21], v[20:21], v[142:143] op_sel_hi:[1,0]
	v_pk_mul_f32 v[18:19], v[18:19], v[142:143] op_sel_hi:[1,0]
	v_pk_mul_f32 v[16:17], v[16:17], v[140:141] op_sel_hi:[1,0]
	v_pk_mul_f32 v[14:15], v[14:15], v[140:141] op_sel_hi:[1,0]
	v_pk_mul_f32 v[12:13], v[12:13], v[140:141] op_sel_hi:[1,0]
	v_pk_mul_f32 v[10:11], v[10:11], v[140:141] op_sel_hi:[1,0]
	v_max_f32_e32 v6, 0, v6
	v_max_f32_e32 v7, 0, v7
	v_max_f32_e32 v8, 0, v8
	v_max_f32_e32 v9, 0, v9
	v_pk_mul_f32 v[4:5], v[4:5], v[140:141] op_sel_hi:[1,0]
	v_pk_mul_f32 v[2:3], v[2:3], v[140:141] op_sel_hi:[1,0]
	s_lshl_b64 s[6:7], s[6:7], 14
	v_lshl_add_u64 v[104:105], v[104:105], 0, v[98:99]
	v_max_f32_e32 v62, 0, v62
	v_max_f32_e32 v63, 0, v63
; #define LDS_BARRIER() do { asm volatile("s_waitcnt lgkmcnt(0)" ::: "memory"); __builtin_amdgcn_s_barrier(); asm volatile("" ::: "memory"); } while (0)
; __device__ __forceinline__ void st16_asm(void* ptr, u32x4 v) { asm volatile("global_store_dwordx4 %0, %1, off\n\ts_nop 7" :: "v"(ptr), "v"(v) : "memory"); }
; __device__ __forceinline__ void stg_flush(bf16* shm, int tid, bf16* dst, size_t pitch, bool first, bool tail_barrier = true) {
;   LDS_BARRIER();
;   if (first) asm volatile("s_waitcnt vmcnt(0)" ::: "memory");
;   _Pragma("unroll") for (int i = 0; i < 8; ++i) {
;     const int idx = tid + 512 * i, bjr = idx >> 11, row = (idx >> 4) & 127, c16 = idx & 15;
;     const u32x4 d = *(const u32x4*)stg_ptr(shm, bjr, row, 2 * c16);
;     st16_asm(dst + (size_t)row * pitch + bjr * HALF + c16 * 8, d); }
;   if (tail_barrier) LDS_BARRIER();
; }
; template <int EPI>
; __device__ void gemm_phase(const bf16* A, int lda, const bf16* Bt, int K, int N, const Params& p, bool last, bf16* dstb, bf16* shm, unsigned long long* SSQ, int wv, const float* gbias = nullptr) {
;     ...
;       _Pragma("unroll") for (int ai = 0; ai < 2; ++ai) {
;         _Pragma("unroll") for (int m = 0; m < 4; ++m) {
;           const int rl = wr * 64 + m * 16 + fr; const float rs = rsv[ai][m];
;           _Pragma("unroll") for (int bj = 0; bj < 2; ++bj) _Pragma("unroll") for (int n = 0; n < 2; ++n) {
;             f32x4 v = acc[ai][bj][m][n] * rs;
;             for (int j = 0; j < 4; ++j) { float r = fmaxf(v[j], 0.f); v[j] = r * r; }
;             u32x2 o = {pk2(v[0], v[1]), pk2(v[2], v[3])};
;             *(u32x2*)stg_ptr(shm, bj, rl, wc * 8 + n * 4 + fq) = o; }
;         }
;         stg_flush(shm, tid, dstb + (size_t)(brow + ai * HALF) * N + bcol, (size_t)N, ai == 0, ai == 0);
;       }
	v_max_f32_e32 v64, 0, v64
	v_max_f32_e32 v65, 0, v65
	v_max_f32_e32 v58, 0, v58
	v_max_f32_e32 v59, 0, v59
	v_max_f32_e32 v60, 0, v60
	v_max_f32_e32 v61, 0, v61
	v_max_f32_e32 v54, 0, v54
	v_max_f32_e32 v55, 0, v55
	v_max_f32_e32 v56, 0, v56
	v_max_f32_e32 v57, 0, v57
	v_max_f32_e32 v50, 0, v50
	v_max_f32_e32 v51, 0, v51
	v_max_f32_e32 v52, 0, v52
	v_max_f32_e32 v53, 0, v53
	v_max_f32_e32 v46, 0, v46
	v_max_f32_e32 v47, 0, v47
	v_max_f32_e32 v48, 0, v48
	v_max_f32_e32 v49, 0, v49
	v_max_f32_e32 v42, 0, v42
	v_max_f32_e32 v43, 0, v43
	v_max_f32_e32 v44, 0, v44
	v_max_f32_e32 v45, 0, v45
	v_max_f32_e32 v38, 0, v38
	v_max_f32_e32 v39, 0, v39
	v_max_f32_e32 v40, 0, v40
	v_max_f32_e32 v41, 0, v41
	v_max_f32_e32 v34, 0, v34
	v_max_f32_e32 v35, 0, v35
	v_max_f32_e32 v36, 0, v36
	v_max_f32_e32 v37, 0, v37
	v_max_f32_e32 v30, 0, v30
	v_max_f32_e32 v31, 0, v31
	v_max_f32_e32 v32, 0, v32
	v_max_f32_e32 v33, 0, v33
	v_max_f32_e32 v26, 0, v26
	v_max_f32_e32 v27, 0, v27
	v_max_f32_e32 v28, 0, v28
	v_max_f32_e32 v29, 0, v29
	v_max_f32_e32 v22, 0, v22
	v_max_f32_e32 v23, 0, v23
	v_max_f32_e32 v24, 0, v24
	v_max_f32_e32 v25, 0, v25
	v_max_f32_e32 v18, 0, v18
	v_max_f32_e32 v19, 0, v19
	v_max_f32_e32 v20, 0, v20
	v_max_f32_e32 v21, 0, v21
	v_max_f32_e32 v14, 0, v14
	v_max_f32_e32 v15, 0, v15
	v_max_f32_e32 v16, 0, v16
	v_max_f32_e32 v17, 0, v17
	v_max_f32_e32 v10, 0, v10
	v_max_f32_e32 v11, 0, v11
	v_max_f32_e32 v12, 0, v12
	v_max_f32_e32 v13, 0, v13
	v_pk_mul_f32 v[6:7], v[6:7], v[6:7]
	v_pk_mul_f32 v[8:9], v[8:9], v[8:9]
	v_max_f32_e32 v2, 0, v2
	v_max_f32_e32 v3, 0, v3
	v_max_f32_e32 v4, 0, v4
	v_max_f32_e32 v5, 0, v5
	s_add_u32 s6, s11, s6
	ds_read_b128 v[100:103], v164
	v_lshl_add_u64 v[104:105], v[104:105], 0, v[66:67]
	s_waitcnt lgkmcnt(0)
	global_store_dwordx4 v[104:105], v[100:103], off
	s_nop 7
	v_pk_mul_f32 v[62:63], v[62:63], v[62:63]
	v_pk_mul_f32 v[64:65], v[64:65], v[64:65]
	v_pk_mul_f32 v[58:59], v[58:59], v[58:59]
	v_pk_mul_f32 v[60:61], v[60:61], v[60:61]
	v_pk_mul_f32 v[54:55], v[54:55], v[54:55]
	v_pk_mul_f32 v[56:57], v[56:57], v[56:57]
	v_pk_mul_f32 v[50:51], v[50:51], v[50:51]
	v_pk_mul_f32 v[52:53], v[52:53], v[52:53]
	v_pk_mul_f32 v[46:47], v[46:47], v[46:47]
	v_pk_mul_f32 v[48:49], v[48:49], v[48:49]
	v_pk_mul_f32 v[42:43], v[42:43], v[42:43]
	v_pk_mul_f32 v[44:45], v[44:45], v[44:45]
	v_pk_mul_f32 v[38:39], v[38:39], v[38:39]
	v_pk_mul_f32 v[40:41], v[40:41], v[40:41]
	v_pk_mul_f32 v[34:35], v[34:35], v[34:35]
	v_pk_mul_f32 v[36:37], v[36:37], v[36:37]
	v_pk_mul_f32 v[30:31], v[30:31], v[30:31]
	v_pk_mul_f32 v[32:33], v[32:33], v[32:33]
	v_pk_mul_f32 v[26:27], v[26:27], v[26:27]
	v_pk_mul_f32 v[28:29], v[28:29], v[28:29]
	v_pk_mul_f32 v[22:23], v[22:23], v[22:23]
	v_pk_mul_f32 v[24:25], v[24:25], v[24:25]
	v_pk_mul_f32 v[18:19], v[18:19], v[18:19]
	v_pk_mul_f32 v[20:21], v[20:21], v[20:21]
	v_pk_mul_f32 v[14:15], v[14:15], v[14:15]
	v_pk_mul_f32 v[16:17], v[16:17], v[16:17]
	v_pk_mul_f32 v[10:11], v[10:11], v[10:11]
	v_pk_mul_f32 v[12:13], v[12:13], v[12:13]
	v_cvt_pk_bf16_f32 v6, v6, v7
	v_cvt_pk_bf16_f32 v7, v8, v9
	v_pk_mul_f32 v[2:3], v[2:3], v[2:3]
	v_pk_mul_f32 v[4:5], v[4:5], v[4:5]
	s_addc_u32 s7, s10, s7
	s_barrier
	v_cvt_pk_bf16_f32 v62, v62, v63
	v_cvt_pk_bf16_f32 v63, v64, v65
	v_cvt_pk_bf16_f32 v58, v58, v59
	v_cvt_pk_bf16_f32 v59, v60, v61
	v_cvt_pk_bf16_f32 v54, v54, v55
	v_cvt_pk_bf16_f32 v55, v56, v57
	v_cvt_pk_bf16_f32 v50, v50, v51
	v_cvt_pk_bf16_f32 v51, v52, v53
	v_cvt_pk_bf16_f32 v46, v46, v47
	v_cvt_pk_bf16_f32 v47, v48, v49
	v_cvt_pk_bf16_f32 v42, v42, v43
	v_cvt_pk_bf16_f32 v43, v44, v45
	v_cvt_pk_bf16_f32 v38, v38, v39
	v_cvt_pk_bf16_f32 v39, v40, v41
	v_cvt_pk_bf16_f32 v34, v34, v35
	v_cvt_pk_bf16_f32 v35, v36, v37
	v_cvt_pk_bf16_f32 v30, v30, v31
	v_cvt_pk_bf16_f32 v31, v32, v33
	v_cvt_pk_bf16_f32 v26, v26, v27
	v_cvt_pk_bf16_f32 v27, v28, v29
	v_cvt_pk_bf16_f32 v22, v22, v23
	v_cvt_pk_bf16_f32 v23, v24, v25
	v_cvt_pk_bf16_f32 v18, v18, v19
	v_cvt_pk_bf16_f32 v19, v20, v21
	v_cvt_pk_bf16_f32 v14, v14, v15
	v_cvt_pk_bf16_f32 v15, v16, v17
	v_cvt_pk_bf16_f32 v10, v10, v11
	v_cvt_pk_bf16_f32 v11, v12, v13
	ds_write_b64 v110, v[6:7]
	v_cvt_pk_bf16_f32 v2, v2, v3
	v_cvt_pk_bf16_f32 v3, v4, v5
	v_lshl_add_u64 v[6:7], s[6:7], 0, v[68:69]
	ds_write_b64 v1, v[62:63] offset:32768
	ds_write_b64 v120, v[54:55]
	ds_write_b64 v116, v[50:51]
	ds_write_b64 v1, v[46:47] offset:36864
	ds_write2st64_b64 v118, v[58:59], v[42:43] offset0:64 offset1:72
	ds_write_b64 v106, v[38:39]
	ds_write_b64 v107, v[34:35]
	ds_write_b64 v1, v[30:31] offset:40960
	ds_write_b64 v108, v[22:23]
	ds_write_b64 v109, v[18:19]
	ds_write_b64 v1, v[14:15] offset:45056
	ds_write2st64_b64 v118, v[26:27], v[10:11] offset0:80 offset1:88
	ds_write_b64 v111, v[2:3]
	v_lshl_add_u64 v[6:7], v[6:7], 0, v[70:71]
	s_waitcnt lgkmcnt(0)
	s_barrier
	v_lshl_add_u64 v[6:7], v[6:7], 0, v[66:67]
	ds_read_b128 v[2:5], v131
	s_waitcnt lgkmcnt(0)
	global_store_dwordx4 v[6:7], v[2:5], off
	s_nop 7
	v_lshl_add_u64 v[6:7], s[6:7], 0, v[72:73]
	v_lshl_add_u64 v[6:7], v[6:7], 0, v[74:75]
	v_lshl_add_u64 v[6:7], v[6:7], 0, v[66:67]
	ds_read_b128 v[2:5], v139
	s_waitcnt lgkmcnt(0)
	global_store_dwordx4 v[6:7], v[2:5], off
	s_nop 7
	v_lshl_add_u64 v[6:7], s[6:7], 0, v[76:77]
	v_lshl_add_u64 v[6:7], v[6:7], 0, v[78:79]
	v_lshl_add_u64 v[6:7], v[6:7], 0, v[66:67]
	ds_read_b128 v[2:5], v141
	s_waitcnt lgkmcnt(0)
	global_store_dwordx4 v[6:7], v[2:5], off
	s_nop 7
	v_lshl_add_u64 v[6:7], s[6:7], 0, v[80:81]
	v_lshl_add_u64 v[6:7], v[6:7], 0, v[82:83]
	v_lshl_add_u64 v[6:7], v[6:7], 0, v[66:67]
	ds_read_b128 v[2:5], v143
	s_waitcnt lgkmcnt(0)
	global_store_dwordx4 v[6:7], v[2:5], off
	s_nop 7
	v_lshl_add_u64 v[6:7], s[6:7], 0, v[84:85]
	v_lshl_add_u64 v[6:7], v[6:7], 0, v[86:87]
	v_lshl_add_u64 v[6:7], v[6:7], 0, v[66:67]
	ds_read_b128 v[2:5], v145
	s_waitcnt lgkmcnt(0)
	global_store_dwordx4 v[6:7], v[2:5], off
	s_nop 7
	v_lshl_add_u64 v[6:7], s[6:7], 0, v[88:89]
	v_lshl_add_u64 v[6:7], v[6:7], 0, v[90:91]
	v_lshl_add_u64 v[6:7], v[6:7], 0, v[66:67]
	ds_read_b128 v[2:5], v162
	s_waitcnt lgkmcnt(0)
	global_store_dwordx4 v[6:7], v[2:5], off
	s_nop 7
	v_lshl_add_u64 v[6:7], s[6:7], 0, v[92:93]
	v_lshl_add_u64 v[6:7], v[6:7], 0, v[94:95]
	v_lshl_add_u64 v[6:7], v[6:7], 0, v[66:67]
	ds_read_b128 v[2:5], v163
	s_waitcnt lgkmcnt(0)
	global_store_dwordx4 v[6:7], v[2:5], off
	s_nop 7
	v_lshl_add_u64 v[6:7], s[6:7], 0, v[96:97]
	v_lshl_add_u64 v[6:7], v[6:7], 0, v[98:99]
	ds_read_b128 v[2:5], v164
	v_lshl_add_u64 v[6:7], v[6:7], 0, v[66:67]
	s_waitcnt lgkmcnt(0)
	global_store_dwordx4 v[6:7], v[2:5], off
	s_nop 7
	s_andn2_b64 vcc, exec, s[4:5]
	s_cbranch_vccz .LBB0_571

;     #define ISSUE_NEXT() do { if (more) { gemm_issue_part1(A, lda, Bt, K, pm * BM, pn * BM, shm, tid); fresh = false; \
;                                           asm volatile("s_waitcnt vmcnt(8)" ::: "memory"); }     \
;                               else asm volatile("s_waitcnt vmcnt(0)" ::: "memory"); } while (0)
; __device__ __forceinline__ float rstd_of(unsigned long long v) { return rsqrtf((float)v * (SSQ_INV / DM) + EPS); }
; template <int EPI>
; __device__ void gemm_phase(const bf16* A, int lda, const bf16* Bt, int K, int N, const Params& p, bool last, bf16* dstb, bf16* shm, unsigned long long* SSQ, int wv, const float* gbias = nullptr) {
;     ...
;       unsigned long long sq[2][4]; float rsv[2][4];
;       _Pragma("unroll") for (int ai = 0; ai < 2; ++ai) _Pragma("unroll") for (int m = 0; m < 4; ++m) sq[ai][m] = SSQ[brow + ai * HALF + wr * 64 + m * 16 + fr];
;       _Pragma("unroll") for (int ai = 0; ai < 2; ++ai) _Pragma("unroll") for (int m = 0; m < 4; ++m) rsv[ai][m] = rstd_of(sq[ai][m]);
;       asm volatile("" : "+v"(rsv[0][0]), "+v"(rsv[0][1]), "+v"(rsv[0][2]), "+v"(rsv[0][3]), "+v"(rsv[1][0]), "+v"(rsv[1][1]), "+v"(rsv[1][2]), "+v"(rsv[1][3]));
;       ISSUE_NEXT();
.LBB0_567:
	v_and_b32_e32 v137, 15, v1
	v_ashrrev_i32_e32 v133, 8, v1
	v_or_b32_e32 v130, s6, v137
	v_lshl_add_u32 v138, v133, 6, v130
	v_ashrrev_i32_e32 v139, 31, v138
	v_lshl_add_u64 v[130:131], v[138:139], 3, s[48:49]
	global_load_dwordx2 v[146:147], v[130:131], off
	global_load_dwordx2 v[148:149], v[130:131], off offset:128
	global_load_dwordx2 v[150:151], v[130:131], off offset:256
	global_load_dwordx2 v[134:135], v[130:131], off offset:384
	v_add_u32_e32 v130, 0x80, v138
	v_ashrrev_i32_e32 v131, 31, v130
	v_lshl_add_u64 v[130:131], v[130:131], 3, s[48:49]
	global_load_dwordx2 v[130:131], v[130:131], off
	v_add_u32_e32 v140, 0x90, v138
	v_ashrrev_i32_e32 v141, 31, v140
	v_lshl_add_u64 v[140:141], v[140:141], 3, s[48:49]
	global_load_dwordx2 v[144:145], v[140:141], off
	v_add_u32_e32 v140, 0xa0, v138
	v_add_u32_e32 v138, 0xb0, v138
	v_ashrrev_i32_e32 v141, 31, v140
	v_ashrrev_i32_e32 v139, 31, v138
	v_lshl_add_u64 v[140:141], v[140:141], 3, s[48:49]
	v_lshl_add_u64 v[138:139], v[138:139], 3, s[48:49]
	global_load_dwordx2 v[142:143], v[140:141], off
	s_mov_b64 s[12:13], -1
	global_load_dwordx2 v[140:141], v[138:139], off
	s_waitcnt vmcnt(7)
	v_ffbh_u32_e32 v132, v147
	v_min_u32_e32 v132, 32, v132
	v_lshlrev_b64 v[138:139], v132, v[146:147]
	v_min_u32_e32 v136, 1, v138
	v_or_b32_e32 v136, v139, v136
	v_cvt_f32_u32_e32 v136, v136
	v_sub_u32_e32 v132, 32, v132
	v_ldexp_f32 v132, v136, v132
	v_fmamk_f32 v132, v132, 0x30000000, v194
	v_cmp_gt_f32_e32 vcc, s80, v132
	v_mul_f32_e32 v136, 0x4b800000, v132
	s_nop 0
	v_cndmask_b32_e32 v132, v132, v136, vcc
	v_rsq_f32_e32 v132, v132
	s_nop 0
	v_mul_f32_e32 v136, 0x45800000, v132
	v_cndmask_b32_e32 v138, v132, v136, vcc
	s_waitcnt vmcnt(6)
	v_ffbh_u32_e32 v132, v149
	v_min_u32_e32 v132, 32, v132
	v_lshlrev_b64 v[146:147], v132, v[148:149]
	v_min_u32_e32 v136, 1, v146
	v_or_b32_e32 v136, v147, v136
	v_cvt_f32_u32_e32 v136, v136
	v_sub_u32_e32 v132, 32, v132
	v_ldexp_f32 v132, v136, v132
	v_fmamk_f32 v132, v132, 0x30000000, v194
	v_cmp_gt_f32_e32 vcc, s80, v132
	v_mul_f32_e32 v136, 0x4b800000, v132
	s_nop 0
	v_cndmask_b32_e32 v132, v132, v136, vcc
	v_rsq_f32_e32 v132, v132
	s_nop 0
	v_mul_f32_e32 v136, 0x45800000, v132
	v_cndmask_b32_e32 v136, v132, v136, vcc
	s_waitcnt vmcnt(5)
	v_ffbh_u32_e32 v132, v151
	v_min_u32_e32 v132, 32, v132
	v_lshlrev_b64 v[146:147], v132, v[150:151]
	v_min_u32_e32 v139, 1, v146
	v_or_b32_e32 v139, v147, v139
	v_cvt_f32_u32_e32 v139, v139
	v_sub_u32_e32 v132, 32, v132
	v_ldexp_f32 v132, v139, v132
	v_fmamk_f32 v132, v132, 0x30000000, v194
	v_cmp_gt_f32_e32 vcc, s80, v132
	v_mul_f32_e32 v139, 0x4b800000, v132
	s_nop 0
	v_cndmask_b32_e32 v132, v132, v139, vcc
	v_rsq_f32_e32 v132, v132
	s_nop 0
	v_mul_f32_e32 v139, 0x45800000, v132
	v_cndmask_b32_e32 v132, v132, v139, vcc
	s_waitcnt vmcnt(4)
	v_ffbh_u32_e32 v139, v135
	v_min_u32_e32 v139, 32, v139
	v_lshlrev_b64 v[134:135], v139, v[134:135]
	v_min_u32_e32 v134, 1, v134
	v_or_b32_e32 v134, v135, v134
	v_cvt_f32_u32_e32 v134, v134
	v_sub_u32_e32 v135, 32, v139
	v_ldexp_f32 v134, v134, v135
	v_fmamk_f32 v134, v134, 0x30000000, v194
	v_cmp_gt_f32_e32 vcc, s80, v134
	v_mul_f32_e32 v135, 0x4b800000, v134
	s_nop 0
	v_cndmask_b32_e32 v134, v134, v135, vcc
	v_rsq_f32_e32 v134, v134
	s_nop 0
	v_mul_f32_e32 v135, 0x45800000, v134
	v_cndmask_b32_e32 v134, v134, v135, vcc
	s_waitcnt vmcnt(3)
	v_ffbh_u32_e32 v135, v131
	v_min_u32_e32 v135, 32, v135
	v_lshlrev_b64 v[130:131], v135, v[130:131]
	v_min_u32_e32 v130, 1, v130
	v_or_b32_e32 v130, v131, v130
	v_cvt_f32_u32_e32 v130, v130
	v_sub_u32_e32 v131, 32, v135
	v_ldexp_f32 v130, v130, v131
	v_fmamk_f32 v130, v130, 0x30000000, v194
	v_cmp_gt_f32_e32 vcc, s80, v130
	v_mul_f32_e32 v131, 0x4b800000, v130
	s_nop 0
	v_cndmask_b32_e32 v130, v130, v131, vcc
	v_rsq_f32_e32 v130, v130
	s_nop 0
	v_mul_f32_e32 v131, 0x45800000, v130
	v_cndmask_b32_e32 v130, v130, v131, vcc
	s_waitcnt vmcnt(2)
	v_ffbh_u32_e32 v131, v145
	v_min_u32_e32 v131, 32, v131
	v_lshlrev_b64 v[144:145], v131, v[144:145]
	v_min_u32_e32 v135, 1, v144
	v_or_b32_e32 v135, v145, v135
	v_cvt_f32_u32_e32 v135, v135
	v_sub_u32_e32 v131, 32, v131
	v_ldexp_f32 v131, v135, v131
	v_fmamk_f32 v131, v131, 0x30000000, v194
	v_cmp_gt_f32_e32 vcc, s80, v131
	v_mul_f32_e32 v135, 0x4b800000, v131
	s_nop 0
	v_cndmask_b32_e32 v131, v131, v135, vcc
	v_rsq_f32_e32 v131, v131
	s_nop 0
	v_mul_f32_e32 v135, 0x45800000, v131
	v_cndmask_b32_e32 v144, v131, v135, vcc
	s_waitcnt vmcnt(1)
	v_ffbh_u32_e32 v131, v143
	v_min_u32_e32 v131, 32, v131
	v_lshlrev_b64 v[142:143], v131, v[142:143]
	v_min_u32_e32 v135, 1, v142
	v_or_b32_e32 v135, v143, v135
	v_cvt_f32_u32_e32 v135, v135
	v_sub_u32_e32 v131, 32, v131
	v_ldexp_f32 v131, v135, v131
	v_fmamk_f32 v131, v131, 0x30000000, v194
	v_cmp_gt_f32_e32 vcc, s80, v131
	v_mul_f32_e32 v135, 0x4b800000, v131
	s_nop 0
	v_cndmask_b32_e32 v131, v131, v135, vcc
	v_rsq_f32_e32 v131, v131
	s_nop 0
	v_mul_f32_e32 v135, 0x45800000, v131
	v_cndmask_b32_e32 v142, v131, v135, vcc
	s_waitcnt vmcnt(0)
	v_ffbh_u32_e32 v131, v141
	v_min_u32_e32 v131, 32, v131
	v_lshlrev_b64 v[140:141], v131, v[140:141]
	v_min_u32_e32 v135, 1, v140
	v_or_b32_e32 v135, v141, v135
	v_cvt_f32_u32_e32 v135, v135
	v_sub_u32_e32 v131, 32, v131
	v_ldexp_f32 v131, v135, v131
	v_fmamk_f32 v131, v131, 0x30000000, v194
	v_cmp_gt_f32_e32 vcc, s80, v131
	v_mul_f32_e32 v135, 0x4b800000, v131
	s_nop 0
	v_cndmask_b32_e32 v131, v131, v135, vcc
	v_rsq_f32_e32 v131, v131
	s_nop 0
	v_mul_f32_e32 v135, 0x45800000, v131
	v_cndmask_b32_e32 v140, v131, v135, vcc
	s_and_b64 vcc, exec, s[4:5]
	s_cbranch_vccz .LBB0_569
	s_mov_b64 s[12:13], 0

; __device__ __forceinline__ float bflo(unsigned u) { return __uint_as_float(u << 16); }
; __device__ __forceinline__ float bfhi(unsigned u) { return __uint_as_float(u & 0xffff0000u); }
;     #define ISSUE_NEXT() do { if (more) { gemm_issue_part1(A, lda, Bt, K, pm * BM, pn * BM, shm, tid); fresh = false; \
;                                           asm volatile("s_waitcnt vmcnt(8)" ::: "memory"); }     \
;                               else asm volatile("s_waitcnt vmcnt(0)" ::: "memory"); } while (0)
; template <int EPI>
; __device__ void gemm_phase(const bf16* A, int lda, const bf16* Bt, int K, int N, const Params& p, bool last, bf16* dstb, bf16* shm, unsigned long long* SSQ, int wv, const float* gbias = nullptr) {
;     ...
;           xo[m][bj][n] = *(const u32x2*)(Xb + (size_t)(brow + ai * HALF + wr * 64 + m * 16 + fr) * DM + bcol + wc * 32 + fq * 4 + bj * HALF + n * 16);
;         if (ai == 0) { ISSUE_NEXT(); asm volatile("s_waitcnt vmcnt(0)" ::: "memory"); } else asm volatile("s_waitcnt vmcnt(0)" ::: "memory");
;         _Pragma("unroll") for (int m = 0; m < 4; ++m) {
;           const int rl = ai * HALF + wr * 64 + m * 16 + fr;
;           const size_t ro = (size_t)(brow + rl) * DM + bcol + wc * 32 + fq * 4;
;           float ssq = 0.f;
;           _Pragma("unroll") for (int bj = 0; bj < 2; ++bj) _Pragma("unroll") for (int n = 0; n < 2; ++n) {
;             const u32x2 xv = xo[m][bj][n];
;             f32x4 v = acc[ai][bj][m][n];
;             v[0] += bflo(xv[0]); v[1] += bfhi(xv[0]); v[2] += bflo(xv[1]); v[3] += bfhi(xv[1]);
;             if (last) *(f32x4*)(p.out + ro + bj * HALF + n * 16) = v;
.LBB0_629:
	v_or_b32_e32 v130, v130, v179
	v_add_u32_e32 v136, s8, v130
	v_ashrrev_i32_e32 v137, 31, v136
	s_waitcnt vmcnt(0)
	v_lshlrev_b64 v[134:135], 13, v[136:137]
	v_lshlrev_b32_e32 v176, 16, v132
	v_and_b32_e32 v177, 0xffff0000, v132
	v_lshlrev_b32_e32 v132, 16, v133
	v_and_b32_e32 v133, 0xffff0000, v133
	v_lshlrev_b32_e32 v139, 5, v178
	v_lshlrev_b32_e32 v171, 2, v131
	v_pk_add_f32 v[128:129], v[128:129], v[132:133]
	v_lshl_add_u64 v[132:133], s[76:77], 0, v[134:135]
	v_pk_add_f32 v[126:127], v[126:127], v[176:177]
	s_mov_b64 s[0:1], -1
	s_andn2_b64 vcc, exec, s[60:61]
	v_lshl_add_u64 v[176:177], s[10:11], 2, v[132:133]
	v_lshlrev_b32_e32 v134, 2, v139
	v_lshlrev_b32_e32 v132, 2, v171
	s_cbranch_vccnz .LBB0_631
	v_mov_b32_e32 v135, v0
	v_lshl_add_u64 v[180:181], v[176:177], 0, v[134:135]
	v_mov_b32_e32 v133, v0
	v_lshl_add_u64 v[180:181], v[180:181], 0, v[132:133]
	s_mov_b64 s[0:1], 0
	global_store_dwordx4 v[180:181], v[126:129], off

; #define LDS_BARRIER() do { asm volatile("s_waitcnt lgkmcnt(0)" ::: "memory"); __builtin_amdgcn_s_barrier(); asm volatile("" ::: "memory"); } while (0)
; __device__ __forceinline__ float bflo(unsigned u) { return __uint_as_float(u << 16); }
; __device__ __forceinline__ float bfhi(unsigned u) { return __uint_as_float(u & 0xffff0000u); }
; __device__ __forceinline__ void st16_asm(void* ptr, u32x4 v) { asm volatile("global_store_dwordx4 %0, %1, off\n\ts_nop 7" :: "v"(ptr), "v"(v) : "memory"); }
; __device__ __forceinline__ void stg_flush(bf16* shm, int tid, bf16* dst, size_t pitch, bool first, bool tail_barrier = true) {
;   LDS_BARRIER();
;   if (first) asm volatile("s_waitcnt vmcnt(0)" ::: "memory");
;   _Pragma("unroll") for (int i = 0; i < 8; ++i) {
;     const int idx = tid + 512 * i, bjr = idx >> 11, row = (idx >> 4) & 127, c16 = idx & 15;
;     const u32x4 d = *(const u32x4*)stg_ptr(shm, bjr, row, 2 * c16);
;     st16_asm(dst + (size_t)row * pitch + bjr * HALF + c16 * 8, d); }
;   if (tail_barrier) LDS_BARRIER();
; }
; template <int EPI>
; __device__ void gemm_phase(const bf16* A, int lda, const bf16* Bt, int K, int N, const Params& p, bool last, bf16* dstb, bf16* shm, unsigned long long* SSQ, int wv, const float* gbias = nullptr) {
;     ...
;       _Pragma("unroll") for (int ai = 0; ai < 2; ++ai) {
;         u32x2 xo[4][2][2];
;         _Pragma("unroll") for (int m = 0; m < 4; ++m) _Pragma("unroll") for (int bj = 0; bj < 2; ++bj) _Pragma("unroll") for (int n = 0; n < 2; ++n)
;           xo[m][bj][n] = *(const u32x2*)(Xb + (size_t)(brow + ai * HALF + wr * 64 + m * 16 + fr) * DM + bcol + wc * 32 + fq * 4 + bj * HALF + n * 16);
;         if (ai == 0) { ISSUE_NEXT(); asm volatile("s_waitcnt vmcnt(0)" ::: "memory"); } else asm volatile("s_waitcnt vmcnt(0)" ::: "memory");
;         _Pragma("unroll") for (int m = 0; m < 4; ++m) {
;           const int rl = ai * HALF + wr * 64 + m * 16 + fr;
;           const size_t ro = (size_t)(brow + rl) * DM + bcol + wc * 32 + fq * 4;
;           float ssq = 0.f;
;           _Pragma("unroll") for (int bj = 0; bj < 2; ++bj) _Pragma("unroll") for (int n = 0; n < 2; ++n) {
;             const u32x2 xv = xo[m][bj][n];
;             f32x4 v = acc[ai][bj][m][n];
;             v[0] += bflo(xv[0]); v[1] += bfhi(xv[0]); v[2] += bflo(xv[1]); v[3] += bfhi(xv[1]);
;             if (last) *(f32x4*)(p.out + ro + bj * HALF + n * 16) = v;
.LBB0_708:
	s_or_b64 exec, exec, s[18:19]
	s_lshl_b64 s[18:19], s[8:9], 12
	s_add_u32 s18, s14, s18
	s_addc_u32 s19, s15, s19
	v_lshlrev_b32_e32 v86, 1, v119
	v_mov_b32_e32 v87, v0
	v_lshl_add_u64 v[86:87], s[18:19], 0, v[86:87]
	v_lshl_add_u64 v[86:87], v[66:67], 1, v[86:87]
	v_lshlrev_b32_e32 v88, 1, v117
	v_mov_b32_e32 v89, v0
	s_waitcnt lgkmcnt(0)
	s_barrier
	v_add_u32_e32 v82, v118, v120
	v_lshl_add_u64 v[86:87], v[86:87], 0, v[88:89]
	ds_read_b128 v[82:85], v82
	s_waitcnt lgkmcnt(0)
	global_store_dwordx4 v[86:87], v[82:85], off
	s_nop 7
	v_lshlrev_b32_e32 v86, 1, v123
	v_mov_b32_e32 v87, v0
	v_lshl_add_u64 v[86:87], s[18:19], 0, v[86:87]
	v_lshl_add_u64 v[86:87], v[68:69], 1, v[86:87]
	v_add_u32_e32 v82, v121, v124
	v_lshl_add_u64 v[86:87], v[86:87], 0, v[88:89]
	ds_read_b128 v[82:85], v82
	s_waitcnt lgkmcnt(0)
	global_store_dwordx4 v[86:87], v[82:85], off
	s_nop 7
	v_lshlrev_b32_e32 v86, 1, v127
	v_mov_b32_e32 v87, v0
	v_lshl_add_u64 v[86:87], s[18:19], 0, v[86:87]
	v_lshl_add_u64 v[86:87], v[70:71], 1, v[86:87]
	v_add_u32_e32 v82, v125, v128
	v_lshl_add_u64 v[86:87], v[86:87], 0, v[88:89]
	ds_read_b128 v[82:85], v82
	s_waitcnt lgkmcnt(0)
	global_store_dwordx4 v[86:87], v[82:85], off
	s_nop 7
	v_lshlrev_b32_e32 v86, 1, v142
	v_mov_b32_e32 v87, v0
	v_lshl_add_u64 v[86:87], s[18:19], 0, v[86:87]
	v_lshl_add_u64 v[86:87], v[72:73], 1, v[86:87]
	v_add_u32_e32 v82, v129, v143
	v_lshl_add_u64 v[86:87], v[86:87], 0, v[88:89]
	ds_read_b128 v[82:85], v82
	s_waitcnt lgkmcnt(0)
	global_store_dwordx4 v[86:87], v[82:85], off
	s_nop 7
	v_lshlrev_b32_e32 v86, 1, v145
	v_mov_b32_e32 v87, v0
	v_lshl_add_u64 v[86:87], s[18:19], 0, v[86:87]
	v_lshl_add_u64 v[86:87], v[74:75], 1, v[86:87]
	v_add_u32_e32 v82, v144, v146
	v_lshl_add_u64 v[86:87], v[86:87], 0, v[88:89]
	ds_read_b128 v[82:85], v82
	s_waitcnt lgkmcnt(0)
	global_store_dwordx4 v[86:87], v[82:85], off
	s_nop 7
	v_lshlrev_b32_e32 v86, 1, v148
	v_mov_b32_e32 v87, v0
	v_lshl_add_u64 v[86:87], s[18:19], 0, v[86:87]
	v_lshl_add_u64 v[86:87], v[76:77], 1, v[86:87]
	v_add_u32_e32 v82, v147, v149
	v_lshl_add_u64 v[86:87], v[86:87], 0, v[88:89]
	ds_read_b128 v[82:85], v82
	s_waitcnt lgkmcnt(0)
	global_store_dwordx4 v[86:87], v[82:85], off
	s_nop 7
	v_lshlrev_b32_e32 v86, 1, v151
	v_mov_b32_e32 v87, v0
	v_lshl_add_u64 v[86:87], s[18:19], 0, v[86:87]
	v_lshl_add_u64 v[86:87], v[78:79], 1, v[86:87]
	v_add_u32_e32 v82, v150, v152
	v_lshl_add_u64 v[86:87], v[86:87], 0, v[88:89]
	ds_read_b128 v[82:85], v82
	s_waitcnt lgkmcnt(0)
	global_store_dwordx4 v[86:87], v[82:85], off
	s_nop 7
	v_lshlrev_b32_e32 v86, 1, v1
	v_mov_b32_e32 v87, v0
	v_lshl_add_u64 v[86:87], s[18:19], 0, v[86:87]
	v_add_u32_e32 v82, v153, v154
	v_lshl_add_u64 v[86:87], v[80:81], 1, v[86:87]
	ds_read_b128 v[82:85], v82
	v_lshl_add_u64 v[86:87], v[86:87], 0, v[88:89]
	s_waitcnt lgkmcnt(0)
	global_store_dwordx4 v[86:87], v[82:85], off
	s_nop 7
	s_barrier
.LBB0_709:
	v_add_u32_e32 v82, 0x80, v138
	v_ashrrev_i32_e32 v83, 31, v82
	v_lshlrev_b64 v[82:83], 12, v[82:83]
	v_lshl_add_u64 v[82:83], v[140:141], 0, v[82:83]
	global_load_dwordx2 v[110:111], v[82:83], off
	global_load_dwordx2 v[112:113], v[82:83], off offset:32
	global_load_dwordx2 v[108:109], v[82:83], off offset:256
	global_load_dwordx2 v[106:107], v[82:83], off offset:288
	v_add_u32_e32 v82, 0x90, v138
	v_ashrrev_i32_e32 v83, 31, v82
	v_lshlrev_b64 v[82:83], 12, v[82:83]
	v_lshl_add_u64 v[82:83], v[140:141], 0, v[82:83]
	global_load_dwordx2 v[104:105], v[82:83], off
	global_load_dwordx2 v[102:103], v[82:83], off offset:32
	global_load_dwordx2 v[100:101], v[82:83], off offset:256
	global_load_dwordx2 v[98:99], v[82:83], off offset:288
	v_add_u32_e32 v82, 0xa0, v138
	v_ashrrev_i32_e32 v83, 31, v82
	v_lshlrev_b64 v[82:83], 12, v[82:83]
	v_lshl_add_u64 v[82:83], v[140:141], 0, v[82:83]
	global_load_dwordx2 v[96:97], v[82:83], off
	global_load_dwordx2 v[94:95], v[82:83], off offset:32
	global_load_dwordx2 v[92:93], v[82:83], off offset:256
	global_load_dwordx2 v[90:91], v[82:83], off offset:288
	v_add_u32_e32 v82, 0xb0, v138
	v_ashrrev_i32_e32 v83, 31, v82
	v_lshlrev_b64 v[82:83], 12, v[82:83]
	v_lshl_add_u64 v[82:83], v[140:141], 0, v[82:83]
	global_load_dwordx2 v[88:89], v[82:83], off
	global_load_dwordx2 v[86:87], v[82:83], off offset:32
	global_load_dwordx2 v[84:85], v[82:83], off offset:256
	s_nop 0
	global_load_dwordx2 v[82:83], v[82:83], off offset:288
	v_add_u32_e32 v140, 0x80, v136
	v_ashrrev_i32_e32 v141, 31, v140
	s_waitcnt vmcnt(0)
	v_lshlrev_b64 v[140:141], 13, v[140:141]
	s_mov_b64 s[18:19], -1
	s_and_b64 vcc, exec, s[60:61]
	v_lshlrev_b32_e32 v156, 16, v110
	v_and_b32_e32 v157, 0xffff0000, v110
	v_lshlrev_b32_e32 v110, 16, v111
	v_and_b32_e32 v111, 0xffff0000, v111
	v_pk_add_f32 v[64:65], v[64:65], v[110:111]
	v_lshl_add_u64 v[110:111], s[76:77], 0, v[140:141]
	v_pk_add_f32 v[62:63], v[62:63], v[156:157]
	v_lshl_add_u64 v[110:111], s[10:11], 2, v[110:111]
	s_cbranch_vccz .LBB0_711
	v_mov_b32_e32 v135, v0
	v_lshl_add_u64 v[140:141], v[110:111], 0, v[134:135]
	v_mov_b32_e32 v133, v0
	v_lshl_add_u64 v[140:141], v[140:141], 0, v[132:133]
	global_store_dwordx4 v[140:141], v[62:65], off
	s_mov_b64 s[18:19], 0
